# epilogue round pipelining: PH14a (EpiPle) rounds 2-4 and PH3 (EpiGateY) round 4 load blocks hoisted one round ahead with register renaming (on v53)
# speedup vs baseline: 1.0127x; 1.0127x over previous
;     __device__ __forceinline__ void operator()(const Acc& acc, const pg8::Unit& u, int wid) const {
;         const int lane_ = lane_id_asm(), wr = wid >> 2, wc = wid & 3, fr = lane_ & 15, fq = lane_ >> 4;
;         const int row0 = u.pm * 256 + wr * 64 + fr, col0 = u.pn * 256 + wc * 32 + 8 * fq, head = u.pn >> 1;
;         f32x4 g4[2][2];
; #pragma unroll
;         for (int bj = 0; bj < 2; ++bj) { g4[bj][0] = *(const f32x4*)(gn + col0 + bj * 128); g4[bj][1] = *(const f32x4*)(gn + col0 + bj * 128 + 4); }
; #pragma unroll
;         for (int ai = 0; ai < 2; ++ai)
; #pragma unroll
;             for (int mp = 0; mp < 2; ++mp) {
;                 float scv[2]; f32x4 rq[2][4]; u32x4 ov[2][2];
; #pragma unroll
;                 for (int mm = 0; mm < 2; ++mm) { const int row = row0 + ai * 128 + (2 * mp + mm) * 16;
;                     scv[mm] = ssq[row];
;                     const f32x4* rp = (const f32x4*)(rssq + (size_t)row * 64 + head * 16);
; #pragma unroll
;                     for (int i = 0; i < 4; ++i) rq[mm][i] = rp[i];
; #pragma unroll
;                     for (int bj = 0; bj < 2; ++bj) ov[mm][bj] = *(const u32x4*)(Y + (size_t)row * 2048 + col0 + bj * 128); }
; #pragma unroll
;                 for (int mm = 0; mm < 2; ++mm) { const int m = 2 * mp + mm, row = row0 + ai * 128 + m * 16;
;                     const float sc = __builtin_amdgcn_rsqf(scv[mm] * (1.f / 1024.f) + EPS);
;                     const f32x4 pa = (rq[mm][0] + rq[mm][1]) + (rq[mm][2] + rq[mm][3]);
;                     const float rg = __builtin_amdgcn_rsqf(((pa[0] + pa[1]) + (pa[2] + pa[3])) * (1.f / 512.f) + EPS);
; #pragma unroll
;                     for (int bj = 0; bj < 2; ++bj) {
;                         const u32x4 w = ov[mm][bj];
;                         f32x4 o0 = (f32x4){bflo(w.x), bfhi(w.x), bflo(w.y), bfhi(w.y)}, o1 = (f32x4){bflo(w.z), bfhi(w.z), bflo(w.w), bfhi(w.w)};
;                         f32x4 a0 = acc[ai][bj][m][0] * sc, a1 = acc[ai][bj][m][1] * sc;
; #pragma unroll
;                         for (int e = 0; e < 4; ++e) { a0[e] = a0[e] * __builtin_amdgcn_rcpf(1.f + __builtin_amdgcn_exp2f(-1.4426950408889634f * a0[e])); a1[e] = a1[e] * __builtin_amdgcn_rcpf(1.f + __builtin_amdgcn_exp2f(-1.4426950408889634f * a1[e])); }
;                         o0 = a0 * o0 * g4[bj][0] * rg; o1 = a1 * o1 * g4[bj][1] * rg;
.LBB0_334:
	s_lshl_b32 s11, s22, 8
	s_add_i32 s11, s11, s66
	v_mbcnt_lo_u32_b32 v50, -1, 0
	v_mbcnt_hi_u32_b32 v50, -1, v50
	s_lshl_b32 s15, s20, 8
	v_and_or_b32 v186, v50, 15, s11
	s_lshl_b32 s11, s20, 3
	s_and_b32 s20, s11, -16
	s_ashr_i32 s21, s20, 31
	s_or_b32 s15, s15, s69
	s_lshl_b64 s[20:21], s[20:21], 2
	s_add_u32 s20, s60, s20
	v_ashrrev_i32_e32 v187, 31, v186
	v_ashrrev_i32_e32 v48, 1, v50
	s_addc_u32 s21, s61, s21
	v_lshl_add_u64 v[188:189], v[186:187], 2, s[54:55]
	v_lshlrev_b64 v[50:51], 8, v[186:187]
	v_lshl_add_u64 v[50:51], s[20:21], 0, v[50:51]
	flat_load_dword v199, v[188:189]
	flat_load_dwordx4 v[200:203], v[50:51]
	flat_load_dwordx4 v[204:207], v[50:51] offset:16
	flat_load_dwordx4 v[208:211], v[50:51] offset:32
	flat_load_dwordx4 v[212:215], v[50:51] offset:48
	v_and_b32_e32 v48, -8, v48
	v_add_u32_e32 v48, s15, v48
	v_ashrrev_i32_e32 v49, 31, v48
	v_lshlrev_b64 v[184:185], 1, v[48:49]
	v_lshl_add_u64 v[190:191], s[36:37], 0, v[184:185]
	v_lshlrev_b64 v[224:225], 12, v[186:187]
	v_lshl_add_u64 v[144:145], v[190:191], 0, v[224:225]
	flat_load_dwordx4 v[216:219], v[144:145]
	v_lshl_add_u64 v[48:49], v[48:49], 2, s[48:49]
	v_or_b32_e32 v50, 16, v186
	flat_load_dwordx4 v[64:67], v[48:49]
	v_ashrrev_i32_e32 v51, 31, v50
	v_lshlrev_b64 v[146:147], 8, v[50:51]
	v_lshlrev_b64 v[192:193], 12, v[50:51]
	flat_load_dwordx4 v[68:71], v[48:49] offset:16
	flat_load_dwordx4 v[56:59], v[48:49] offset:512
	s_nop 0
	flat_load_dwordx4 v[48:51], v[48:49] offset:528
	v_lshl_add_u64 v[146:147], s[20:21], 0, v[146:147]
	flat_load_dword v187, v[188:189] offset:64
	flat_load_dwordx4 v[160:163], v[146:147] offset:16
	flat_load_dwordx4 v[152:155], v[146:147] offset:32
	v_lshl_add_u64 v[226:227], v[190:191], 0, v[192:193]
	flat_load_dwordx4 v[220:223], v[144:145] offset:256
	flat_load_dwordx4 v[164:167], v[146:147]
	flat_load_dwordx4 v[156:159], v[146:147] offset:48
	flat_load_dwordx4 v[148:151], v[226:227]
	s_nop 0
	flat_load_dwordx4 v[144:147], v[226:227] offset:256
	s_andn2_b64 vcc, exec, s[0:1]
	s_mov_b64 s[0:1], -1
	s_waitcnt vmcnt(0) lgkmcnt(0)
	v_fmamk_f32 v199, v199, 0x3a800000, v198
	v_rsq_f32_e32 v226, v199
	v_pk_add_f32 v[202:203], v[202:203], v[206:207]
	v_pk_add_f32 v[200:201], v[200:201], v[204:205]
	v_pk_add_f32 v[204:205], v[210:211], v[214:215]
	v_pk_add_f32 v[206:207], v[208:209], v[212:213]
	v_pk_add_f32 v[202:203], v[202:203], v[204:205]
	v_pk_add_f32 v[200:201], v[200:201], v[206:207]
	v_pk_mul_f32 v[140:141], v[140:141], v[226:227] op_sel_hi:[1,0]
	v_pk_mov_b32 v[212:213], v[200:201], v[202:203] op_sel:[1,0]
	v_mov_b32_e32 v201, v203
	v_pk_add_f32 v[200:201], v[212:213], v[200:201]
	v_pk_mul_f32 v[136:137], v[136:137], v[226:227] op_sel_hi:[1,0]
	v_pk_mul_f32 v[142:143], v[142:143], v[226:227] op_sel_hi:[1,0]
	v_add_f32_e32 v199, v200, v201
	v_mul_f32_e32 v200, 0xbfb8aa3b, v140
	v_mul_f32_e32 v201, 0xbfb8aa3b, v136
	v_mul_f32_e32 v202, 0xbfb8aa3b, v141
	v_mul_f32_e32 v212, 0xbfb8aa3b, v142
	v_exp_f32_e32 v214, v200
	v_exp_f32_e32 v201, v201
	v_exp_f32_e32 v202, v202
	v_exp_f32_e32 v212, v212
	v_fmamk_f32 v199, v199, 0x3b000000, v198
	v_pk_mul_f32 v[138:139], v[138:139], v[226:227] op_sel_hi:[1,0]
	v_mul_f32_e32 v215, 0xbfb8aa3b, v143
	v_rsq_f32_e32 v200, v199
	v_add_f32_e32 v199, 1.0, v214
	v_add_f32_e32 v201, 1.0, v201
	v_lshlrev_b32_e32 v204, 16, v216
	v_and_b32_e32 v205, 0xffff0000, v216
	v_mul_f32_e32 v203, 0xbfb8aa3b, v137
	v_mul_f32_e32 v213, 0xbfb8aa3b, v138
	v_add_f32_e32 v214, 1.0, v202
	v_add_f32_e32 v216, 1.0, v212
	v_rcp_f32_e32 v202, v199
	v_rcp_f32_e32 v212, v201
	v_exp_f32_e32 v199, v215
	v_mul_f32_e32 v201, 0xbfb8aa3b, v139
	v_exp_f32_e32 v203, v203
	v_exp_f32_e32 v213, v213
	v_exp_f32_e32 v201, v201
	v_add_f32_e32 v199, 1.0, v199
	v_lshlrev_b32_e32 v208, 16, v218
	v_and_b32_e32 v209, 0xffff0000, v218
	v_add_f32_e32 v218, 1.0, v203
	v_add_f32_e32 v213, 1.0, v213
	v_rcp_f32_e32 v215, v199
	v_add_f32_e32 v199, 1.0, v201
	v_lshlrev_b32_e32 v206, 16, v217
	v_and_b32_e32 v207, 0xffff0000, v217
	v_rcp_f32_e32 v203, v214
	v_rcp_f32_e32 v214, v216
	v_rcp_f32_e32 v216, v213
	v_rcp_f32_e32 v217, v199
	v_rcp_f32_e32 v213, v218
	v_lshlrev_b32_e32 v210, 16, v219
	v_and_b32_e32 v211, 0xffff0000, v219
	v_pk_mul_f32 v[142:143], v[142:143], v[214:215]
	v_pk_mul_f32 v[140:141], v[140:141], v[202:203]
	v_pk_mul_f32 v[138:139], v[138:139], v[216:217]
	v_pk_mul_f32 v[136:137], v[136:137], v[212:213]
	v_pk_mul_f32 v[140:141], v[140:141], v[204:205]
	v_pk_mul_f32 v[142:143], v[142:143], v[206:207]
	v_pk_mul_f32 v[136:137], v[136:137], v[208:209]
	v_pk_mul_f32 v[138:139], v[138:139], v[210:211]
	v_pk_mul_f32 v[132:133], v[132:133], v[226:227] op_sel_hi:[1,0]
	v_pk_mul_f32 v[142:143], v[66:67], v[142:143]
	v_pk_mul_f32 v[140:141], v[64:65], v[140:141]
	v_pk_mul_f32 v[138:139], v[70:71], v[138:139]
	v_pk_mul_f32 v[136:137], v[68:69], v[136:137]
	v_mul_f32_e32 v199, 0xbfb8aa3b, v132
	v_pk_mul_f32 v[128:129], v[128:129], v[226:227] op_sel_hi:[1,0]
	v_pk_mul_f32 v[142:143], v[200:201], v[142:143] op_sel_hi:[0,1]
	v_pk_mul_f32 v[140:141], v[200:201], v[140:141] op_sel_hi:[0,1]
	v_pk_mul_f32 v[202:203], v[200:201], v[138:139] op_sel_hi:[0,1]
	v_pk_mul_f32 v[138:139], v[200:201], v[136:137] op_sel_hi:[0,1]
	v_exp_f32_e32 v199, v199
	v_mul_f32_e32 v201, 0xbfb8aa3b, v128
	v_exp_f32_e32 v201, v201
	v_pk_mul_f32 v[134:135], v[134:135], v[226:227] op_sel_hi:[1,0]
	v_add_f32_e32 v199, 1.0, v199
	v_mul_f32_e32 v204, 0xbfb8aa3b, v133
	v_pk_mul_f32 v[130:131], v[130:131], v[226:227] op_sel_hi:[1,0]
	v_exp_f32_e32 v205, v204
	v_rcp_f32_e32 v204, v199
	v_add_f32_e32 v199, 1.0, v201
	v_mul_f32_e32 v201, 0xbfb8aa3b, v134
	v_exp_f32_e32 v201, v201
; __device__ __forceinline__ u32x4 pack8(f32x4 a, f32x4 b) { u32x4 w; w.x = pk2(a[0], a[1]); w.y = pk2(a[2], a[3]); w.z = pk2(b[0], b[1]); w.w = pk2(b[2], b[3]); return w; }
;     __device__ __forceinline__ void operator()(const Acc& acc, const pg8::Unit& u, int wid) const {
;     ...
;                 for (int mm = 0; mm < 2; ++mm) { const int m = 2 * mp + mm, row = row0 + ai * 128 + m * 16;
;                     const float sc = __builtin_amdgcn_rsqf(scv[mm] * (1.f / 1024.f) + EPS);
;                     const f32x4 pa = (rq[mm][0] + rq[mm][1]) + (rq[mm][2] + rq[mm][3]);
;                     const float rg = __builtin_amdgcn_rsqf(((pa[0] + pa[1]) + (pa[2] + pa[3])) * (1.f / 512.f) + EPS);
; #pragma unroll
;                     for (int bj = 0; bj < 2; ++bj) {
;                         const u32x4 w = ov[mm][bj];
;                         f32x4 o0 = (f32x4){bflo(w.x), bfhi(w.x), bflo(w.y), bfhi(w.y)}, o1 = (f32x4){bflo(w.z), bfhi(w.z), bflo(w.w), bfhi(w.w)};
;                         f32x4 a0 = acc[ai][bj][m][0] * sc, a1 = acc[ai][bj][m][1] * sc;
; #pragma unroll
;                         for (int e = 0; e < 4; ++e) { a0[e] = a0[e] * __builtin_amdgcn_rcpf(1.f + __builtin_amdgcn_exp2f(-1.4426950408889634f * a0[e])); a1[e] = a1[e] * __builtin_amdgcn_rcpf(1.f + __builtin_amdgcn_exp2f(-1.4426950408889634f * a1[e])); }
;                         o0 = a0 * o0 * g4[bj][0] * rg; o1 = a1 * o1 * g4[bj][1] * rg;
;                         *(u32x4*)(Y + (size_t)row * 2048 + col0 + bj * 128) = pack8(o0, o1);
;                     } }
	v_mul_f32_e32 v207, 0xbfb8aa3b, v130
	v_exp_f32_e32 v207, v207
	v_rcp_f32_e32 v206, v199
	v_add_f32_e32 v201, 1.0, v201
	v_add_f32_e32 v199, 1.0, v205
	v_rcp_f32_e32 v208, v201
	v_add_f32_e32 v201, 1.0, v207
	v_mul_f32_e32 v207, 0xbfb8aa3b, v135
	v_rcp_f32_e32 v205, v199
	v_mul_f32_e32 v199, 0xbfb8aa3b, v129
	v_exp_f32_e32 v207, v207
	v_mul_f32_e32 v209, 0xbfb8aa3b, v131
	v_exp_f32_e32 v199, v199
	v_exp_f32_e32 v211, v209
	v_rcp_f32_e32 v210, v201
	v_add_f32_e32 v201, 1.0, v207
	v_add_f32_e32 v199, 1.0, v199
	v_rcp_f32_e32 v209, v201
	v_add_f32_e32 v201, 1.0, v211
	v_rcp_f32_e32 v211, v201
	v_rcp_f32_e32 v207, v199
	v_cvt_pk_bf16_f32 v136, v140, v141
	v_lshl_add_u64 v[140:141], s[36:37], 0, v[224:225]
	v_cvt_pk_bf16_f32 v137, v142, v143
	v_cvt_pk_bf16_f32 v138, v138, v139
	v_cvt_pk_bf16_f32 v139, v202, v203
	v_lshl_add_u64 v[140:141], v[140:141], 0, v[184:185]
	flat_store_dwordx4 v[140:141], v[136:139]
	v_lshlrev_b32_e32 v142, 16, v222
	v_and_b32_e32 v143, 0xffff0000, v222
	v_lshlrev_b32_e32 v136, 16, v220
	v_and_b32_e32 v137, 0xffff0000, v220
	v_lshlrev_b32_e32 v138, 16, v221
	v_and_b32_e32 v139, 0xffff0000, v221
	v_lshlrev_b32_e32 v202, 16, v223
	v_and_b32_e32 v203, 0xffff0000, v223
	v_pk_mul_f32 v[134:135], v[134:135], v[208:209]
	v_pk_mul_f32 v[132:133], v[132:133], v[204:205]
	v_pk_mul_f32 v[130:131], v[130:131], v[210:211]
	v_pk_mul_f32 v[128:129], v[128:129], v[206:207]
	v_pk_mul_f32 v[132:133], v[132:133], v[136:137]
	v_pk_mul_f32 v[134:135], v[134:135], v[138:139]
	v_pk_mul_f32 v[128:129], v[128:129], v[142:143]
	v_pk_mul_f32 v[130:131], v[130:131], v[202:203]
	v_pk_mul_f32 v[134:135], v[58:59], v[134:135]
	v_pk_mul_f32 v[132:133], v[56:57], v[132:133]
	v_pk_mul_f32 v[130:131], v[50:51], v[130:131]
	v_pk_mul_f32 v[128:129], v[48:49], v[128:129]
	v_pk_mul_f32 v[134:135], v[200:201], v[134:135] op_sel_hi:[0,1]
	v_pk_mul_f32 v[132:133], v[200:201], v[132:133] op_sel_hi:[0,1]
	v_pk_mul_f32 v[136:137], v[200:201], v[130:131] op_sel_hi:[0,1]
	v_pk_mul_f32 v[130:131], v[200:201], v[128:129] op_sel_hi:[0,1]
	v_cvt_pk_bf16_f32 v128, v132, v133
	v_cvt_pk_bf16_f32 v129, v134, v135
	v_cvt_pk_bf16_f32 v130, v130, v131
	v_cvt_pk_bf16_f32 v131, v136, v137
	flat_store_dwordx4 v[140:141], v[128:131] offset:256
	v_pk_add_f32 v[132:133], v[154:155], v[158:159]
	v_pk_add_f32 v[136:137], v[152:153], v[156:157]
	v_fmamk_f32 v128, v187, 0x3a800000, v198
	v_rsq_f32_e32 v134, v128
	v_pk_add_f32 v[128:129], v[166:167], v[162:163]
	v_pk_add_f32 v[130:131], v[164:165], v[160:161]
	v_pk_add_f32 v[128:129], v[128:129], v[132:133]
	v_pk_add_f32 v[130:131], v[130:131], v[136:137]
	v_pk_mul_f32 v[124:125], v[124:125], v[134:135] op_sel_hi:[1,0]
	v_pk_mov_b32 v[132:133], v[130:131], v[128:129] op_sel:[1,0]
	v_mov_b32_e32 v131, v129
	v_pk_add_f32 v[128:129], v[132:133], v[130:131]
	v_pk_mul_f32 v[120:121], v[120:121], v[134:135] op_sel_hi:[1,0]
	v_add_f32_e32 v128, v128, v129
	v_mul_f32_e32 v129, 0xbfb8aa3b, v124
	v_exp_f32_e32 v129, v129
	v_pk_mul_f32 v[126:127], v[126:127], v[134:135] op_sel_hi:[1,0]
	v_pk_mul_f32 v[122:123], v[122:123], v[134:135] op_sel_hi:[1,0]
	v_mul_f32_e32 v135, 0xbfb8aa3b, v120
	v_exp_f32_e32 v135, v135
	v_add_f32_e32 v129, 1.0, v129
	v_mul_f32_e32 v140, 0xbfb8aa3b, v125
	v_exp_f32_e32 v141, v140
	v_rcp_f32_e32 v140, v129
	v_add_f32_e32 v129, 1.0, v135
	v_mul_f32_e32 v135, 0xbfb8aa3b, v126
	v_exp_f32_e32 v135, v135
	v_mul_f32_e32 v143, 0xbfb8aa3b, v122
	v_exp_f32_e32 v143, v143
	v_lshlrev_b32_e32 v130, 16, v148
	v_add_f32_e32 v135, 1.0, v135
	v_and_b32_e32 v131, 0xffff0000, v148
	v_rcp_f32_e32 v142, v129
	v_add_f32_e32 v129, 1.0, v141
	v_rcp_f32_e32 v148, v135
	v_add_f32_e32 v135, 1.0, v143
	v_mul_f32_e32 v143, 0xbfb8aa3b, v127
	v_lshlrev_b32_e32 v132, 16, v149
	v_and_b32_e32 v133, 0xffff0000, v149
	v_rcp_f32_e32 v141, v129
	v_mul_f32_e32 v129, 0xbfb8aa3b, v121
	v_exp_f32_e32 v143, v143
	v_mul_f32_e32 v149, 0xbfb8aa3b, v123
	v_lshlrev_b32_e32 v138, 16, v151
	v_and_b32_e32 v139, 0xffff0000, v151
	v_exp_f32_e32 v129, v129
	v_exp_f32_e32 v151, v149
	v_lshlrev_b32_e32 v136, 16, v150
	v_and_b32_e32 v137, 0xffff0000, v150
	v_rcp_f32_e32 v150, v135
	v_add_f32_e32 v135, 1.0, v143
	v_add_f32_e32 v129, 1.0, v129
	v_rcp_f32_e32 v149, v135
	v_add_f32_e32 v135, 1.0, v151
	v_rcp_f32_e32 v151, v135
	v_rcp_f32_e32 v143, v129
	v_fmamk_f32 v128, v128, 0x3b000000, v198
	v_rsq_f32_e32 v128, v128
	v_pk_mul_f32 v[126:127], v[126:127], v[148:149]
	v_pk_mul_f32 v[124:125], v[124:125], v[140:141]
	v_pk_mul_f32 v[122:123], v[122:123], v[150:151]
	v_pk_mul_f32 v[120:121], v[120:121], v[142:143]
	v_pk_mul_f32 v[124:125], v[124:125], v[130:131]
	v_pk_mul_f32 v[126:127], v[126:127], v[132:133]
	v_pk_mul_f32 v[120:121], v[120:121], v[136:137]
	v_pk_mul_f32 v[122:123], v[122:123], v[138:139]
	v_pk_mul_f32 v[126:127], v[66:67], v[126:127]
	v_pk_mul_f32 v[124:125], v[64:65], v[124:125]
	v_pk_mul_f32 v[122:123], v[70:71], v[122:123]
	v_pk_mul_f32 v[120:121], v[68:69], v[120:121]
	v_pk_mul_f32 v[116:117], v[116:117], v[134:135] op_sel_hi:[1,0]
	v_pk_mul_f32 v[126:127], v[128:129], v[126:127] op_sel_hi:[0,1]
	v_pk_mul_f32 v[124:125], v[128:129], v[124:125] op_sel_hi:[0,1]
	v_pk_mul_f32 v[130:131], v[128:129], v[122:123] op_sel_hi:[0,1]
	v_pk_mul_f32 v[122:123], v[128:129], v[120:121] op_sel_hi:[0,1]
	v_mul_f32_e32 v129, 0xbfb8aa3b, v116
	v_pk_mul_f32 v[112:113], v[112:113], v[134:135] op_sel_hi:[1,0]
	v_exp_f32_e32 v129, v129
	v_pk_mul_f32 v[118:119], v[118:119], v[134:135] op_sel_hi:[1,0]
	v_pk_mul_f32 v[114:115], v[114:115], v[134:135] op_sel_hi:[1,0]
	v_mul_f32_e32 v134, 0xbfb8aa3b, v112
	v_exp_f32_e32 v135, v134
	v_mul_f32_e32 v134, 0xbfb8aa3b, v117
	v_exp_f32_e32 v143, v134
; __device__ __forceinline__ u32x4 pack8(f32x4 a, f32x4 b) { u32x4 w; w.x = pk2(a[0], a[1]); w.y = pk2(a[2], a[3]); w.z = pk2(b[0], b[1]); w.w = pk2(b[2], b[3]); return w; }
;     __device__ __forceinline__ void operator()(const Acc& acc, const pg8::Unit& u, int wid) const {
;     ...
;                 for (int mm = 0; mm < 2; ++mm) { const int row = row0 + ai * 128 + (2 * mp + mm) * 16;
;                     scv[mm] = ssq[row];
;                     const f32x4* rp = (const f32x4*)(rssq + (size_t)row * 64 + head * 16);
; #pragma unroll
;                     for (int i = 0; i < 4; ++i) rq[mm][i] = rp[i];
; #pragma unroll
;                     for (int bj = 0; bj < 2; ++bj) ov[mm][bj] = *(const u32x4*)(Y + (size_t)row * 2048 + col0 + bj * 128); }
; #pragma unroll
;                 for (int mm = 0; mm < 2; ++mm) { const int m = 2 * mp + mm, row = row0 + ai * 128 + m * 16;
;                     const float sc = __builtin_amdgcn_rsqf(scv[mm] * (1.f / 1024.f) + EPS);
;                     const f32x4 pa = (rq[mm][0] + rq[mm][1]) + (rq[mm][2] + rq[mm][3]);
;                     const float rg = __builtin_amdgcn_rsqf(((pa[0] + pa[1]) + (pa[2] + pa[3])) * (1.f / 512.f) + EPS);
; #pragma unroll
;                     for (int bj = 0; bj < 2; ++bj) {
;                         const u32x4 w = ov[mm][bj];
;                         f32x4 o0 = (f32x4){bflo(w.x), bfhi(w.x), bflo(w.y), bfhi(w.y)}, o1 = (f32x4){bflo(w.z), bfhi(w.z), bflo(w.w), bfhi(w.w)};
;                         f32x4 a0 = acc[ai][bj][m][0] * sc, a1 = acc[ai][bj][m][1] * sc;
; #pragma unroll
;                         for (int e = 0; e < 4; ++e) { a0[e] = a0[e] * __builtin_amdgcn_rcpf(1.f + __builtin_amdgcn_exp2f(-1.4426950408889634f * a0[e])); a1[e] = a1[e] * __builtin_amdgcn_rcpf(1.f + __builtin_amdgcn_exp2f(-1.4426950408889634f * a1[e])); }
;                         o0 = a0 * o0 * g4[bj][0] * rg; o1 = a1 * o1 * g4[bj][1] * rg;
;                         *(u32x4*)(Y + (size_t)row * 2048 + col0 + bj * 128) = pack8(o0, o1);
;                     } }
	v_add_f32_e32 v129, 1.0, v129
	v_rcp_f32_e32 v134, v129
	v_add_f32_e32 v129, 1.0, v135
	v_rcp_f32_e32 v142, v129
	v_add_f32_e32 v129, 1.0, v143
	v_mul_f32_e32 v143, 0xbfb8aa3b, v118
	v_cvt_pk_bf16_f32 v121, v126, v127
	v_lshlrev_b32_e32 v126, 16, v144
	v_and_b32_e32 v127, 0xffff0000, v144
	v_exp_f32_e32 v143, v143
	v_mul_f32_e32 v144, 0xbfb8aa3b, v114
	v_lshlrev_b32_e32 v136, 16, v145
	v_and_b32_e32 v137, 0xffff0000, v145
	v_exp_f32_e32 v145, v144
	v_add_f32_e32 v143, 1.0, v143
	v_rcp_f32_e32 v144, v143
	v_lshlrev_b32_e32 v138, 16, v146
	v_add_f32_e32 v143, 1.0, v145
	v_mul_f32_e32 v145, 0xbfb8aa3b, v119
	v_and_b32_e32 v139, 0xffff0000, v146
	v_rcp_f32_e32 v135, v129
	v_mul_f32_e32 v129, 0xbfb8aa3b, v113
	v_exp_f32_e32 v145, v145
	v_mul_f32_e32 v146, 0xbfb8aa3b, v115
	v_lshlrev_b32_e32 v140, 16, v147
	v_and_b32_e32 v141, 0xffff0000, v147
	v_exp_f32_e32 v129, v129
	v_exp_f32_e32 v147, v146
	v_rcp_f32_e32 v146, v143
	v_add_f32_e32 v143, 1.0, v145
	v_add_f32_e32 v129, 1.0, v129
	v_rcp_f32_e32 v145, v143
	v_add_f32_e32 v143, 1.0, v147
	v_rcp_f32_e32 v147, v143
	v_rcp_f32_e32 v143, v129
	v_cvt_pk_bf16_f32 v120, v124, v125
	v_lshl_add_u64 v[124:125], s[36:37], 0, v[192:193]
	v_pk_mul_f32 v[118:119], v[118:119], v[144:145]
	v_pk_mul_f32 v[116:117], v[116:117], v[134:135]
	v_pk_mul_f32 v[114:115], v[114:115], v[146:147]
	v_pk_mul_f32 v[112:113], v[112:113], v[142:143]
	v_cvt_pk_bf16_f32 v122, v122, v123
	v_cvt_pk_bf16_f32 v123, v130, v131
	v_lshl_add_u64 v[124:125], v[124:125], 0, v[184:185]
	v_pk_mul_f32 v[116:117], v[116:117], v[126:127]
	v_pk_mul_f32 v[118:119], v[118:119], v[136:137]
	v_pk_mul_f32 v[112:113], v[112:113], v[138:139]
	v_pk_mul_f32 v[114:115], v[114:115], v[140:141]
	flat_store_dwordx4 v[124:125], v[120:123]
	v_pk_mul_f32 v[118:119], v[58:59], v[118:119]
	v_pk_mul_f32 v[116:117], v[56:57], v[116:117]
	v_or_b32_e32 v120, 32, v186
	v_pk_mul_f32 v[114:115], v[50:51], v[114:115]
	v_pk_mul_f32 v[112:113], v[48:49], v[112:113]
	v_ashrrev_i32_e32 v121, 31, v120
	v_pk_mul_f32 v[118:119], v[128:129], v[118:119] op_sel_hi:[0,1]
	v_pk_mul_f32 v[116:117], v[128:129], v[116:117] op_sel_hi:[0,1]
	v_pk_mul_f32 v[126:127], v[128:129], v[114:115] op_sel_hi:[0,1]
	v_pk_mul_f32 v[114:115], v[128:129], v[112:113] op_sel_hi:[0,1]
	v_lshlrev_b64 v[162:163], 12, v[120:121]
	v_cvt_pk_bf16_f32 v112, v116, v117
	v_cvt_pk_bf16_f32 v113, v118, v119
	v_cvt_pk_bf16_f32 v114, v114, v115
	v_cvt_pk_bf16_f32 v115, v126, v127
	v_lshl_add_u64 v[122:123], v[190:191], 0, v[162:163]
	flat_store_dwordx4 v[124:125], v[112:115] offset:256
	flat_load_dwordx4 v[130:133], v[122:123]
	s_nop 0
	v_lshlrev_b64 v[112:113], 8, v[120:121]
	v_lshl_add_u64 v[112:113], s[20:21], 0, v[112:113]
	flat_load_dword v164, v[188:189] offset:128
	flat_load_dwordx4 v[134:137], v[112:113]
	flat_load_dwordx4 v[138:141], v[112:113] offset:16
	flat_load_dwordx4 v[142:145], v[112:113] offset:32
	flat_load_dwordx4 v[146:149], v[112:113] offset:48
	flat_load_dwordx4 v[150:153], v[122:123] offset:256
	flat_load_dword v165, v[188:189] offset:192
	v_or_b32_e32 v112, 48, v186
	v_ashrrev_i32_e32 v113, 31, v112
	v_lshlrev_b64 v[114:115], 8, v[112:113]
	v_lshl_add_u64 v[114:115], s[20:21], 0, v[114:115]
	flat_load_dwordx4 v[154:157], v[114:115]
	flat_load_dwordx4 v[158:161], v[114:115] offset:16
	flat_load_dwordx4 v[120:123], v[114:115] offset:32
	flat_load_dwordx4 v[124:127], v[114:115] offset:48
	v_lshlrev_b64 v[128:129], 12, v[112:113]
	v_lshl_add_u64 v[112:113], v[190:191], 0, v[128:129]
	flat_load_dwordx4 v[116:119], v[112:113]
	s_nop 0
	flat_load_dwordx4 v[112:115], v[112:113] offset:256
	s_waitcnt vmcnt(0) lgkmcnt(0)
	v_fmamk_f32 v164, v164, 0x3a800000, v198
	v_rsq_f32_e32 v164, v164
	v_pk_add_f32 v[136:137], v[136:137], v[140:141]
	v_pk_add_f32 v[134:135], v[134:135], v[138:139]
	v_pk_add_f32 v[138:139], v[144:145], v[148:149]
	v_pk_add_f32 v[140:141], v[142:143], v[146:147]
	v_pk_add_f32 v[136:137], v[136:137], v[138:139]
	v_pk_add_f32 v[134:135], v[134:135], v[140:141]
	v_pk_mul_f32 v[108:109], v[108:109], v[164:165] op_sel_hi:[1,0]
	v_pk_mov_b32 v[138:139], v[134:135], v[136:137] op_sel:[1,0]
	v_mov_b32_e32 v135, v137
	v_pk_add_f32 v[134:135], v[138:139], v[134:135]
	v_pk_mul_f32 v[104:105], v[104:105], v[164:165] op_sel_hi:[1,0]
	v_add_f32_e32 v134, v134, v135
	v_mul_f32_e32 v135, 0xbfb8aa3b, v108
	v_exp_f32_e32 v135, v135
	v_mul_f32_e32 v140, 0xbfb8aa3b, v104
	v_exp_f32_e32 v141, v140
	v_mul_f32_e32 v140, 0xbfb8aa3b, v109
	v_exp_f32_e32 v143, v140
	v_add_f32_e32 v135, 1.0, v135
	v_pk_mul_f32 v[110:111], v[110:111], v[164:165] op_sel_hi:[1,0]
	v_rcp_f32_e32 v140, v135
	v_add_f32_e32 v135, 1.0, v141
	v_pk_mul_f32 v[106:107], v[106:107], v[164:165] op_sel_hi:[1,0]
	v_rcp_f32_e32 v142, v135
	v_add_f32_e32 v135, 1.0, v143
	v_mul_f32_e32 v143, 0xbfb8aa3b, v110
	v_exp_f32_e32 v143, v143
	v_mul_f32_e32 v144, 0xbfb8aa3b, v106
	v_exp_f32_e32 v145, v144
	v_rcp_f32_e32 v141, v135
	v_add_f32_e32 v143, 1.0, v143
	v_rcp_f32_e32 v144, v143
	v_add_f32_e32 v143, 1.0, v145
	v_mul_f32_e32 v145, 0xbfb8aa3b, v111
	v_mul_f32_e32 v135, 0xbfb8aa3b, v105
	v_exp_f32_e32 v145, v145
	v_mul_f32_e32 v146, 0xbfb8aa3b, v107
	v_exp_f32_e32 v135, v135
	v_exp_f32_e32 v147, v146
	v_rcp_f32_e32 v146, v143
	v_add_f32_e32 v143, 1.0, v145
	v_add_f32_e32 v135, 1.0, v135
	v_rcp_f32_e32 v145, v143
	v_add_f32_e32 v143, 1.0, v147
	v_rcp_f32_e32 v147, v143
	v_rcp_f32_e32 v143, v135
	v_fmamk_f32 v134, v134, 0x3b000000, v198
	v_rsq_f32_e32 v134, v134
	v_lshlrev_b32_e32 v136, 16, v130
	v_and_b32_e32 v137, 0xffff0000, v130
	v_lshlrev_b32_e32 v130, 16, v131
	v_and_b32_e32 v131, 0xffff0000, v131
	v_lshlrev_b32_e32 v138, 16, v132
; __device__ __forceinline__ u32x4 pack8(f32x4 a, f32x4 b) { u32x4 w; w.x = pk2(a[0], a[1]); w.y = pk2(a[2], a[3]); w.z = pk2(b[0], b[1]); w.w = pk2(b[2], b[3]); return w; }
;     __device__ __forceinline__ void operator()(const Acc& acc, const pg8::Unit& u, int wid) const {
;     ...
;                 for (int mm = 0; mm < 2; ++mm) { const int m = 2 * mp + mm, row = row0 + ai * 128 + m * 16;
;                     const float sc = __builtin_amdgcn_rsqf(scv[mm] * (1.f / 1024.f) + EPS);
;                     const f32x4 pa = (rq[mm][0] + rq[mm][1]) + (rq[mm][2] + rq[mm][3]);
;                     const float rg = __builtin_amdgcn_rsqf(((pa[0] + pa[1]) + (pa[2] + pa[3])) * (1.f / 512.f) + EPS);
; #pragma unroll
;                     for (int bj = 0; bj < 2; ++bj) {
;                         const u32x4 w = ov[mm][bj];
;                         f32x4 o0 = (f32x4){bflo(w.x), bfhi(w.x), bflo(w.y), bfhi(w.y)}, o1 = (f32x4){bflo(w.z), bfhi(w.z), bflo(w.w), bfhi(w.w)};
;                         f32x4 a0 = acc[ai][bj][m][0] * sc, a1 = acc[ai][bj][m][1] * sc;
; #pragma unroll
;                         for (int e = 0; e < 4; ++e) { a0[e] = a0[e] * __builtin_amdgcn_rcpf(1.f + __builtin_amdgcn_exp2f(-1.4426950408889634f * a0[e])); a1[e] = a1[e] * __builtin_amdgcn_rcpf(1.f + __builtin_amdgcn_exp2f(-1.4426950408889634f * a1[e])); }
;                         o0 = a0 * o0 * g4[bj][0] * rg; o1 = a1 * o1 * g4[bj][1] * rg;
;                         *(u32x4*)(Y + (size_t)row * 2048 + col0 + bj * 128) = pack8(o0, o1);
;                     } }
	v_and_b32_e32 v139, 0xffff0000, v132
	v_lshlrev_b32_e32 v132, 16, v133
	v_and_b32_e32 v133, 0xffff0000, v133
	v_pk_mul_f32 v[110:111], v[110:111], v[144:145]
	v_pk_mul_f32 v[108:109], v[108:109], v[140:141]
	v_pk_mul_f32 v[106:107], v[106:107], v[146:147]
	v_pk_mul_f32 v[104:105], v[104:105], v[142:143]
	v_pk_mul_f32 v[102:103], v[102:103], v[164:165] op_sel_hi:[1,0]
	v_pk_mul_f32 v[108:109], v[108:109], v[136:137]
	v_pk_mul_f32 v[110:111], v[110:111], v[130:131]
	v_pk_mul_f32 v[104:105], v[104:105], v[138:139]
	v_pk_mul_f32 v[106:107], v[106:107], v[132:133]
	v_pk_mul_f32 v[98:99], v[98:99], v[164:165] op_sel_hi:[1,0]
	v_pk_mul_f32 v[96:97], v[96:97], v[164:165] op_sel_hi:[1,0]
	v_mul_f32_e32 v137, 0xbfb8aa3b, v102
	v_pk_mul_f32 v[110:111], v[66:67], v[110:111]
	v_pk_mul_f32 v[108:109], v[64:65], v[108:109]
	v_pk_mul_f32 v[106:107], v[70:71], v[106:107]
	v_pk_mul_f32 v[104:105], v[68:69], v[104:105]
	v_pk_mul_f32 v[100:101], v[100:101], v[164:165] op_sel_hi:[1,0]
	v_mul_f32_e32 v133, 0xbfb8aa3b, v96
	v_exp_f32_e32 v137, v137
	v_mul_f32_e32 v138, 0xbfb8aa3b, v98
	v_pk_mul_f32 v[110:111], v[134:135], v[110:111] op_sel_hi:[0,1]
	v_pk_mul_f32 v[108:109], v[134:135], v[108:109] op_sel_hi:[0,1]
	v_pk_mul_f32 v[130:131], v[134:135], v[106:107] op_sel_hi:[0,1]
	v_pk_mul_f32 v[106:107], v[134:135], v[104:105] op_sel_hi:[0,1]
	v_exp_f32_e32 v133, v133
	v_mul_f32_e32 v135, 0xbfb8aa3b, v101
	v_exp_f32_e32 v139, v138
	v_exp_f32_e32 v135, v135
	v_add_f32_e32 v137, 1.0, v137
	v_add_f32_e32 v133, 1.0, v133
	v_rcp_f32_e32 v138, v137
	v_add_f32_e32 v137, 1.0, v139
	v_mul_f32_e32 v139, 0xbfb8aa3b, v103
	v_mul_f32_e32 v132, 0xbfb8aa3b, v100
	v_rcp_f32_e32 v136, v133
	v_add_f32_e32 v133, 1.0, v135
	v_mul_f32_e32 v135, 0xbfb8aa3b, v97
	v_exp_f32_e32 v139, v139
	v_mul_f32_e32 v140, 0xbfb8aa3b, v99
	v_exp_f32_e32 v132, v132
	v_exp_f32_e32 v135, v135
	v_exp_f32_e32 v141, v140
	v_rcp_f32_e32 v140, v137
	v_add_f32_e32 v137, 1.0, v139
	v_add_f32_e32 v132, 1.0, v132
	v_add_f32_e32 v135, 1.0, v135
	v_rcp_f32_e32 v139, v137
	v_add_f32_e32 v137, 1.0, v141
	v_rcp_f32_e32 v132, v132
	v_rcp_f32_e32 v133, v133
	v_rcp_f32_e32 v141, v137
	v_rcp_f32_e32 v137, v135
	v_cvt_pk_bf16_f32 v104, v108, v109
	v_lshl_add_u64 v[108:109], s[36:37], 0, v[162:163]
	v_cvt_pk_bf16_f32 v105, v110, v111
	v_cvt_pk_bf16_f32 v106, v106, v107
	v_cvt_pk_bf16_f32 v107, v130, v131
	v_lshl_add_u64 v[108:109], v[108:109], 0, v[184:185]
	flat_store_dwordx4 v[108:109], v[104:107]
	v_lshlrev_b32_e32 v110, 16, v152
	v_and_b32_e32 v111, 0xffff0000, v152
	v_lshlrev_b32_e32 v104, 16, v150
	v_and_b32_e32 v105, 0xffff0000, v150
	v_lshlrev_b32_e32 v106, 16, v151
	v_and_b32_e32 v107, 0xffff0000, v151
	v_lshlrev_b32_e32 v130, 16, v153
	v_and_b32_e32 v131, 0xffff0000, v153
	v_pk_mul_f32 v[102:103], v[102:103], v[138:139]
	v_pk_mul_f32 v[100:101], v[100:101], v[132:133]
	v_pk_mul_f32 v[98:99], v[98:99], v[140:141]
	v_pk_mul_f32 v[96:97], v[96:97], v[136:137]
	v_pk_mul_f32 v[100:101], v[100:101], v[104:105]
	v_pk_mul_f32 v[102:103], v[102:103], v[106:107]
	v_pk_mul_f32 v[96:97], v[96:97], v[110:111]
	v_pk_mul_f32 v[98:99], v[98:99], v[130:131]
	v_pk_mul_f32 v[102:103], v[58:59], v[102:103]
	v_pk_mul_f32 v[100:101], v[56:57], v[100:101]
	v_pk_mul_f32 v[98:99], v[50:51], v[98:99]
	v_pk_mul_f32 v[96:97], v[48:49], v[96:97]
	v_pk_mul_f32 v[102:103], v[134:135], v[102:103] op_sel_hi:[0,1]
	v_pk_mul_f32 v[100:101], v[134:135], v[100:101] op_sel_hi:[0,1]
	v_pk_mul_f32 v[104:105], v[134:135], v[98:99] op_sel_hi:[0,1]
	v_pk_mul_f32 v[98:99], v[134:135], v[96:97] op_sel_hi:[0,1]
	v_cvt_pk_bf16_f32 v96, v100, v101
	v_cvt_pk_bf16_f32 v97, v102, v103
	v_cvt_pk_bf16_f32 v98, v98, v99
	v_cvt_pk_bf16_f32 v99, v104, v105
	flat_store_dwordx4 v[108:109], v[96:99] offset:256
	v_pk_add_f32 v[100:101], v[154:155], v[158:159]
	v_pk_add_f32 v[102:103], v[122:123], v[126:127]
	v_pk_add_f32 v[98:99], v[156:157], v[160:161]
	v_pk_add_f32 v[104:105], v[120:121], v[124:125]
	v_fmamk_f32 v96, v165, 0x3a800000, v198
	v_pk_add_f32 v[98:99], v[98:99], v[102:103]
	v_pk_add_f32 v[100:101], v[100:101], v[104:105]
	v_rsq_f32_e32 v96, v96
	v_pk_mov_b32 v[102:103], v[100:101], v[98:99] op_sel:[1,0]
	v_mov_b32_e32 v101, v99
	v_pk_add_f32 v[98:99], v[102:103], v[100:101]
	v_lshlrev_b32_e32 v100, 16, v116
	v_add_f32_e32 v97, v98, v99
	v_fmamk_f32 v97, v97, 0x3b000000, v198
	v_pk_mul_f32 v[92:93], v[92:93], v[96:97] op_sel_hi:[1,0]
	v_rsq_f32_e32 v98, v97
	v_mul_f32_e32 v97, 0xbfb8aa3b, v92
	v_exp_f32_e32 v97, v97
	v_mul_f32_e32 v108, 0xbfb8aa3b, v93
	v_exp_f32_e32 v109, v108
	v_and_b32_e32 v101, 0xffff0000, v116
	v_pk_mul_f32 v[88:89], v[88:89], v[96:97] op_sel_hi:[1,0]
	v_pk_mul_f32 v[94:95], v[94:95], v[96:97] op_sel_hi:[1,0]
	v_mul_f32_e32 v99, 0xbfb8aa3b, v88
	v_exp_f32_e32 v99, v99
	v_pk_mul_f32 v[90:91], v[90:91], v[96:97] op_sel_hi:[1,0]
	v_add_f32_e32 v97, 1.0, v97
	v_rcp_f32_e32 v108, v97
	v_add_f32_e32 v97, 1.0, v99
	v_mul_f32_e32 v99, 0xbfb8aa3b, v94
	v_exp_f32_e32 v99, v99
	v_mul_f32_e32 v111, 0xbfb8aa3b, v90
	v_exp_f32_e32 v111, v111
	v_rcp_f32_e32 v110, v97
	v_add_f32_e32 v97, 1.0, v109
	v_rcp_f32_e32 v109, v97
	v_mul_f32_e32 v97, 0xbfb8aa3b, v89
	v_add_f32_e32 v99, 1.0, v99
	v_exp_f32_e32 v97, v97
	v_rcp_f32_e32 v116, v99
	v_add_f32_e32 v99, 1.0, v111
	v_mul_f32_e32 v111, 0xbfb8aa3b, v95
	v_lshlrev_b32_e32 v102, 16, v117
	v_and_b32_e32 v103, 0xffff0000, v117
	v_exp_f32_e32 v111, v111
	v_mul_f32_e32 v117, 0xbfb8aa3b, v91
	v_lshlrev_b32_e32 v106, 16, v119
	v_and_b32_e32 v107, 0xffff0000, v119
	v_exp_f32_e32 v119, v117
	v_add_f32_e32 v97, 1.0, v97
	v_lshlrev_b32_e32 v104, 16, v118
	v_and_b32_e32 v105, 0xffff0000, v118
	v_rcp_f32_e32 v118, v99
; __device__ __forceinline__ u32x4 pack8(f32x4 a, f32x4 b) { u32x4 w; w.x = pk2(a[0], a[1]); w.y = pk2(a[2], a[3]); w.z = pk2(b[0], b[1]); w.w = pk2(b[2], b[3]); return w; }
;     __device__ __forceinline__ void operator()(const Acc& acc, const pg8::Unit& u, int wid) const {
;     ...
;                 for (int mm = 0; mm < 2; ++mm) { const int row = row0 + ai * 128 + (2 * mp + mm) * 16;
;                     scv[mm] = ssq[row];
;                     const f32x4* rp = (const f32x4*)(rssq + (size_t)row * 64 + head * 16);
; #pragma unroll
;                     for (int i = 0; i < 4; ++i) rq[mm][i] = rp[i];
; #pragma unroll
;                     for (int bj = 0; bj < 2; ++bj) ov[mm][bj] = *(const u32x4*)(Y + (size_t)row * 2048 + col0 + bj * 128); }
; #pragma unroll
;                 for (int mm = 0; mm < 2; ++mm) { const int m = 2 * mp + mm, row = row0 + ai * 128 + m * 16;
;                     const float sc = __builtin_amdgcn_rsqf(scv[mm] * (1.f / 1024.f) + EPS);
;                     const f32x4 pa = (rq[mm][0] + rq[mm][1]) + (rq[mm][2] + rq[mm][3]);
;                     const float rg = __builtin_amdgcn_rsqf(((pa[0] + pa[1]) + (pa[2] + pa[3])) * (1.f / 512.f) + EPS);
; #pragma unroll
;                     for (int bj = 0; bj < 2; ++bj) {
;                         const u32x4 w = ov[mm][bj];
;                         f32x4 o0 = (f32x4){bflo(w.x), bfhi(w.x), bflo(w.y), bfhi(w.y)}, o1 = (f32x4){bflo(w.z), bfhi(w.z), bflo(w.w), bfhi(w.w)};
;                         f32x4 a0 = acc[ai][bj][m][0] * sc, a1 = acc[ai][bj][m][1] * sc;
; #pragma unroll
;                         for (int e = 0; e < 4; ++e) { a0[e] = a0[e] * __builtin_amdgcn_rcpf(1.f + __builtin_amdgcn_exp2f(-1.4426950408889634f * a0[e])); a1[e] = a1[e] * __builtin_amdgcn_rcpf(1.f + __builtin_amdgcn_exp2f(-1.4426950408889634f * a1[e])); }
;                         o0 = a0 * o0 * g4[bj][0] * rg; o1 = a1 * o1 * g4[bj][1] * rg;
;                         *(u32x4*)(Y + (size_t)row * 2048 + col0 + bj * 128) = pack8(o0, o1);
;                     } }
	v_add_f32_e32 v99, 1.0, v111
	v_pk_mul_f32 v[84:85], v[84:85], v[96:97] op_sel_hi:[1,0]
	v_rcp_f32_e32 v117, v99
	v_add_f32_e32 v99, 1.0, v119
	v_rcp_f32_e32 v111, v97
	v_mul_f32_e32 v97, 0xbfb8aa3b, v84
	v_rcp_f32_e32 v119, v99
	v_exp_f32_e32 v97, v97
	v_pk_mul_f32 v[94:95], v[94:95], v[116:117]
	v_pk_mul_f32 v[92:93], v[92:93], v[108:109]
	v_pk_mul_f32 v[90:91], v[90:91], v[118:119]
	v_pk_mul_f32 v[88:89], v[88:89], v[110:111]
	v_pk_mul_f32 v[86:87], v[86:87], v[96:97] op_sel_hi:[1,0]
	v_pk_mul_f32 v[92:93], v[92:93], v[100:101]
	v_pk_mul_f32 v[94:95], v[94:95], v[102:103]
	v_pk_mul_f32 v[88:89], v[88:89], v[104:105]
	v_pk_mul_f32 v[90:91], v[90:91], v[106:107]
	v_pk_mul_f32 v[82:83], v[82:83], v[96:97] op_sel_hi:[1,0]
	v_pk_mul_f32 v[80:81], v[80:81], v[96:97] op_sel_hi:[1,0]
	v_mul_f32_e32 v103, 0xbfb8aa3b, v86
	v_pk_mul_f32 v[94:95], v[66:67], v[94:95]
	v_pk_mul_f32 v[92:93], v[64:65], v[92:93]
	v_pk_mul_f32 v[90:91], v[70:71], v[90:91]
	v_pk_mul_f32 v[88:89], v[68:69], v[88:89]
	v_add_f32_e32 v96, 1.0, v97
	v_mul_f32_e32 v97, 0xbfb8aa3b, v80
	v_exp_f32_e32 v103, v103
	v_mul_f32_e32 v104, 0xbfb8aa3b, v82
	v_pk_mul_f32 v[94:95], v[98:99], v[94:95] op_sel_hi:[0,1]
	v_pk_mul_f32 v[92:93], v[98:99], v[92:93] op_sel_hi:[0,1]
	v_pk_mul_f32 v[100:101], v[98:99], v[90:91] op_sel_hi:[0,1]
	v_pk_mul_f32 v[90:91], v[98:99], v[88:89] op_sel_hi:[0,1]
	v_exp_f32_e32 v97, v97
	v_mul_f32_e32 v99, 0xbfb8aa3b, v85
	v_exp_f32_e32 v105, v104
	v_exp_f32_e32 v99, v99
	v_add_f32_e32 v103, 1.0, v103
	v_add_f32_e32 v97, 1.0, v97
	v_rcp_f32_e32 v104, v103
	v_add_f32_e32 v103, 1.0, v105
	v_mul_f32_e32 v105, 0xbfb8aa3b, v87
	v_rcp_f32_e32 v102, v97
	v_add_f32_e32 v97, 1.0, v99
	v_mul_f32_e32 v99, 0xbfb8aa3b, v81
	v_exp_f32_e32 v105, v105
	v_mul_f32_e32 v106, 0xbfb8aa3b, v83
	v_exp_f32_e32 v99, v99
	v_exp_f32_e32 v107, v106
	v_rcp_f32_e32 v106, v103
	v_add_f32_e32 v103, 1.0, v105
	v_add_f32_e32 v99, 1.0, v99
	v_rcp_f32_e32 v105, v103
	v_add_f32_e32 v103, 1.0, v107
	v_rcp_f32_e32 v96, v96
	v_rcp_f32_e32 v97, v97
	v_rcp_f32_e32 v107, v103
	v_rcp_f32_e32 v103, v99
	v_cvt_pk_bf16_f32 v88, v92, v93
	v_lshl_add_u64 v[92:93], s[36:37], 0, v[128:129]
	v_cvt_pk_bf16_f32 v89, v94, v95
	v_cvt_pk_bf16_f32 v90, v90, v91
	v_cvt_pk_bf16_f32 v91, v100, v101
	v_lshl_add_u64 v[92:93], v[92:93], 0, v[184:185]
	flat_store_dwordx4 v[92:93], v[88:91]
	v_lshlrev_b32_e32 v94, 16, v114
	v_and_b32_e32 v95, 0xffff0000, v114
	v_lshlrev_b32_e32 v88, 16, v112
	v_and_b32_e32 v89, 0xffff0000, v112
	v_lshlrev_b32_e32 v90, 16, v113
	v_and_b32_e32 v91, 0xffff0000, v113
	v_lshlrev_b32_e32 v100, 16, v115
	v_and_b32_e32 v101, 0xffff0000, v115
	v_pk_mul_f32 v[86:87], v[86:87], v[104:105]
	v_pk_mul_f32 v[84:85], v[84:85], v[96:97]
	v_pk_mul_f32 v[82:83], v[82:83], v[106:107]
	v_pk_mul_f32 v[80:81], v[80:81], v[102:103]
	v_pk_mul_f32 v[84:85], v[84:85], v[88:89]
	v_pk_mul_f32 v[86:87], v[86:87], v[90:91]
	v_pk_mul_f32 v[80:81], v[80:81], v[94:95]
	v_pk_mul_f32 v[82:83], v[82:83], v[100:101]
	v_pk_mul_f32 v[86:87], v[58:59], v[86:87]
	v_pk_mul_f32 v[84:85], v[56:57], v[84:85]
	v_pk_mul_f32 v[82:83], v[50:51], v[82:83]
	v_pk_mul_f32 v[80:81], v[48:49], v[80:81]
	v_pk_mul_f32 v[86:87], v[98:99], v[86:87] op_sel_hi:[0,1]
	v_pk_mul_f32 v[84:85], v[98:99], v[84:85] op_sel_hi:[0,1]
	v_pk_mul_f32 v[88:89], v[98:99], v[82:83] op_sel_hi:[0,1]
	v_pk_mul_f32 v[82:83], v[98:99], v[80:81] op_sel_hi:[0,1]
	v_cvt_pk_bf16_f32 v80, v84, v85
	v_cvt_pk_bf16_f32 v81, v86, v87
	v_cvt_pk_bf16_f32 v82, v82, v83
	v_cvt_pk_bf16_f32 v83, v88, v89
	flat_store_dwordx4 v[92:93], v[80:83] offset:256
	s_nop 1
	v_add_u32_e32 v80, 0x80, v186
	v_ashrrev_i32_e32 v81, 31, v80
	v_lshlrev_b64 v[82:83], 8, v[80:81]
	v_lshl_add_u64 v[82:83], s[20:21], 0, v[82:83]
	flat_load_dword v132, v[188:189] offset:512
	flat_load_dwordx4 v[94:97], v[82:83]
	flat_load_dwordx4 v[98:101], v[82:83] offset:16
	flat_load_dwordx4 v[102:105], v[82:83] offset:32
	flat_load_dwordx4 v[106:109], v[82:83] offset:48
	v_lshlrev_b64 v[130:131], 12, v[80:81]
	v_lshl_add_u64 v[80:81], v[190:191], 0, v[130:131]
	flat_load_dwordx4 v[110:113], v[80:81]
	flat_load_dword v133, v[188:189] offset:576
	v_add_u32_e32 v82, 0x90, v186
	v_ashrrev_i32_e32 v83, 31, v82
	v_lshlrev_b64 v[84:85], 8, v[82:83]
	v_lshl_add_u64 v[84:85], s[20:21], 0, v[84:85]
	flat_load_dwordx4 v[114:117], v[80:81] offset:256
	flat_load_dwordx4 v[118:121], v[84:85]
	flat_load_dwordx4 v[122:125], v[84:85] offset:16
	flat_load_dwordx4 v[88:91], v[84:85] offset:32
	v_lshlrev_b64 v[92:93], 12, v[82:83]
	v_lshl_add_u64 v[80:81], v[190:191], 0, v[92:93]
	flat_load_dwordx4 v[126:129], v[84:85] offset:48
	s_nop 0
	flat_load_dwordx4 v[84:87], v[80:81]
	s_nop 0
	flat_load_dwordx4 v[80:83], v[80:81] offset:256
	s_waitcnt vmcnt(0) lgkmcnt(0)
; __device__ __forceinline__ u32x4 pack8(f32x4 a, f32x4 b) { u32x4 w; w.x = pk2(a[0], a[1]); w.y = pk2(a[2], a[3]); w.z = pk2(b[0], b[1]); w.w = pk2(b[2], b[3]); return w; }
;     __device__ __forceinline__ void operator()(const Acc& acc, const pg8::Unit& u, int wid) const {
;     ...
;                 for (int mm = 0; mm < 2; ++mm) { const int row = row0 + ai * 128 + (2 * mp + mm) * 16;
;                     scv[mm] = ssq[row];
;                     const f32x4* rp = (const f32x4*)(rssq + (size_t)row * 64 + head * 16);
; #pragma unroll
;                     for (int i = 0; i < 4; ++i) rq[mm][i] = rp[i];
; #pragma unroll
;                     for (int bj = 0; bj < 2; ++bj) ov[mm][bj] = *(const u32x4*)(Y + (size_t)row * 2048 + col0 + bj * 128); }
; #pragma unroll
;                 for (int mm = 0; mm < 2; ++mm) { const int m = 2 * mp + mm, row = row0 + ai * 128 + m * 16;
;                     const float sc = __builtin_amdgcn_rsqf(scv[mm] * (1.f / 1024.f) + EPS);
;                     const f32x4 pa = (rq[mm][0] + rq[mm][1]) + (rq[mm][2] + rq[mm][3]);
;                     const float rg = __builtin_amdgcn_rsqf(((pa[0] + pa[1]) + (pa[2] + pa[3])) * (1.f / 512.f) + EPS);
; #pragma unroll
;                     for (int bj = 0; bj < 2; ++bj) {
;                         const u32x4 w = ov[mm][bj];
;                         f32x4 o0 = (f32x4){bflo(w.x), bfhi(w.x), bflo(w.y), bfhi(w.y)}, o1 = (f32x4){bflo(w.z), bfhi(w.z), bflo(w.w), bfhi(w.w)};
;                         f32x4 a0 = acc[ai][bj][m][0] * sc, a1 = acc[ai][bj][m][1] * sc;
; #pragma unroll
;                         for (int e = 0; e < 4; ++e) { a0[e] = a0[e] * __builtin_amdgcn_rcpf(1.f + __builtin_amdgcn_exp2f(-1.4426950408889634f * a0[e])); a1[e] = a1[e] * __builtin_amdgcn_rcpf(1.f + __builtin_amdgcn_exp2f(-1.4426950408889634f * a1[e])); }
;                         o0 = a0 * o0 * g4[bj][0] * rg; o1 = a1 * o1 * g4[bj][1] * rg;
;                         *(u32x4*)(Y + (size_t)row * 2048 + col0 + bj * 128) = pack8(o0, o1);
;                     } }
	v_add_u32_e32 v144, 0xa0, v186
	v_ashrrev_i32_e32 v145, 31, v144
	v_lshlrev_b64 v[216:217], 12, v[144:145]
	v_lshl_add_u64 v[146:147], v[190:191], 0, v[216:217]
	global_load_dwordx4 v[152:155], v[146:147], off
	s_nop 0
	v_lshlrev_b64 v[136:137], 8, v[144:145]
	v_lshl_add_u64 v[136:137], s[20:21], 0, v[136:137]
	global_load_dword v192, v[188:189], off offset:640
	global_load_dwordx4 v[156:159], v[136:137], off
	global_load_dwordx4 v[160:163], v[136:137], off offset:16
	global_load_dwordx4 v[164:167], v[136:137], off offset:32
	global_load_dwordx4 v[200:203], v[136:137], off offset:48
	global_load_dwordx4 v[204:207], v[146:147], off offset:256
	v_add_u32_e32 v136, 0xb0, v186
	v_ashrrev_i32_e32 v137, 31, v136
	v_lshlrev_b64 v[138:139], 8, v[136:137]
	v_lshl_add_u64 v[138:139], s[20:21], 0, v[138:139]
	global_load_dword v187, v[188:189], off offset:704
	global_load_dwordx4 v[208:211], v[138:139], off
	global_load_dwordx4 v[212:215], v[138:139], off offset:16
	global_load_dwordx4 v[144:147], v[138:139], off offset:32
	global_load_dwordx4 v[148:151], v[138:139], off offset:48
	v_lshlrev_b64 v[134:135], 12, v[136:137]
	v_lshl_add_u64 v[136:137], v[190:191], 0, v[134:135]
	global_load_dwordx4 v[140:143], v[136:137], off
	s_nop 0
	global_load_dwordx4 v[136:139], v[136:137], off offset:256
	v_fmamk_f32 v132, v132, 0x3a800000, v198
	v_rsq_f32_e32 v132, v132
	v_pk_add_f32 v[96:97], v[96:97], v[100:101]
	v_pk_add_f32 v[94:95], v[94:95], v[98:99]
	v_pk_add_f32 v[98:99], v[104:105], v[108:109]
	v_pk_add_f32 v[100:101], v[102:103], v[106:107]
	v_pk_add_f32 v[96:97], v[96:97], v[98:99]
	v_pk_add_f32 v[94:95], v[94:95], v[100:101]
	v_pk_mul_f32 v[76:77], v[76:77], v[132:133] op_sel_hi:[1,0]
	v_pk_mov_b32 v[98:99], v[94:95], v[96:97] op_sel:[1,0]
	v_mov_b32_e32 v95, v97
	v_pk_add_f32 v[94:95], v[98:99], v[94:95]
	v_pk_mul_f32 v[72:73], v[72:73], v[132:133] op_sel_hi:[1,0]
	v_add_f32_e32 v94, v94, v95
	v_mul_f32_e32 v95, 0xbfb8aa3b, v76
	v_exp_f32_e32 v95, v95
	v_mul_f32_e32 v104, 0xbfb8aa3b, v72
	v_exp_f32_e32 v105, v104
	v_mul_f32_e32 v104, 0xbfb8aa3b, v77
	v_exp_f32_e32 v107, v104
	v_add_f32_e32 v95, 1.0, v95
	v_pk_mul_f32 v[78:79], v[78:79], v[132:133] op_sel_hi:[1,0]
	v_rcp_f32_e32 v104, v95
	v_add_f32_e32 v95, 1.0, v105
	v_pk_mul_f32 v[74:75], v[74:75], v[132:133] op_sel_hi:[1,0]
	v_rcp_f32_e32 v106, v95
	v_add_f32_e32 v95, 1.0, v107
	v_mul_f32_e32 v107, 0xbfb8aa3b, v78
	v_exp_f32_e32 v107, v107
	v_mul_f32_e32 v108, 0xbfb8aa3b, v74
	v_exp_f32_e32 v109, v108
	v_lshlrev_b32_e32 v96, 16, v110
	v_add_f32_e32 v107, 1.0, v107
	v_rcp_f32_e32 v108, v107
	v_add_f32_e32 v107, 1.0, v109
	v_mul_f32_e32 v109, 0xbfb8aa3b, v79
	v_and_b32_e32 v97, 0xffff0000, v110
	v_rcp_f32_e32 v105, v95
	v_mul_f32_e32 v95, 0xbfb8aa3b, v73
	v_exp_f32_e32 v109, v109
	v_mul_f32_e32 v110, 0xbfb8aa3b, v75
	v_lshlrev_b32_e32 v98, 16, v111
	v_and_b32_e32 v99, 0xffff0000, v111
	v_exp_f32_e32 v95, v95
	v_exp_f32_e32 v111, v110
	v_rcp_f32_e32 v110, v107
	v_add_f32_e32 v107, 1.0, v109
	v_add_f32_e32 v95, 1.0, v95
	v_rcp_f32_e32 v109, v107
	v_add_f32_e32 v107, 1.0, v111
	v_rcp_f32_e32 v111, v107
	v_rcp_f32_e32 v107, v95
	v_fmamk_f32 v94, v94, 0x3b000000, v198
	v_rsq_f32_e32 v94, v94
	v_lshlrev_b32_e32 v100, 16, v112
	v_and_b32_e32 v101, 0xffff0000, v112
	v_lshlrev_b32_e32 v102, 16, v113
	v_and_b32_e32 v103, 0xffff0000, v113
	v_pk_mul_f32 v[78:79], v[78:79], v[108:109]
	v_pk_mul_f32 v[76:77], v[76:77], v[104:105]
	v_pk_mul_f32 v[74:75], v[74:75], v[110:111]
	v_pk_mul_f32 v[72:73], v[72:73], v[106:107]
	v_pk_mul_f32 v[76:77], v[76:77], v[96:97]
	v_pk_mul_f32 v[78:79], v[78:79], v[98:99]
	v_pk_mul_f32 v[72:73], v[72:73], v[100:101]
	v_pk_mul_f32 v[74:75], v[74:75], v[102:103]
	v_pk_mul_f32 v[78:79], v[66:67], v[78:79]
	v_pk_mul_f32 v[76:77], v[64:65], v[76:77]
	v_pk_mul_f32 v[74:75], v[70:71], v[74:75]
	v_pk_mul_f32 v[72:73], v[68:69], v[72:73]
	v_pk_mul_f32 v[60:61], v[60:61], v[132:133] op_sel_hi:[1,0]
	v_pk_mul_f32 v[78:79], v[94:95], v[78:79] op_sel_hi:[0,1]
	v_pk_mul_f32 v[76:77], v[94:95], v[76:77] op_sel_hi:[0,1]
	v_pk_mul_f32 v[96:97], v[94:95], v[74:75] op_sel_hi:[0,1]
	v_pk_mul_f32 v[74:75], v[94:95], v[72:73] op_sel_hi:[0,1]
	v_mul_f32_e32 v95, 0xbfb8aa3b, v60
	v_pk_mul_f32 v[52:53], v[52:53], v[132:133] op_sel_hi:[1,0]
	v_exp_f32_e32 v95, v95
	v_mul_f32_e32 v98, 0xbfb8aa3b, v52
	v_exp_f32_e32 v99, v98
	v_mul_f32_e32 v98, 0xbfb8aa3b, v61
	v_exp_f32_e32 v101, v98
	v_add_f32_e32 v95, 1.0, v95
	v_pk_mul_f32 v[62:63], v[62:63], v[132:133] op_sel_hi:[1,0]
	v_rcp_f32_e32 v98, v95
	v_add_f32_e32 v95, 1.0, v99
	v_pk_mul_f32 v[54:55], v[54:55], v[132:133] op_sel_hi:[1,0]
	v_rcp_f32_e32 v100, v95
	v_add_f32_e32 v95, 1.0, v101
	v_mul_f32_e32 v101, 0xbfb8aa3b, v62
	v_exp_f32_e32 v101, v101
	v_mul_f32_e32 v102, 0xbfb8aa3b, v54
	v_exp_f32_e32 v103, v102
	v_rcp_f32_e32 v99, v95
	v_add_f32_e32 v101, 1.0, v101
	v_rcp_f32_e32 v102, v101
	v_add_f32_e32 v101, 1.0, v103
	v_mul_f32_e32 v103, 0xbfb8aa3b, v63
	v_mul_f32_e32 v95, 0xbfb8aa3b, v53
	v_exp_f32_e32 v103, v103
	v_mul_f32_e32 v104, 0xbfb8aa3b, v55
	v_exp_f32_e32 v95, v95
	v_exp_f32_e32 v105, v104
	v_rcp_f32_e32 v104, v101
	v_add_f32_e32 v101, 1.0, v103
	v_add_f32_e32 v95, 1.0, v95
	v_rcp_f32_e32 v103, v101
	v_add_f32_e32 v101, 1.0, v105
	v_rcp_f32_e32 v105, v101
	v_rcp_f32_e32 v101, v95
	v_cvt_pk_bf16_f32 v72, v76, v77
	v_lshl_add_u64 v[76:77], s[36:37], 0, v[130:131]
	v_cvt_pk_bf16_f32 v73, v78, v79
	v_cvt_pk_bf16_f32 v74, v74, v75
	v_cvt_pk_bf16_f32 v75, v96, v97
	v_lshl_add_u64 v[76:77], v[76:77], 0, v[184:185]
	flat_store_dwordx4 v[76:77], v[72:75]
	v_lshlrev_b32_e32 v78, 16, v116
	v_and_b32_e32 v79, 0xffff0000, v116
	v_lshlrev_b32_e32 v72, 16, v114
; __device__ __forceinline__ u32x4 pack8(f32x4 a, f32x4 b) { u32x4 w; w.x = pk2(a[0], a[1]); w.y = pk2(a[2], a[3]); w.z = pk2(b[0], b[1]); w.w = pk2(b[2], b[3]); return w; }
;     __device__ __forceinline__ void operator()(const Acc& acc, const pg8::Unit& u, int wid) const {
;     ...
;                 for (int mm = 0; mm < 2; ++mm) { const int m = 2 * mp + mm, row = row0 + ai * 128 + m * 16;
;                     const float sc = __builtin_amdgcn_rsqf(scv[mm] * (1.f / 1024.f) + EPS);
;                     const f32x4 pa = (rq[mm][0] + rq[mm][1]) + (rq[mm][2] + rq[mm][3]);
;                     const float rg = __builtin_amdgcn_rsqf(((pa[0] + pa[1]) + (pa[2] + pa[3])) * (1.f / 512.f) + EPS);
; #pragma unroll
;                     for (int bj = 0; bj < 2; ++bj) {
;                         const u32x4 w = ov[mm][bj];
;                         f32x4 o0 = (f32x4){bflo(w.x), bfhi(w.x), bflo(w.y), bfhi(w.y)}, o1 = (f32x4){bflo(w.z), bfhi(w.z), bflo(w.w), bfhi(w.w)};
;                         f32x4 a0 = acc[ai][bj][m][0] * sc, a1 = acc[ai][bj][m][1] * sc;
; #pragma unroll
;                         for (int e = 0; e < 4; ++e) { a0[e] = a0[e] * __builtin_amdgcn_rcpf(1.f + __builtin_amdgcn_exp2f(-1.4426950408889634f * a0[e])); a1[e] = a1[e] * __builtin_amdgcn_rcpf(1.f + __builtin_amdgcn_exp2f(-1.4426950408889634f * a1[e])); }
;                         o0 = a0 * o0 * g4[bj][0] * rg; o1 = a1 * o1 * g4[bj][1] * rg;
;                         *(u32x4*)(Y + (size_t)row * 2048 + col0 + bj * 128) = pack8(o0, o1);
;                     } }
	v_and_b32_e32 v73, 0xffff0000, v114
	v_lshlrev_b32_e32 v74, 16, v115
	v_and_b32_e32 v75, 0xffff0000, v115
	v_lshlrev_b32_e32 v96, 16, v117
	v_and_b32_e32 v97, 0xffff0000, v117
	v_pk_mul_f32 v[62:63], v[62:63], v[102:103]
	v_pk_mul_f32 v[60:61], v[60:61], v[98:99]
	v_pk_mul_f32 v[54:55], v[54:55], v[104:105]
	v_pk_mul_f32 v[52:53], v[52:53], v[100:101]
	v_pk_mul_f32 v[60:61], v[60:61], v[72:73]
	v_pk_mul_f32 v[62:63], v[62:63], v[74:75]
	v_pk_mul_f32 v[52:53], v[52:53], v[78:79]
	v_pk_mul_f32 v[54:55], v[54:55], v[96:97]
	v_pk_mul_f32 v[62:63], v[58:59], v[62:63]
	v_pk_mul_f32 v[60:61], v[56:57], v[60:61]
	v_pk_mul_f32 v[54:55], v[50:51], v[54:55]
	v_pk_mul_f32 v[52:53], v[48:49], v[52:53]
	v_pk_mul_f32 v[62:63], v[94:95], v[62:63] op_sel_hi:[0,1]
	v_pk_mul_f32 v[60:61], v[94:95], v[60:61] op_sel_hi:[0,1]
	v_pk_mul_f32 v[72:73], v[94:95], v[54:55] op_sel_hi:[0,1]
	v_pk_mul_f32 v[54:55], v[94:95], v[52:53] op_sel_hi:[0,1]
	v_cvt_pk_bf16_f32 v52, v60, v61
	v_cvt_pk_bf16_f32 v53, v62, v63
	v_cvt_pk_bf16_f32 v54, v54, v55
	v_cvt_pk_bf16_f32 v55, v72, v73
	flat_store_dwordx4 v[76:77], v[52:55] offset:256
	v_pk_add_f32 v[60:61], v[118:119], v[122:123]
	v_pk_add_f32 v[62:63], v[90:91], v[128:129]
	v_fmamk_f32 v52, v133, 0x3a800000, v198
	v_rsq_f32_e32 v54, v52
	v_pk_add_f32 v[52:53], v[120:121], v[124:125]
	v_pk_add_f32 v[72:73], v[88:89], v[126:127]
	v_pk_add_f32 v[52:53], v[52:53], v[62:63]
	v_pk_add_f32 v[60:61], v[60:61], v[72:73]
	v_pk_mul_f32 v[44:45], v[44:45], v[54:55] op_sel_hi:[1,0]
	v_pk_mov_b32 v[62:63], v[60:61], v[52:53] op_sel:[1,0]
	v_mov_b32_e32 v61, v53
	v_pk_add_f32 v[52:53], v[62:63], v[60:61]
	v_pk_mul_f32 v[40:41], v[40:41], v[54:55] op_sel_hi:[1,0]
	v_add_f32_e32 v52, v52, v53
	v_mul_f32_e32 v53, 0xbfb8aa3b, v44
	v_exp_f32_e32 v53, v53
	v_pk_mul_f32 v[46:47], v[46:47], v[54:55] op_sel_hi:[1,0]
	v_pk_mul_f32 v[42:43], v[42:43], v[54:55] op_sel_hi:[1,0]
	v_mul_f32_e32 v55, 0xbfb8aa3b, v40
	v_exp_f32_e32 v55, v55
	v_add_f32_e32 v53, 1.0, v53
	v_mul_f32_e32 v76, 0xbfb8aa3b, v45
	v_exp_f32_e32 v77, v76
	v_rcp_f32_e32 v76, v53
	v_add_f32_e32 v53, 1.0, v55
	v_mul_f32_e32 v55, 0xbfb8aa3b, v46
	v_exp_f32_e32 v55, v55
	v_mul_f32_e32 v79, 0xbfb8aa3b, v42
	v_exp_f32_e32 v79, v79
	v_lshlrev_b32_e32 v60, 16, v84
	v_add_f32_e32 v55, 1.0, v55
	v_and_b32_e32 v61, 0xffff0000, v84
	v_rcp_f32_e32 v78, v53
	v_add_f32_e32 v53, 1.0, v77
	v_rcp_f32_e32 v84, v55
	v_add_f32_e32 v55, 1.0, v79
	v_mul_f32_e32 v79, 0xbfb8aa3b, v47
	v_lshlrev_b32_e32 v62, 16, v85
	v_and_b32_e32 v63, 0xffff0000, v85
	v_rcp_f32_e32 v77, v53
	v_mul_f32_e32 v53, 0xbfb8aa3b, v41
	v_exp_f32_e32 v79, v79
	v_mul_f32_e32 v85, 0xbfb8aa3b, v43
	v_lshlrev_b32_e32 v74, 16, v87
	v_and_b32_e32 v75, 0xffff0000, v87
	v_exp_f32_e32 v53, v53
	v_exp_f32_e32 v87, v85
	v_lshlrev_b32_e32 v72, 16, v86
	v_and_b32_e32 v73, 0xffff0000, v86
	v_rcp_f32_e32 v86, v55
	v_add_f32_e32 v55, 1.0, v79
	v_add_f32_e32 v53, 1.0, v53
	v_rcp_f32_e32 v85, v55
	v_add_f32_e32 v55, 1.0, v87
	v_rcp_f32_e32 v87, v55
	v_rcp_f32_e32 v79, v53
	v_fmamk_f32 v52, v52, 0x3b000000, v198
	v_rsq_f32_e32 v52, v52
	v_pk_mul_f32 v[46:47], v[46:47], v[84:85]
	v_pk_mul_f32 v[44:45], v[44:45], v[76:77]
	v_pk_mul_f32 v[42:43], v[42:43], v[86:87]
	v_pk_mul_f32 v[40:41], v[40:41], v[78:79]
	v_pk_mul_f32 v[44:45], v[44:45], v[60:61]
	v_pk_mul_f32 v[46:47], v[46:47], v[62:63]
	v_pk_mul_f32 v[40:41], v[40:41], v[72:73]
	v_pk_mul_f32 v[42:43], v[42:43], v[74:75]
	v_pk_mul_f32 v[46:47], v[66:67], v[46:47]
	v_pk_mul_f32 v[44:45], v[64:65], v[44:45]
	v_pk_mul_f32 v[42:43], v[70:71], v[42:43]
	v_pk_mul_f32 v[40:41], v[68:69], v[40:41]
	v_pk_mul_f32 v[36:37], v[36:37], v[54:55] op_sel_hi:[1,0]
	v_pk_mul_f32 v[46:47], v[52:53], v[46:47] op_sel_hi:[0,1]
	v_pk_mul_f32 v[44:45], v[52:53], v[44:45] op_sel_hi:[0,1]
	v_pk_mul_f32 v[60:61], v[52:53], v[42:43] op_sel_hi:[0,1]
	v_pk_mul_f32 v[42:43], v[52:53], v[40:41] op_sel_hi:[0,1]
	v_mul_f32_e32 v53, 0xbfb8aa3b, v36
	v_pk_mul_f32 v[32:33], v[32:33], v[54:55] op_sel_hi:[1,0]
	v_exp_f32_e32 v53, v53
	v_pk_mul_f32 v[38:39], v[38:39], v[54:55] op_sel_hi:[1,0]
	v_pk_mul_f32 v[34:35], v[34:35], v[54:55] op_sel_hi:[1,0]
	v_mul_f32_e32 v54, 0xbfb8aa3b, v32
	v_exp_f32_e32 v55, v54
	v_mul_f32_e32 v54, 0xbfb8aa3b, v37
	v_exp_f32_e32 v79, v54
	v_add_f32_e32 v53, 1.0, v53
	v_rcp_f32_e32 v54, v53
	v_add_f32_e32 v53, 1.0, v55
	v_rcp_f32_e32 v78, v53
	v_add_f32_e32 v53, 1.0, v79
	v_mul_f32_e32 v79, 0xbfb8aa3b, v38
	v_cvt_pk_bf16_f32 v41, v46, v47
	v_lshlrev_b32_e32 v46, 16, v80
	v_and_b32_e32 v47, 0xffff0000, v80
	v_exp_f32_e32 v79, v79
	v_mul_f32_e32 v80, 0xbfb8aa3b, v34
	v_lshlrev_b32_e32 v72, 16, v81
	v_and_b32_e32 v73, 0xffff0000, v81
	v_exp_f32_e32 v81, v80
	v_add_f32_e32 v79, 1.0, v79
	v_rcp_f32_e32 v80, v79
	v_lshlrev_b32_e32 v74, 16, v82
	v_add_f32_e32 v79, 1.0, v81
	v_mul_f32_e32 v81, 0xbfb8aa3b, v39
	v_and_b32_e32 v75, 0xffff0000, v82
	v_rcp_f32_e32 v55, v53
	v_mul_f32_e32 v53, 0xbfb8aa3b, v33
	v_exp_f32_e32 v81, v81
	v_mul_f32_e32 v82, 0xbfb8aa3b, v35
	v_lshlrev_b32_e32 v76, 16, v83
	v_and_b32_e32 v77, 0xffff0000, v83
	v_exp_f32_e32 v53, v53
	v_exp_f32_e32 v83, v82
	v_rcp_f32_e32 v82, v79
	v_add_f32_e32 v79, 1.0, v81
	v_add_f32_e32 v53, 1.0, v53
	v_rcp_f32_e32 v81, v79
	v_add_f32_e32 v79, 1.0, v83
	v_rcp_f32_e32 v83, v79
	v_rcp_f32_e32 v79, v53
	v_cvt_pk_bf16_f32 v40, v44, v45
	v_lshl_add_u64 v[44:45], s[36:37], 0, v[92:93]
	v_pk_mul_f32 v[38:39], v[38:39], v[80:81]
	v_pk_mul_f32 v[36:37], v[36:37], v[54:55]
	v_pk_mul_f32 v[34:35], v[34:35], v[82:83]
	v_pk_mul_f32 v[32:33], v[32:33], v[78:79]
	v_cvt_pk_bf16_f32 v42, v42, v43
	v_cvt_pk_bf16_f32 v43, v60, v61
	v_lshl_add_u64 v[44:45], v[44:45], 0, v[184:185]
	v_pk_mul_f32 v[36:37], v[36:37], v[46:47]
	v_pk_mul_f32 v[38:39], v[38:39], v[72:73]
	v_pk_mul_f32 v[32:33], v[32:33], v[74:75]
	v_pk_mul_f32 v[34:35], v[34:35], v[76:77]
	flat_store_dwordx4 v[44:45], v[40:43]
	v_pk_mul_f32 v[38:39], v[58:59], v[38:39]
	v_pk_mul_f32 v[36:37], v[56:57], v[36:37]
	v_add_u32_e32 v40, 0xa0, v186
	v_pk_mul_f32 v[34:35], v[50:51], v[34:35]
	v_pk_mul_f32 v[32:33], v[48:49], v[32:33]
	v_ashrrev_i32_e32 v41, 31, v40
	v_pk_mul_f32 v[38:39], v[52:53], v[38:39] op_sel_hi:[0,1]
	v_pk_mul_f32 v[36:37], v[52:53], v[36:37] op_sel_hi:[0,1]
	v_pk_mul_f32 v[46:47], v[52:53], v[34:35] op_sel_hi:[0,1]
	v_pk_mul_f32 v[34:35], v[52:53], v[32:33] op_sel_hi:[0,1]
	v_lshlrev_b64 v[100:101], 12, v[40:41]
	v_cvt_pk_bf16_f32 v32, v36, v37
	v_cvt_pk_bf16_f32 v33, v38, v39
	v_cvt_pk_bf16_f32 v34, v34, v35
	v_cvt_pk_bf16_f32 v35, v46, v47
	v_lshl_add_u64 v[42:43], v[190:191], 0, v[100:101]
	flat_store_dwordx4 v[44:45], v[32:35] offset:256
	s_waitcnt vmcnt(4) lgkmcnt(0)
; __device__ __forceinline__ u32x4 pack8(f32x4 a, f32x4 b) { u32x4 w; w.x = pk2(a[0], a[1]); w.y = pk2(a[2], a[3]); w.z = pk2(b[0], b[1]); w.w = pk2(b[2], b[3]); return w; }
;     __device__ __forceinline__ void operator()(const Acc& acc, const pg8::Unit& u, int wid) const {
;     ...
;                 for (int mm = 0; mm < 2; ++mm) { const int m = 2 * mp + mm, row = row0 + ai * 128 + m * 16;
;                     const float sc = __builtin_amdgcn_rsqf(scv[mm] * (1.f / 1024.f) + EPS);
;                     const f32x4 pa = (rq[mm][0] + rq[mm][1]) + (rq[mm][2] + rq[mm][3]);
;                     const float rg = __builtin_amdgcn_rsqf(((pa[0] + pa[1]) + (pa[2] + pa[3])) * (1.f / 512.f) + EPS);
; #pragma unroll
;                     for (int bj = 0; bj < 2; ++bj) {
;                         const u32x4 w = ov[mm][bj];
;                         f32x4 o0 = (f32x4){bflo(w.x), bfhi(w.x), bflo(w.y), bfhi(w.y)}, o1 = (f32x4){bflo(w.z), bfhi(w.z), bflo(w.w), bfhi(w.w)};
;                         f32x4 a0 = acc[ai][bj][m][0] * sc, a1 = acc[ai][bj][m][1] * sc;
; #pragma unroll
;                         for (int e = 0; e < 4; ++e) { a0[e] = a0[e] * __builtin_amdgcn_rcpf(1.f + __builtin_amdgcn_exp2f(-1.4426950408889634f * a0[e])); a1[e] = a1[e] * __builtin_amdgcn_rcpf(1.f + __builtin_amdgcn_exp2f(-1.4426950408889634f * a1[e])); }
;                         o0 = a0 * o0 * g4[bj][0] * rg; o1 = a1 * o1 * g4[bj][1] * rg;
;                         *(u32x4*)(Y + (size_t)row * 2048 + col0 + bj * 128) = pack8(o0, o1);
;                     } }
	v_fmamk_f32 v192, v192, 0x3a800000, v198
	v_rsq_f32_e32 v192, v192
	v_pk_add_f32 v[158:159], v[158:159], v[162:163]
	v_pk_add_f32 v[156:157], v[156:157], v[160:161]
	v_pk_add_f32 v[160:161], v[166:167], v[202:203]
	v_pk_add_f32 v[162:163], v[164:165], v[200:201]
	v_pk_add_f32 v[158:159], v[158:159], v[160:161]
	v_pk_add_f32 v[156:157], v[156:157], v[162:163]
	s_nop 0
	v_pk_mov_b32 v[160:161], v[156:157], v[158:159] op_sel:[1,0]
	v_mov_b32_e32 v157, v159
	v_pk_add_f32 v[156:157], v[160:161], v[156:157]
	v_lshlrev_b32_e32 v158, 16, v152
	v_add_f32_e32 v193, v156, v157
	v_fmamk_f32 v193, v193, 0x3b000000, v198
	v_pk_mul_f32 v[28:29], v[28:29], v[192:193] op_sel_hi:[1,0]
	v_rsq_f32_e32 v156, v193
	v_mul_f32_e32 v193, 0xbfb8aa3b, v28
	v_exp_f32_e32 v193, v193
	v_mul_f32_e32 v162, 0xbfb8aa3b, v29
	v_exp_f32_e32 v163, v162
	v_and_b32_e32 v159, 0xffff0000, v152
	v_pk_mul_f32 v[24:25], v[24:25], v[192:193] op_sel_hi:[1,0]
	v_pk_mul_f32 v[30:31], v[30:31], v[192:193] op_sel_hi:[1,0]
	v_mul_f32_e32 v157, 0xbfb8aa3b, v24
	v_exp_f32_e32 v157, v157
	v_pk_mul_f32 v[26:27], v[26:27], v[192:193] op_sel_hi:[1,0]
	v_add_f32_e32 v193, 1.0, v193
	v_rcp_f32_e32 v162, v193
	v_add_f32_e32 v193, 1.0, v157
	v_mul_f32_e32 v157, 0xbfb8aa3b, v30
	v_exp_f32_e32 v157, v157
	v_mul_f32_e32 v165, 0xbfb8aa3b, v26
	v_exp_f32_e32 v165, v165
	v_rcp_f32_e32 v164, v193
	v_add_f32_e32 v157, 1.0, v157
	v_add_f32_e32 v193, 1.0, v163
	v_rcp_f32_e32 v166, v157
	v_add_f32_e32 v157, 1.0, v165
	v_mul_f32_e32 v165, 0xbfb8aa3b, v31
	v_rcp_f32_e32 v163, v193
	v_mul_f32_e32 v193, 0xbfb8aa3b, v25
	v_exp_f32_e32 v165, v165
	v_mul_f32_e32 v167, 0xbfb8aa3b, v27
	v_exp_f32_e32 v193, v193
	v_exp_f32_e32 v201, v167
	v_rcp_f32_e32 v200, v157
	v_add_f32_e32 v157, 1.0, v165
	v_add_f32_e32 v193, 1.0, v193
	v_rcp_f32_e32 v167, v157
	v_add_f32_e32 v157, 1.0, v201
	v_rcp_f32_e32 v201, v157
	v_rcp_f32_e32 v165, v193
	v_pk_mul_f32 v[20:21], v[20:21], v[192:193] op_sel_hi:[1,0]
	v_lshlrev_b32_e32 v152, 16, v153
	v_mul_f32_e32 v193, 0xbfb8aa3b, v20
	v_exp_f32_e32 v193, v193
	v_and_b32_e32 v153, 0xffff0000, v153
	v_lshlrev_b32_e32 v160, 16, v154
	v_and_b32_e32 v161, 0xffff0000, v154
	v_lshlrev_b32_e32 v154, 16, v155
	v_and_b32_e32 v155, 0xffff0000, v155
	v_pk_mul_f32 v[30:31], v[30:31], v[166:167]
	v_pk_mul_f32 v[28:29], v[28:29], v[162:163]
	v_pk_mul_f32 v[26:27], v[26:27], v[200:201]
	v_pk_mul_f32 v[24:25], v[24:25], v[164:165]
	v_pk_mul_f32 v[28:29], v[28:29], v[158:159]
	v_pk_mul_f32 v[30:31], v[30:31], v[152:153]
	v_pk_mul_f32 v[24:25], v[24:25], v[160:161]
	v_pk_mul_f32 v[26:27], v[26:27], v[154:155]
	v_pk_mul_f32 v[30:31], v[66:67], v[30:31]
	v_pk_mul_f32 v[28:29], v[64:65], v[28:29]
	v_pk_mul_f32 v[26:27], v[70:71], v[26:27]
	v_pk_mul_f32 v[24:25], v[68:69], v[24:25]
	v_pk_mul_f32 v[22:23], v[22:23], v[192:193] op_sel_hi:[1,0]
	v_pk_mul_f32 v[30:31], v[156:157], v[30:31] op_sel_hi:[0,1]
	v_pk_mul_f32 v[28:29], v[156:157], v[28:29] op_sel_hi:[0,1]
	v_pk_mul_f32 v[152:153], v[156:157], v[26:27] op_sel_hi:[0,1]
	v_pk_mul_f32 v[26:27], v[156:157], v[24:25] op_sel_hi:[0,1]
	v_pk_mul_f32 v[18:19], v[18:19], v[192:193] op_sel_hi:[1,0]
	v_pk_mul_f32 v[16:17], v[16:17], v[192:193] op_sel_hi:[1,0]
	v_mul_f32_e32 v157, 0xbfb8aa3b, v22
	v_add_f32_e32 v192, 1.0, v193
	v_mul_f32_e32 v193, 0xbfb8aa3b, v16
	v_exp_f32_e32 v157, v157
	v_mul_f32_e32 v158, 0xbfb8aa3b, v18
	v_exp_f32_e32 v193, v193
	v_mul_f32_e32 v154, 0xbfb8aa3b, v21
	v_exp_f32_e32 v159, v158
	v_exp_f32_e32 v155, v154
	v_add_f32_e32 v157, 1.0, v157
	v_add_f32_e32 v193, 1.0, v193
	v_rcp_f32_e32 v158, v157
	v_add_f32_e32 v157, 1.0, v159
	v_mul_f32_e32 v159, 0xbfb8aa3b, v23
	v_rcp_f32_e32 v154, v193
	v_add_f32_e32 v193, 1.0, v155
	v_mul_f32_e32 v155, 0xbfb8aa3b, v17
	v_exp_f32_e32 v159, v159
	v_mul_f32_e32 v160, 0xbfb8aa3b, v19
	v_exp_f32_e32 v155, v155
	v_exp_f32_e32 v161, v160
	v_rcp_f32_e32 v160, v157
	v_add_f32_e32 v157, 1.0, v159
	v_add_f32_e32 v155, 1.0, v155
	v_rcp_f32_e32 v159, v157
	v_add_f32_e32 v157, 1.0, v161
	v_rcp_f32_e32 v192, v192
	v_rcp_f32_e32 v193, v193
	v_rcp_f32_e32 v161, v157
	v_rcp_f32_e32 v155, v155
	v_cvt_pk_bf16_f32 v24, v28, v29
	v_lshl_add_u64 v[28:29], s[36:37], 0, v[216:217]
	v_cvt_pk_bf16_f32 v25, v30, v31
	v_cvt_pk_bf16_f32 v26, v26, v27
	v_cvt_pk_bf16_f32 v27, v152, v153
	v_lshl_add_u64 v[28:29], v[28:29], 0, v[184:185]
	flat_store_dwordx4 v[28:29], v[24:27]
	v_lshlrev_b32_e32 v30, 16, v206
	v_and_b32_e32 v31, 0xffff0000, v206
	v_lshlrev_b32_e32 v24, 16, v204
	v_and_b32_e32 v25, 0xffff0000, v204
	v_lshlrev_b32_e32 v26, 16, v205
	v_and_b32_e32 v27, 0xffff0000, v205
	v_lshlrev_b32_e32 v152, 16, v207
	v_and_b32_e32 v153, 0xffff0000, v207
	v_pk_mul_f32 v[22:23], v[22:23], v[158:159]
	v_pk_mul_f32 v[20:21], v[20:21], v[192:193]
	v_pk_mul_f32 v[18:19], v[18:19], v[160:161]
	v_pk_mul_f32 v[16:17], v[16:17], v[154:155]
	v_pk_mul_f32 v[20:21], v[20:21], v[24:25]
	v_pk_mul_f32 v[22:23], v[22:23], v[26:27]
	v_pk_mul_f32 v[16:17], v[16:17], v[30:31]
	v_pk_mul_f32 v[18:19], v[18:19], v[152:153]
	v_pk_mul_f32 v[22:23], v[58:59], v[22:23]
	v_pk_mul_f32 v[20:21], v[56:57], v[20:21]
	v_pk_mul_f32 v[18:19], v[50:51], v[18:19]
	v_pk_mul_f32 v[16:17], v[48:49], v[16:17]
	v_pk_mul_f32 v[22:23], v[156:157], v[22:23] op_sel_hi:[0,1]
	v_pk_mul_f32 v[20:21], v[156:157], v[20:21] op_sel_hi:[0,1]
	v_pk_mul_f32 v[24:25], v[156:157], v[18:19] op_sel_hi:[0,1]
	v_pk_mul_f32 v[18:19], v[156:157], v[16:17] op_sel_hi:[0,1]
	v_cvt_pk_bf16_f32 v16, v20, v21
; __device__ __forceinline__ u32x4 pack8(f32x4 a, f32x4 b) { u32x4 w; w.x = pk2(a[0], a[1]); w.y = pk2(a[2], a[3]); w.z = pk2(b[0], b[1]); w.w = pk2(b[2], b[3]); return w; }
;     __device__ __forceinline__ void operator()(const Acc& acc, const pg8::Unit& u, int wid) const {
;     ...
;                 for (int mm = 0; mm < 2; ++mm) { const int m = 2 * mp + mm, row = row0 + ai * 128 + m * 16;
;                     const float sc = __builtin_amdgcn_rsqf(scv[mm] * (1.f / 1024.f) + EPS);
;                     const f32x4 pa = (rq[mm][0] + rq[mm][1]) + (rq[mm][2] + rq[mm][3]);
;                     const float rg = __builtin_amdgcn_rsqf(((pa[0] + pa[1]) + (pa[2] + pa[3])) * (1.f / 512.f) + EPS);
; #pragma unroll
;                     for (int bj = 0; bj < 2; ++bj) {
;                         const u32x4 w = ov[mm][bj];
;                         f32x4 o0 = (f32x4){bflo(w.x), bfhi(w.x), bflo(w.y), bfhi(w.y)}, o1 = (f32x4){bflo(w.z), bfhi(w.z), bflo(w.w), bfhi(w.w)};
;                         f32x4 a0 = acc[ai][bj][m][0] * sc, a1 = acc[ai][bj][m][1] * sc;
; #pragma unroll
;                         for (int e = 0; e < 4; ++e) { a0[e] = a0[e] * __builtin_amdgcn_rcpf(1.f + __builtin_amdgcn_exp2f(-1.4426950408889634f * a0[e])); a1[e] = a1[e] * __builtin_amdgcn_rcpf(1.f + __builtin_amdgcn_exp2f(-1.4426950408889634f * a1[e])); }
;                         o0 = a0 * o0 * g4[bj][0] * rg; o1 = a1 * o1 * g4[bj][1] * rg;
;                         *(u32x4*)(Y + (size_t)row * 2048 + col0 + bj * 128) = pack8(o0, o1);
;                     } }
	v_cvt_pk_bf16_f32 v17, v22, v23
	v_cvt_pk_bf16_f32 v18, v18, v19
	v_cvt_pk_bf16_f32 v19, v24, v25
	flat_store_dwordx4 v[28:29], v[16:19] offset:256
	v_pk_add_f32 v[20:21], v[208:209], v[212:213]
	v_pk_add_f32 v[22:23], v[146:147], v[150:151]
	v_pk_add_f32 v[18:19], v[210:211], v[214:215]
	v_pk_add_f32 v[24:25], v[144:145], v[148:149]
	v_fmamk_f32 v16, v187, 0x3a800000, v198
	v_pk_add_f32 v[18:19], v[18:19], v[22:23]
	v_pk_add_f32 v[20:21], v[20:21], v[24:25]
	v_rsq_f32_e32 v16, v16
	v_pk_mov_b32 v[22:23], v[20:21], v[18:19] op_sel:[1,0]
	v_mov_b32_e32 v21, v19
	v_pk_add_f32 v[18:19], v[22:23], v[20:21]
	v_lshlrev_b32_e32 v20, 16, v140
	v_add_f32_e32 v17, v18, v19
	v_fmamk_f32 v17, v17, 0x3b000000, v198
	v_pk_mul_f32 v[12:13], v[12:13], v[16:17] op_sel_hi:[1,0]
	v_rsq_f32_e32 v18, v17
	v_mul_f32_e32 v17, 0xbfb8aa3b, v12
	v_exp_f32_e32 v17, v17
	v_mul_f32_e32 v28, 0xbfb8aa3b, v13
	v_exp_f32_e32 v29, v28
	v_and_b32_e32 v21, 0xffff0000, v140
	v_pk_mul_f32 v[8:9], v[8:9], v[16:17] op_sel_hi:[1,0]
	v_pk_mul_f32 v[14:15], v[14:15], v[16:17] op_sel_hi:[1,0]
	v_mul_f32_e32 v19, 0xbfb8aa3b, v8
	v_exp_f32_e32 v19, v19
	v_pk_mul_f32 v[10:11], v[10:11], v[16:17] op_sel_hi:[1,0]
	v_add_f32_e32 v17, 1.0, v17
	v_rcp_f32_e32 v28, v17
	v_add_f32_e32 v17, 1.0, v19
	v_mul_f32_e32 v19, 0xbfb8aa3b, v14
	v_exp_f32_e32 v19, v19
	v_mul_f32_e32 v31, 0xbfb8aa3b, v10
	v_exp_f32_e32 v31, v31
	v_rcp_f32_e32 v30, v17
	v_add_f32_e32 v17, 1.0, v29
	v_rcp_f32_e32 v29, v17
	v_mul_f32_e32 v17, 0xbfb8aa3b, v9
	v_add_f32_e32 v19, 1.0, v19
	v_exp_f32_e32 v17, v17
	v_rcp_f32_e32 v140, v19
	v_add_f32_e32 v19, 1.0, v31
	v_mul_f32_e32 v31, 0xbfb8aa3b, v15
	v_lshlrev_b32_e32 v22, 16, v141
	v_and_b32_e32 v23, 0xffff0000, v141
	v_exp_f32_e32 v31, v31
	v_mul_f32_e32 v141, 0xbfb8aa3b, v11
	v_lshlrev_b32_e32 v26, 16, v143
	v_and_b32_e32 v27, 0xffff0000, v143
	v_exp_f32_e32 v143, v141
	v_add_f32_e32 v17, 1.0, v17
	v_lshlrev_b32_e32 v24, 16, v142
	v_and_b32_e32 v25, 0xffff0000, v142
	v_rcp_f32_e32 v142, v19
	v_add_f32_e32 v19, 1.0, v31
	v_pk_mul_f32 v[4:5], v[4:5], v[16:17] op_sel_hi:[1,0]
	v_rcp_f32_e32 v141, v19
	v_add_f32_e32 v19, 1.0, v143
	v_rcp_f32_e32 v31, v17
	v_mul_f32_e32 v17, 0xbfb8aa3b, v4
	v_rcp_f32_e32 v143, v19
	v_exp_f32_e32 v17, v17
	v_pk_mul_f32 v[14:15], v[14:15], v[140:141]
	v_pk_mul_f32 v[12:13], v[12:13], v[28:29]
	v_pk_mul_f32 v[10:11], v[10:11], v[142:143]
	v_pk_mul_f32 v[8:9], v[8:9], v[30:31]
	v_pk_mul_f32 v[6:7], v[6:7], v[16:17] op_sel_hi:[1,0]
	v_pk_mul_f32 v[12:13], v[12:13], v[20:21]
	v_pk_mul_f32 v[14:15], v[14:15], v[22:23]
	v_pk_mul_f32 v[8:9], v[8:9], v[24:25]
	v_pk_mul_f32 v[10:11], v[10:11], v[26:27]
	v_pk_mul_f32 v[2:3], v[2:3], v[16:17] op_sel_hi:[1,0]
	v_pk_mul_f32 v[0:1], v[0:1], v[16:17] op_sel_hi:[1,0]
	v_mul_f32_e32 v23, 0xbfb8aa3b, v6
	v_pk_mul_f32 v[14:15], v[66:67], v[14:15]
	v_pk_mul_f32 v[12:13], v[64:65], v[12:13]
	v_pk_mul_f32 v[10:11], v[70:71], v[10:11]
	v_pk_mul_f32 v[8:9], v[68:69], v[8:9]
	v_add_f32_e32 v16, 1.0, v17
	v_mul_f32_e32 v17, 0xbfb8aa3b, v0
	v_exp_f32_e32 v23, v23
	v_mul_f32_e32 v24, 0xbfb8aa3b, v2
	v_pk_mul_f32 v[14:15], v[18:19], v[14:15] op_sel_hi:[0,1]
	v_pk_mul_f32 v[12:13], v[18:19], v[12:13] op_sel_hi:[0,1]
	v_pk_mul_f32 v[20:21], v[18:19], v[10:11] op_sel_hi:[0,1]
	v_pk_mul_f32 v[10:11], v[18:19], v[8:9] op_sel_hi:[0,1]
	v_exp_f32_e32 v17, v17
	v_mul_f32_e32 v19, 0xbfb8aa3b, v5
	v_exp_f32_e32 v25, v24
	v_exp_f32_e32 v19, v19
	v_add_f32_e32 v23, 1.0, v23
	v_add_f32_e32 v17, 1.0, v17
	v_rcp_f32_e32 v24, v23
	v_add_f32_e32 v23, 1.0, v25
	v_mul_f32_e32 v25, 0xbfb8aa3b, v7
	v_rcp_f32_e32 v22, v17
	v_add_f32_e32 v17, 1.0, v19
	v_mul_f32_e32 v19, 0xbfb8aa3b, v1
	v_exp_f32_e32 v25, v25
	v_mul_f32_e32 v26, 0xbfb8aa3b, v3
	v_exp_f32_e32 v19, v19
	v_exp_f32_e32 v27, v26
	v_rcp_f32_e32 v26, v23
	v_add_f32_e32 v23, 1.0, v25
	v_add_f32_e32 v19, 1.0, v19
	v_rcp_f32_e32 v25, v23
	v_add_f32_e32 v23, 1.0, v27
	v_rcp_f32_e32 v16, v16
	v_rcp_f32_e32 v17, v17
	v_rcp_f32_e32 v27, v23
	v_rcp_f32_e32 v23, v19
	v_cvt_pk_bf16_f32 v8, v12, v13
	v_lshl_add_u64 v[12:13], s[36:37], 0, v[134:135]
	v_cvt_pk_bf16_f32 v9, v14, v15
	v_cvt_pk_bf16_f32 v10, v10, v11
	v_cvt_pk_bf16_f32 v11, v20, v21
	v_lshl_add_u64 v[12:13], v[12:13], 0, v[184:185]
	flat_store_dwordx4 v[12:13], v[8:11]
	v_lshlrev_b32_e32 v14, 16, v138
	v_and_b32_e32 v15, 0xffff0000, v138
	v_lshlrev_b32_e32 v8, 16, v136
	v_and_b32_e32 v9, 0xffff0000, v136
	v_lshlrev_b32_e32 v10, 16, v137
	v_and_b32_e32 v11, 0xffff0000, v137
	v_lshlrev_b32_e32 v20, 16, v139
	v_and_b32_e32 v21, 0xffff0000, v139
	v_pk_mul_f32 v[6:7], v[6:7], v[24:25]
	v_pk_mul_f32 v[4:5], v[4:5], v[16:17]
	v_pk_mul_f32 v[2:3], v[2:3], v[26:27]
	v_pk_mul_f32 v[0:1], v[0:1], v[22:23]
	v_pk_mul_f32 v[4:5], v[4:5], v[8:9]
	v_pk_mul_f32 v[6:7], v[6:7], v[10:11]
	v_pk_mul_f32 v[0:1], v[0:1], v[14:15]
	v_pk_mul_f32 v[2:3], v[2:3], v[20:21]
	v_pk_mul_f32 v[6:7], v[58:59], v[6:7]
	v_pk_mul_f32 v[4:5], v[56:57], v[4:5]
	v_pk_mul_f32 v[2:3], v[50:51], v[2:3]
	v_pk_mul_f32 v[0:1], v[48:49], v[0:1]
	v_pk_mul_f32 v[6:7], v[18:19], v[6:7] op_sel_hi:[0,1]
	v_pk_mul_f32 v[4:5], v[18:19], v[4:5] op_sel_hi:[0,1]
	v_pk_mul_f32 v[8:9], v[18:19], v[2:3] op_sel_hi:[0,1]
	v_pk_mul_f32 v[2:3], v[18:19], v[0:1] op_sel_hi:[0,1]
	v_cvt_pk_bf16_f32 v0, v4, v5
	v_cvt_pk_bf16_f32 v1, v6, v7
	v_cvt_pk_bf16_f32 v2, v2, v3
	v_cvt_pk_bf16_f32 v3, v8, v9
	flat_store_dwordx4 v[12:13], v[0:3] offset:256
	s_cbranch_vccnz .LBB0_323

; #define PG8_BAR __builtin_amdgcn_s_barrier()
; template <class Epi>
; __device__ __forceinline__ void gemm_phase(LAS unsigned char* lds, const Gemm g, const StaticOrder& S, const Epi& E, const int wid) {
;     ...
;         cur = nxt; cA = nA; cB = nB; ++ui;
;         if (wr == 1) PG8_BAR;
	s_andn2_b64 vcc, exec, s[4:5]
	s_cbranch_vccnz .LBB0_322
	s_barrier
	s_branch .LBB0_322

; __device__ __forceinline__ u32x4 pack8(f32x4 a, f32x4 b) { u32x4 w; w.x = pk2(a[0], a[1]); w.y = pk2(a[2], a[3]); w.z = pk2(b[0], b[1]); w.w = pk2(b[2], b[3]); return w; }
;     __device__ __forceinline__ void operator()(const Acc& acc, const pg8::Unit& u, int wid) const {
;     ...
; #pragma unroll
;         for (int ai = 0; ai < 2; ++ai)
; #pragma unroll
;             for (int mp = 0; mp < 2; ++mp) {
;                 u32x4 hv[2][2], pw[2][2]; float scv[2];
; #pragma unroll
;                 for (int mm = 0; mm < 2; ++mm) {
;                     const int row = row0 + ai * 128 + (2 * mp + mm) * 16;
;                     scv[mm] = ssq[row];
; #pragma unroll
;                     for (int bj = 0; bj < 2; ++bj) { const size_t off = (size_t)row * 1024 + col0 + bj * 128; hv[mm][bj] = *(const u32x4*)(hbase + off); pw[mm][bj] = *(const u32x4*)(pp + off); }
;                 }
; #pragma unroll
;                 for (int mm = 0; mm < 2; ++mm) {
;                     const int m = 2 * mp + mm, row = row0 + ai * 128 + m * 16; float sq = 0.f;
;                     const float sc = __builtin_amdgcn_rsqf(scv[mm] * (1.f / 1024.f) + EPS);
; #pragma unroll
;                     for (int bj = 0; bj < 2; ++bj) {
;                         const size_t off = (size_t)row * 1024 + col0 + bj * 128;
;                         const u32x4 pwv = pw[mm][bj], hw = hv[mm][bj];
;                         const f32x4 p0 = (f32x4){bflo(pwv.x), bfhi(pwv.x), bflo(pwv.y), bfhi(pwv.y)}, p1 = (f32x4){bflo(pwv.z), bfhi(pwv.z), bflo(pwv.w), bfhi(pwv.w)};
;                         f32x4 g0 = acc[ai][bj][m][0] * sc, g1 = acc[ai][bj][m][1] * sc;
; #pragma unroll
;                         for (int e = 0; e < 4; ++e) { g0[e] = __builtin_amdgcn_rcpf(1.f + __builtin_amdgcn_exp2f(-1.4426950408889634f * g0[e])); g1[e] = __builtin_amdgcn_rcpf(1.f + __builtin_amdgcn_exp2f(-1.4426950408889634f * g1[e])); }
;                         const f32x4 o0 = (f32x4){bflo(hw.x), bfhi(hw.x), bflo(hw.y), bfhi(hw.y)} + g0 * p0;
;                         const f32x4 o1 = (f32x4){bflo(hw.z), bfhi(hw.z), bflo(hw.w), bfhi(hw.w)} + g1 * p1;
;                         if (fout) { *(f32x4*)(fout + off) = o0; *(f32x4*)(fout + off + 4) = o1; }
;                         if (hb_out) *(u32x4*)(hb_out + off) = pack8(o0, o1);
.LBB0_668:
	s_lshl_b32 s4, s10, 8
	s_add_i32 s4, s4, s67
	v_mbcnt_lo_u32_b32 v188, -1, 0
	v_mbcnt_hi_u32_b32 v188, -1, v188
	v_cndmask_b32_e64 v181, 0, 1, s[40:41]
	v_and_or_b32 v172, v188, 15, s4
	v_ashrrev_i32_e32 v173, 31, v172
	v_lshl_add_u64 v[170:171], v[172:173], 2, s[60:61]
	flat_load_dword v180, v[170:171]
	s_lshl_b32 s4, s8, 8
	v_ashrrev_i32_e32 v128, 1, v188
	s_or_b32 s4, s4, s69
	v_and_b32_e32 v128, -8, v128
	v_add_u32_e32 v168, s4, v128
	v_or_b32_e32 v174, 16, v172
	v_ashrrev_i32_e32 v169, 31, v168
	v_lshlrev_b64 v[128:129], 10, v[172:173]
	v_ashrrev_i32_e32 v175, 31, v174
	v_lshl_add_u64 v[178:179], v[128:129], 0, v[168:169]
	v_lshlrev_b64 v[134:135], 10, v[174:175]
	v_lshlrev_b64 v[128:129], 1, v[178:179]
	v_lshl_add_u64 v[176:177], v[134:135], 0, v[168:169]
	v_lshl_add_u64 v[130:131], s[48:49], 0, v[128:129]
	v_lshl_add_u64 v[128:129], s[42:43], 0, v[128:129]
	v_lshl_add_u64 v[132:133], v[174:175], 2, s[60:61]
	v_lshlrev_b64 v[134:135], 1, v[176:177]
	flat_load_dwordx4 v[190:193], v[130:131]
	flat_load_dwordx4 v[194:197], v[128:129]
	flat_load_dwordx4 v[144:147], v[128:129] offset:256
	flat_load_dwordx4 v[148:151], v[130:131] offset:256
	flat_load_dword v189, v[132:133]
	v_lshl_add_u64 v[128:129], s[42:43], 0, v[134:135]
	v_lshl_add_u64 v[132:133], s[48:49], 0, v[134:135]
	flat_load_dwordx4 v[136:139], v[128:129]
	s_nop 0
	flat_load_dwordx4 v[128:131], v[128:129] offset:256
	s_nop 0
	flat_load_dwordx4 v[140:143], v[132:133]
	s_nop 0
	flat_load_dwordx4 v[132:135], v[132:133] offset:256
	v_cmp_ne_u32_e64 s[8:9], 1, v181
	s_andn2_b64 vcc, exec, s[40:41]
	v_lshl_add_u64 v[178:179], v[178:179], 1, s[52:53]
	s_waitcnt vmcnt(0) lgkmcnt(0)
	v_or_b32_e32 v248, 32, v172
	v_ashrrev_i32_e32 v249, 31, v248
	s_waitcnt lgkmcnt(0)
	v_lshl_add_u64 v[212:213], v[248:249], 2, s[60:61]
	global_load_dword v252, v[212:213], off
	v_or_b32_e32 v210, 48, v172
	v_ashrrev_i32_e32 v211, 31, v210
	v_lshlrev_b64 v[212:213], 10, v[248:249]
	v_lshlrev_b64 v[218:219], 10, v[210:211]
	v_lshl_add_u64 v[250:251], v[212:213], 0, v[168:169]
	v_lshl_add_u64 v[246:247], v[218:219], 0, v[168:169]
	v_lshlrev_b64 v[212:213], 1, v[250:251]
	v_lshlrev_b64 v[218:219], 1, v[246:247]
	v_lshl_add_u64 v[214:215], s[48:49], 0, v[212:213]
	v_lshl_add_u64 v[212:213], s[42:43], 0, v[212:213]
	v_lshl_add_u64 v[216:217], v[210:211], 2, s[60:61]
	v_lshl_add_u64 v[224:225], s[42:43], 0, v[218:219]
	v_lshl_add_u64 v[218:219], s[48:49], 0, v[218:219]
	global_load_dwordx4 v[236:239], v[214:215], off
	global_load_dwordx4 v[240:243], v[212:213], off
	global_load_dwordx4 v[228:231], v[212:213], off offset:256
	global_load_dwordx4 v[232:235], v[214:215], off offset:256
	global_load_dword v209, v[216:217], off
	global_load_dwordx4 v[220:223], v[224:225], off
	s_nop 0
	global_load_dwordx4 v[212:215], v[224:225], off offset:256
	s_nop 0
	global_load_dwordx4 v[224:227], v[218:219], off
	s_nop 0
	global_load_dwordx4 v[216:219], v[218:219], off offset:256
	v_fmamk_f32 v180, v180, 0x3a800000, v186
	v_rsq_f32_e32 v180, v180
	v_lshlrev_b32_e32 v198, 16, v190
	v_pk_mul_f32 v[126:127], v[126:127], v[180:181] op_sel_hi:[1,0]
	v_pk_mul_f32 v[124:125], v[124:125], v[180:181] op_sel_hi:[1,0]
	v_pk_mul_f32 v[122:123], v[122:123], v[180:181] op_sel_hi:[1,0]
	v_pk_mul_f32 v[120:121], v[120:121], v[180:181] op_sel_hi:[1,0]
	v_mul_f32_e32 v124, 0xbfb8aa3b, v124
	v_mul_f32_e32 v120, 0xbfb8aa3b, v120
	v_mul_f32_e32 v125, 0xbfb8aa3b, v125
	v_mul_f32_e32 v121, 0xbfb8aa3b, v121
	v_mul_f32_e32 v126, 0xbfb8aa3b, v126
	v_mul_f32_e32 v122, 0xbfb8aa3b, v122
	v_mul_f32_e32 v127, 0xbfb8aa3b, v127
	v_mul_f32_e32 v123, 0xbfb8aa3b, v123
	v_exp_f32_e32 v124, v124
	v_exp_f32_e32 v120, v120
	v_exp_f32_e32 v125, v125
	v_exp_f32_e32 v121, v121
	v_exp_f32_e32 v126, v126
	v_exp_f32_e32 v122, v122
	v_exp_f32_e32 v127, v127
	v_exp_f32_e32 v123, v123
	v_add_f32_e32 v124, 1.0, v124
	v_add_f32_e32 v181, 1.0, v120
	v_add_f32_e32 v125, 1.0, v125
	v_add_f32_e32 v208, 1.0, v121
	v_add_f32_e32 v126, 1.0, v126
	v_add_f32_e32 v206, 1.0, v122
	v_add_f32_e32 v127, 1.0, v127
	v_add_f32_e32 v123, 1.0, v123
	v_rcp_f32_e32 v120, v124
	v_rcp_f32_e32 v122, v181
	v_rcp_f32_e32 v121, v125
	v_rcp_f32_e32 v124, v126
	v_rcp_f32_e32 v125, v127
	v_rcp_f32_e32 v206, v206
	v_rcp_f32_e32 v207, v123
	v_rcp_f32_e32 v123, v208
	v_and_b32_e32 v199, 0xffff0000, v190
	v_lshlrev_b32_e32 v190, 16, v191
	v_and_b32_e32 v191, 0xffff0000, v191
	v_lshlrev_b32_e32 v200, 16, v192
	v_and_b32_e32 v201, 0xffff0000, v192
	v_lshlrev_b32_e32 v192, 16, v193
	v_and_b32_e32 v193, 0xffff0000, v193
	v_lshlrev_b32_e32 v202, 16, v194
	v_and_b32_e32 v203, 0xffff0000, v194
	v_lshlrev_b32_e32 v194, 16, v195
	v_and_b32_e32 v195, 0xffff0000, v195
	v_lshlrev_b32_e32 v204, 16, v196
	v_and_b32_e32 v205, 0xffff0000, v196
	v_lshlrev_b32_e32 v196, 16, v197
	v_and_b32_e32 v197, 0xffff0000, v197
	v_pk_fma_f32 v[124:125], v[124:125], v[190:191], v[194:195]
	v_pk_fma_f32 v[126:127], v[120:121], v[198:199], v[202:203]
	v_pk_fma_f32 v[120:121], v[206:207], v[192:193], v[196:197]
	v_pk_fma_f32 v[122:123], v[122:123], v[200:201], v[204:205]
	s_cbranch_vccnz .LBB0_670
	v_cvt_pk_bf16_f32 v190, v126, v127
	v_cvt_pk_bf16_f32 v191, v124, v125
	v_cvt_pk_bf16_f32 v192, v122, v123
	v_cvt_pk_bf16_f32 v193, v120, v121
	global_store_dwordx4 v[178:179], v[190:193], off

; __device__ __forceinline__ u32x4 pack8(f32x4 a, f32x4 b) { u32x4 w; w.x = pk2(a[0], a[1]); w.y = pk2(a[2], a[3]); w.z = pk2(b[0], b[1]); w.w = pk2(b[2], b[3]); return w; }
;     __device__ __forceinline__ void operator()(const Acc& acc, const pg8::Unit& u, int wid) const {
;     ...
;                 for (int mm = 0; mm < 2; ++mm) {
;                     const int m = 2 * mp + mm, row = row0 + ai * 128 + m * 16; float sq = 0.f;
;                     const float sc = __builtin_amdgcn_rsqf(scv[mm] * (1.f / 1024.f) + EPS);
; #pragma unroll
;                     for (int bj = 0; bj < 2; ++bj) {
;                         const size_t off = (size_t)row * 1024 + col0 + bj * 128;
;                         const u32x4 pwv = pw[mm][bj], hw = hv[mm][bj];
;                         const f32x4 p0 = (f32x4){bflo(pwv.x), bfhi(pwv.x), bflo(pwv.y), bfhi(pwv.y)}, p1 = (f32x4){bflo(pwv.z), bfhi(pwv.z), bflo(pwv.w), bfhi(pwv.w)};
;                         f32x4 g0 = acc[ai][bj][m][0] * sc, g1 = acc[ai][bj][m][1] * sc;
; #pragma unroll
;                         for (int e = 0; e < 4; ++e) { g0[e] = __builtin_amdgcn_rcpf(1.f + __builtin_amdgcn_exp2f(-1.4426950408889634f * g0[e])); g1[e] = __builtin_amdgcn_rcpf(1.f + __builtin_amdgcn_exp2f(-1.4426950408889634f * g1[e])); }
;                         const f32x4 o0 = (f32x4){bflo(hw.x), bfhi(hw.x), bflo(hw.y), bfhi(hw.y)} + g0 * p0;
;                         const f32x4 o1 = (f32x4){bflo(hw.z), bfhi(hw.z), bflo(hw.w), bfhi(hw.w)} + g1 * p1;
;                         if (fout) { *(f32x4*)(fout + off) = o0; *(f32x4*)(fout + off + 4) = o1; }
;                         if (hb_out) *(u32x4*)(hb_out + off) = pack8(o0, o1);
.LBB0_680:
	s_or_b64 exec, exec, s[28:29]
	s_and_b64 vcc, exec, s[8:9]
	v_lshl_add_u64 v[250:251], v[250:251], 1, s[52:53]
	s_waitcnt vmcnt(4) lgkmcnt(0)
	global_load_dword v180, v[170:171], off offset:512
	v_add_u32_e32 v174, 0x80, v172
	v_add_u32_e32 v118, 0x90, v172
	v_ashrrev_i32_e32 v175, 31, v174
	v_ashrrev_i32_e32 v119, 31, v118
	s_waitcnt lgkmcnt(0)
	v_lshlrev_b64 v[120:121], 10, v[174:175]
	v_lshlrev_b64 v[124:125], 10, v[118:119]
	v_lshl_add_u64 v[200:201], v[120:121], 0, v[168:169]
	v_lshl_add_u64 v[128:129], v[124:125], 0, v[168:169]
	v_lshlrev_b64 v[120:121], 1, v[200:201]
	v_lshlrev_b64 v[124:125], 1, v[128:129]
	v_lshl_add_u64 v[122:123], s[48:49], 0, v[120:121]
	v_lshl_add_u64 v[120:121], s[42:43], 0, v[120:121]
	v_lshl_add_u64 v[126:127], s[42:43], 0, v[124:125]
	v_lshl_add_u64 v[124:125], s[48:49], 0, v[124:125]
	global_load_dwordx4 v[192:195], v[122:123], off
	global_load_dwordx4 v[196:199], v[120:121], off
	global_load_dwordx4 v[176:179], v[120:121], off offset:256
	global_load_dword v117, v[170:171], off offset:576
	global_load_dwordx4 v[188:191], v[122:123], off offset:256
	global_load_dwordx4 v[132:135], v[126:127], off
	global_load_dwordx4 v[136:139], v[124:125], off
	s_nop 0
	global_load_dwordx4 v[120:123], v[126:127], off offset:256
	s_nop 0
	global_load_dwordx4 v[124:127], v[124:125], off offset:256
	v_fmamk_f32 v252, v252, 0x3a800000, v186
	v_rsq_f32_e32 v252, v252
	v_lshlrev_b32_e32 v140, 16, v236
	v_pk_mul_f32 v[94:95], v[94:95], v[252:253] op_sel_hi:[1,0]
	v_pk_mul_f32 v[92:93], v[92:93], v[252:253] op_sel_hi:[1,0]
	v_pk_mul_f32 v[90:91], v[90:91], v[252:253] op_sel_hi:[1,0]
	v_pk_mul_f32 v[88:89], v[88:89], v[252:253] op_sel_hi:[1,0]
	v_mul_f32_e32 v92, 0xbfb8aa3b, v92
	v_mul_f32_e32 v88, 0xbfb8aa3b, v88
	v_mul_f32_e32 v93, 0xbfb8aa3b, v93
	v_mul_f32_e32 v89, 0xbfb8aa3b, v89
	v_mul_f32_e32 v94, 0xbfb8aa3b, v94
	v_mul_f32_e32 v90, 0xbfb8aa3b, v90
	v_mul_f32_e32 v95, 0xbfb8aa3b, v95
	v_mul_f32_e32 v91, 0xbfb8aa3b, v91
	v_exp_f32_e32 v92, v92
	v_exp_f32_e32 v88, v88
	v_exp_f32_e32 v93, v93
	v_exp_f32_e32 v89, v89
	v_exp_f32_e32 v94, v94
	v_exp_f32_e32 v90, v90
	v_exp_f32_e32 v95, v95
	v_exp_f32_e32 v91, v91
	v_add_f32_e32 v92, 1.0, v92
	v_add_f32_e32 v253, 1.0, v88
	v_add_f32_e32 v93, 1.0, v93
	v_add_f32_e32 v131, 1.0, v89
	v_add_f32_e32 v94, 1.0, v94
	v_add_f32_e32 v150, 1.0, v90
	v_add_f32_e32 v95, 1.0, v95
	v_add_f32_e32 v91, 1.0, v91
	v_rcp_f32_e32 v88, v92
	v_rcp_f32_e32 v90, v253
	v_rcp_f32_e32 v89, v93
	v_rcp_f32_e32 v92, v94
	v_rcp_f32_e32 v93, v95
	v_rcp_f32_e32 v150, v150
	v_rcp_f32_e32 v151, v91
	v_rcp_f32_e32 v91, v131
	v_and_b32_e32 v141, 0xffff0000, v236
	v_lshlrev_b32_e32 v236, 16, v237
	v_and_b32_e32 v237, 0xffff0000, v237
	v_lshlrev_b32_e32 v142, 16, v238
	v_and_b32_e32 v143, 0xffff0000, v238
	v_lshlrev_b32_e32 v238, 16, v239
	v_and_b32_e32 v239, 0xffff0000, v239
	v_lshlrev_b32_e32 v146, 16, v240
	v_and_b32_e32 v147, 0xffff0000, v240
	v_lshlrev_b32_e32 v240, 16, v241
	v_and_b32_e32 v241, 0xffff0000, v241
	v_lshlrev_b32_e32 v148, 16, v242
	v_and_b32_e32 v149, 0xffff0000, v242
	v_lshlrev_b32_e32 v242, 16, v243
	v_and_b32_e32 v243, 0xffff0000, v243
	v_pk_fma_f32 v[92:93], v[92:93], v[236:237], v[240:241]
	v_pk_fma_f32 v[94:95], v[88:89], v[140:141], v[146:147]
	v_pk_fma_f32 v[88:89], v[150:151], v[238:239], v[242:243]
	v_pk_fma_f32 v[90:91], v[90:91], v[142:143], v[148:149]
	s_cbranch_vccnz .LBB0_682

; __device__ __forceinline__ u32x4 pack8(f32x4 a, f32x4 b) { u32x4 w; w.x = pk2(a[0], a[1]); w.y = pk2(a[2], a[3]); w.z = pk2(b[0], b[1]); w.w = pk2(b[2], b[3]); return w; }
;     __device__ __forceinline__ void operator()(const Acc& acc, const pg8::Unit& u, int wid) const {
;     ...
;                     for (int bj = 0; bj < 2; ++bj) {
;                         const size_t off = (size_t)row * 1024 + col0 + bj * 128;
;                         const u32x4 pwv = pw[mm][bj], hw = hv[mm][bj];
;                         const f32x4 p0 = (f32x4){bflo(pwv.x), bfhi(pwv.x), bflo(pwv.y), bfhi(pwv.y)}, p1 = (f32x4){bflo(pwv.z), bfhi(pwv.z), bflo(pwv.w), bfhi(pwv.w)};
;                         f32x4 g0 = acc[ai][bj][m][0] * sc, g1 = acc[ai][bj][m][1] * sc;
; #pragma unroll
;                         for (int e = 0; e < 4; ++e) { g0[e] = __builtin_amdgcn_rcpf(1.f + __builtin_amdgcn_exp2f(-1.4426950408889634f * g0[e])); g1[e] = __builtin_amdgcn_rcpf(1.f + __builtin_amdgcn_exp2f(-1.4426950408889634f * g1[e])); }
;                         const f32x4 o0 = (f32x4){bflo(hw.x), bfhi(hw.x), bflo(hw.y), bfhi(hw.y)} + g0 * p0;
;                         const f32x4 o1 = (f32x4){bflo(hw.z), bfhi(hw.z), bflo(hw.w), bfhi(hw.w)} + g1 * p1;
;                         if (fout) { *(f32x4*)(fout + off) = o0; *(f32x4*)(fout + off + 4) = o1; }
;                         if (hb_out) *(u32x4*)(hb_out + off) = pack8(o0, o1);
	v_cvt_pk_bf16_f32 v236, v94, v95
	v_cvt_pk_bf16_f32 v237, v92, v93
	v_cvt_pk_bf16_f32 v238, v90, v91
	v_cvt_pk_bf16_f32 v239, v88, v89
	global_store_dwordx4 v[250:251], v[236:239], off
.LBB0_682:
	v_mov_b32_e32 v253, v252
	v_pk_mul_f32 v[84:85], v[84:85], v[252:253]
	v_pk_mul_f32 v[80:81], v[80:81], v[252:253]
	v_mul_f32_e32 v84, 0xbfb8aa3b, v84
	v_mul_f32_e32 v80, 0xbfb8aa3b, v80
	v_mov_b32_e32 v240, v252
	v_mov_b32_e32 v241, v252
	v_exp_f32_e32 v84, v84
	v_exp_f32_e32 v252, v80
	v_mul_f32_e32 v85, 0xbfb8aa3b, v85
	v_mul_f32_e32 v81, 0xbfb8aa3b, v81
	v_add_f32_e32 v80, 1.0, v84
	v_add_f32_e32 v84, 1.0, v252
	v_exp_f32_e32 v85, v85
	v_exp_f32_e32 v252, v81
	v_pk_mul_f32 v[86:87], v[86:87], v[240:241]
	v_pk_mul_f32 v[82:83], v[82:83], v[240:241]
	v_mul_f32_e32 v86, 0xbfb8aa3b, v86
	v_mul_f32_e32 v82, 0xbfb8aa3b, v82
	v_add_f32_e32 v81, 1.0, v85
	v_add_f32_e32 v85, 1.0, v252
	v_exp_f32_e32 v86, v86
	v_exp_f32_e32 v252, v82
	v_mul_f32_e32 v87, 0xbfb8aa3b, v87
	v_exp_f32_e32 v87, v87
	v_mul_f32_e32 v83, 0xbfb8aa3b, v83
	v_add_f32_e32 v82, 1.0, v86
	v_add_f32_e32 v86, 1.0, v252
	v_exp_f32_e32 v252, v83
	v_add_f32_e32 v83, 1.0, v87
	v_rcp_f32_e32 v82, v82
	v_rcp_f32_e32 v83, v83
	v_add_f32_e32 v87, 1.0, v252
	v_rcp_f32_e32 v80, v80
	v_rcp_f32_e32 v84, v84
	v_rcp_f32_e32 v81, v81
	v_rcp_f32_e32 v85, v85
	v_rcp_f32_e32 v86, v86
	v_rcp_f32_e32 v87, v87
	v_lshlrev_b32_e32 v236, 16, v232
	v_and_b32_e32 v237, 0xffff0000, v232
	v_lshlrev_b32_e32 v232, 16, v233
	v_and_b32_e32 v233, 0xffff0000, v233
	v_lshlrev_b32_e32 v252, 16, v228
	v_and_b32_e32 v253, 0xffff0000, v228
	v_lshlrev_b32_e32 v228, 16, v229
	v_and_b32_e32 v229, 0xffff0000, v229
	v_lshlrev_b32_e32 v238, 16, v234
	v_and_b32_e32 v239, 0xffff0000, v234
	v_lshlrev_b32_e32 v234, 16, v235
	v_and_b32_e32 v235, 0xffff0000, v235
	v_pk_fma_f32 v[82:83], v[82:83], v[232:233], v[228:229]
	v_lshlrev_b32_e32 v228, 16, v230
	v_and_b32_e32 v229, 0xffff0000, v230
	v_lshlrev_b32_e32 v230, 16, v231
	v_and_b32_e32 v231, 0xffff0000, v231
	v_pk_fma_f32 v[80:81], v[80:81], v[236:237], v[252:253]
	v_pk_fma_f32 v[84:85], v[84:85], v[238:239], v[228:229]
	s_and_b64 vcc, exec, s[8:9]
	v_pk_fma_f32 v[86:87], v[86:87], v[234:235], v[230:231]
	s_cbranch_vccnz .LBB0_684

; __device__ __forceinline__ u32x4 pack8(f32x4 a, f32x4 b) { u32x4 w; w.x = pk2(a[0], a[1]); w.y = pk2(a[2], a[3]); w.z = pk2(b[0], b[1]); w.w = pk2(b[2], b[3]); return w; }
;     __device__ __forceinline__ void operator()(const Acc& acc, const pg8::Unit& u, int wid) const {
;     ...
;                     for (int bj = 0; bj < 2; ++bj) {
;                         const size_t off = (size_t)row * 1024 + col0 + bj * 128;
;                         const u32x4 pwv = pw[mm][bj], hw = hv[mm][bj];
;                         const f32x4 p0 = (f32x4){bflo(pwv.x), bfhi(pwv.x), bflo(pwv.y), bfhi(pwv.y)}, p1 = (f32x4){bflo(pwv.z), bfhi(pwv.z), bflo(pwv.w), bfhi(pwv.w)};
;                         f32x4 g0 = acc[ai][bj][m][0] * sc, g1 = acc[ai][bj][m][1] * sc;
; #pragma unroll
;                         for (int e = 0; e < 4; ++e) { g0[e] = __builtin_amdgcn_rcpf(1.f + __builtin_amdgcn_exp2f(-1.4426950408889634f * g0[e])); g1[e] = __builtin_amdgcn_rcpf(1.f + __builtin_amdgcn_exp2f(-1.4426950408889634f * g1[e])); }
;                         const f32x4 o0 = (f32x4){bflo(hw.x), bfhi(hw.x), bflo(hw.y), bfhi(hw.y)} + g0 * p0;
;                         const f32x4 o1 = (f32x4){bflo(hw.z), bfhi(hw.z), bflo(hw.w), bfhi(hw.w)} + g1 * p1;
;                         if (fout) { *(f32x4*)(fout + off) = o0; *(f32x4*)(fout + off + 4) = o1; }
;                         if (hb_out) *(u32x4*)(hb_out + off) = pack8(o0, o1);
;                         sq += (o0[0] * o0[0] + o0[1] * o0[1]) + (o0[2] * o0[2] + o0[3] * o0[3]) + (o1[0] * o1[0] + o1[1] * o1[1]) + (o1[2] * o1[2] + o1[3] * o1[3]);
;                     }
;                     if (ssq_out) { sq += __shfl_xor(sq, 16); sq += __shfl_xor(sq, 32); if (fq == 0) atomicAdd(ssq_out + row, sq); }
	v_cvt_pk_bf16_f32 v228, v80, v81
	v_cvt_pk_bf16_f32 v229, v82, v83
	v_cvt_pk_bf16_f32 v230, v84, v85
	v_cvt_pk_bf16_f32 v231, v86, v87
	global_store_dwordx4 v[250:251], v[228:231], off offset:256
.LBB0_684:
	v_mul_f32_e32 v81, v81, v81
	v_fmac_f32_e32 v81, v80, v80
	v_mul_f32_e32 v80, v83, v83
	v_mul_f32_e32 v95, v95, v95
	v_mul_f32_e32 v93, v93, v93
	v_fmac_f32_e32 v80, v82, v82
	v_fmac_f32_e32 v95, v94, v94
	v_fmac_f32_e32 v93, v92, v92
	v_mul_f32_e32 v91, v91, v91
	v_add_f32_e32 v80, v81, v80
	v_mul_f32_e32 v81, v85, v85
	v_add_f32_e32 v92, v95, v93
	v_fmac_f32_e32 v91, v90, v90
	v_mul_f32_e32 v89, v89, v89
	v_mul_f32_e32 v87, v87, v87
	v_fmac_f32_e32 v81, v84, v84
	v_add_f32_e32 v90, v91, v92
	v_fmac_f32_e32 v89, v88, v88
	v_fmac_f32_e32 v87, v86, v86
	v_add_f32_e32 v80, v81, v80
	v_add_f32_e32 v88, v89, v90
	v_add_f32_e32 v80, v87, v80
	v_add_f32_e32 v80, v88, v80
	ds_bpermute_b32 v81, v144, v80
	s_waitcnt lgkmcnt(0)
	v_add_f32_e32 v80, v80, v81
	ds_bpermute_b32 v81, v145, v80
	s_and_saveexec_b64 s[28:29], s[10:11]
	s_cbranch_execz .LBB0_686

; __device__ __forceinline__ u32x4 pack8(f32x4 a, f32x4 b) { u32x4 w; w.x = pk2(a[0], a[1]); w.y = pk2(a[2], a[3]); w.z = pk2(b[0], b[1]); w.w = pk2(b[2], b[3]); return w; }
;     __device__ __forceinline__ void operator()(const Acc& acc, const pg8::Unit& u, int wid) const {
;     ...
;                 for (int mm = 0; mm < 2; ++mm) {
;                     const int m = 2 * mp + mm, row = row0 + ai * 128 + m * 16; float sq = 0.f;
;                     const float sc = __builtin_amdgcn_rsqf(scv[mm] * (1.f / 1024.f) + EPS);
; #pragma unroll
;                     for (int bj = 0; bj < 2; ++bj) {
;                         const size_t off = (size_t)row * 1024 + col0 + bj * 128;
;                         const u32x4 pwv = pw[mm][bj], hw = hv[mm][bj];
;                         const f32x4 p0 = (f32x4){bflo(pwv.x), bfhi(pwv.x), bflo(pwv.y), bfhi(pwv.y)}, p1 = (f32x4){bflo(pwv.z), bfhi(pwv.z), bflo(pwv.w), bfhi(pwv.w)};
;                         f32x4 g0 = acc[ai][bj][m][0] * sc, g1 = acc[ai][bj][m][1] * sc;
; #pragma unroll
;                         for (int e = 0; e < 4; ++e) { g0[e] = __builtin_amdgcn_rcpf(1.f + __builtin_amdgcn_exp2f(-1.4426950408889634f * g0[e])); g1[e] = __builtin_amdgcn_rcpf(1.f + __builtin_amdgcn_exp2f(-1.4426950408889634f * g1[e])); }
;                         const f32x4 o0 = (f32x4){bflo(hw.x), bfhi(hw.x), bflo(hw.y), bfhi(hw.y)} + g0 * p0;
;                         const f32x4 o1 = (f32x4){bflo(hw.z), bfhi(hw.z), bflo(hw.w), bfhi(hw.w)} + g1 * p1;
;                         if (fout) { *(f32x4*)(fout + off) = o0; *(f32x4*)(fout + off + 4) = o1; }
;                         if (hb_out) *(u32x4*)(hb_out + off) = pack8(o0, o1);
;                         sq += (o0[0] * o0[0] + o0[1] * o0[1]) + (o0[2] * o0[2] + o0[3] * o0[3]) + (o1[0] * o1[0] + o1[1] * o1[1]) + (o1[2] * o1[2] + o1[3] * o1[3]);
;                     }
;                     if (ssq_out) { sq += __shfl_xor(sq, 16); sq += __shfl_xor(sq, 32); if (fq == 0) atomicAdd(ssq_out + row, sq); }
	v_lshl_add_u64 v[82:83], v[248:249], 2, s[58:59]
	s_waitcnt lgkmcnt(0)
	v_add_f32_e32 v80, v80, v81
	flat_atomic_add_f32 v[82:83], v80
.LBB0_686:
	s_or_b64 exec, exec, s[28:29]
	v_fmamk_f32 v80, v209, 0x3a800000, v186
	v_rsq_f32_e32 v80, v80
	v_lshlrev_b32_e32 v82, 16, v224
	v_and_b32_e32 v83, 0xffff0000, v224
	v_lshlrev_b32_e32 v84, 16, v225
	s_waitcnt lgkmcnt(0)
	v_pk_mul_f32 v[72:73], v[72:73], v[80:81] op_sel_hi:[1,0]
	v_pk_mul_f32 v[76:77], v[76:77], v[80:81] op_sel_hi:[1,0]
	v_mul_f32_e32 v72, 0xbfb8aa3b, v72
	v_exp_f32_e32 v72, v72
	v_mul_f32_e32 v77, 0xbfb8aa3b, v77
	v_exp_f32_e32 v77, v77
	v_mul_f32_e32 v73, 0xbfb8aa3b, v73
	v_exp_f32_e32 v73, v73
	v_add_f32_e32 v72, 1.0, v72
	v_pk_mul_f32 v[78:79], v[78:79], v[80:81] op_sel_hi:[1,0]
	v_pk_mul_f32 v[74:75], v[74:75], v[80:81] op_sel_hi:[1,0]
	v_rcp_f32_e32 v90, v72
	v_add_f32_e32 v72, 1.0, v77
	v_rcp_f32_e32 v77, v72
	v_add_f32_e32 v72, 1.0, v73
	v_mul_f32_e32 v73, 0xbfb8aa3b, v78
	v_mul_f32_e32 v74, 0xbfb8aa3b, v74
	v_exp_f32_e32 v73, v73
	v_exp_f32_e32 v74, v74
	v_mul_f32_e32 v76, 0xbfb8aa3b, v76
	v_exp_f32_e32 v76, v76
	v_rcp_f32_e32 v91, v72
	v_add_f32_e32 v72, 1.0, v73
	v_add_f32_e32 v73, 1.0, v74
	v_mul_f32_e32 v74, 0xbfb8aa3b, v79
	v_mul_f32_e32 v75, 0xbfb8aa3b, v75
	v_exp_f32_e32 v74, v74
	v_exp_f32_e32 v75, v75
	v_add_f32_e32 v76, 1.0, v76
	v_rcp_f32_e32 v76, v76
	v_rcp_f32_e32 v78, v73
	v_add_f32_e32 v73, 1.0, v74
	v_add_f32_e32 v74, 1.0, v75
	v_rcp_f32_e32 v72, v72
	v_rcp_f32_e32 v73, v73
	v_rcp_f32_e32 v79, v74
	v_lshlrev_b32_e32 v74, 16, v220
	v_and_b32_e32 v75, 0xffff0000, v220
	v_and_b32_e32 v85, 0xffff0000, v225
	v_lshlrev_b32_e32 v86, 16, v226
	v_and_b32_e32 v87, 0xffff0000, v226
	v_lshlrev_b32_e32 v88, 16, v227
	v_and_b32_e32 v89, 0xffff0000, v227
	v_lshlrev_b32_e32 v92, 16, v221
	v_and_b32_e32 v93, 0xffff0000, v221
	v_pk_fma_f32 v[74:75], v[76:77], v[82:83], v[74:75]
	v_lshlrev_b32_e32 v82, 16, v222
	v_and_b32_e32 v83, 0xffff0000, v222
	v_lshlrev_b32_e32 v76, 16, v223
	v_and_b32_e32 v77, 0xffff0000, v223
	v_pk_fma_f32 v[72:73], v[72:73], v[84:85], v[92:93]
	v_pk_fma_f32 v[76:77], v[78:79], v[88:89], v[76:77]
	v_pk_fma_f32 v[78:79], v[90:91], v[86:87], v[82:83]
	s_and_b64 vcc, exec, s[8:9]
	v_lshl_add_u64 v[82:83], v[246:247], 1, s[52:53]
	s_cbranch_vccnz .LBB0_688

; __device__ __forceinline__ u32x4 pack8(f32x4 a, f32x4 b) { u32x4 w; w.x = pk2(a[0], a[1]); w.y = pk2(a[2], a[3]); w.z = pk2(b[0], b[1]); w.w = pk2(b[2], b[3]); return w; }
;     __device__ __forceinline__ void operator()(const Acc& acc, const pg8::Unit& u, int wid) const {
;     ...
;                     for (int bj = 0; bj < 2; ++bj) {
;                         const size_t off = (size_t)row * 1024 + col0 + bj * 128;
;                         const u32x4 pwv = pw[mm][bj], hw = hv[mm][bj];
;                         const f32x4 p0 = (f32x4){bflo(pwv.x), bfhi(pwv.x), bflo(pwv.y), bfhi(pwv.y)}, p1 = (f32x4){bflo(pwv.z), bfhi(pwv.z), bflo(pwv.w), bfhi(pwv.w)};
;                         f32x4 g0 = acc[ai][bj][m][0] * sc, g1 = acc[ai][bj][m][1] * sc;
; #pragma unroll
;                         for (int e = 0; e < 4; ++e) { g0[e] = __builtin_amdgcn_rcpf(1.f + __builtin_amdgcn_exp2f(-1.4426950408889634f * g0[e])); g1[e] = __builtin_amdgcn_rcpf(1.f + __builtin_amdgcn_exp2f(-1.4426950408889634f * g1[e])); }
;                         const f32x4 o0 = (f32x4){bflo(hw.x), bfhi(hw.x), bflo(hw.y), bfhi(hw.y)} + g0 * p0;
;                         const f32x4 o1 = (f32x4){bflo(hw.z), bfhi(hw.z), bflo(hw.w), bfhi(hw.w)} + g1 * p1;
;                         if (fout) { *(f32x4*)(fout + off) = o0; *(f32x4*)(fout + off + 4) = o1; }
;                         if (hb_out) *(u32x4*)(hb_out + off) = pack8(o0, o1);
	v_cvt_pk_bf16_f32 v84, v74, v75
	v_cvt_pk_bf16_f32 v85, v72, v73
	v_cvt_pk_bf16_f32 v86, v78, v79
	v_cvt_pk_bf16_f32 v87, v76, v77
	global_store_dwordx4 v[82:83], v[84:87], off
.LBB0_688:
	v_mov_b32_e32 v81, v80
	v_pk_mul_f32 v[68:69], v[68:69], v[80:81]
	v_pk_mul_f32 v[64:65], v[64:65], v[80:81]
	v_mul_f32_e32 v68, 0xbfb8aa3b, v68
	v_mul_f32_e32 v64, 0xbfb8aa3b, v64
	v_mov_b32_e32 v92, v80
	v_mov_b32_e32 v93, v80
	v_exp_f32_e32 v68, v68
	v_exp_f32_e32 v80, v64
	v_mul_f32_e32 v69, 0xbfb8aa3b, v69
	v_mul_f32_e32 v65, 0xbfb8aa3b, v65
	v_add_f32_e32 v64, 1.0, v68
	v_add_f32_e32 v68, 1.0, v80
	v_exp_f32_e32 v69, v69
	v_exp_f32_e32 v80, v65
	v_pk_mul_f32 v[70:71], v[70:71], v[92:93]
	v_pk_mul_f32 v[66:67], v[66:67], v[92:93]
	v_mul_f32_e32 v70, 0xbfb8aa3b, v70
	v_mul_f32_e32 v66, 0xbfb8aa3b, v66
	v_add_f32_e32 v65, 1.0, v69
	v_add_f32_e32 v69, 1.0, v80
	v_exp_f32_e32 v70, v70
	v_exp_f32_e32 v80, v66
	v_mul_f32_e32 v71, 0xbfb8aa3b, v71
	v_mul_f32_e32 v67, 0xbfb8aa3b, v67
	v_add_f32_e32 v66, 1.0, v70
	v_add_f32_e32 v70, 1.0, v80
	v_exp_f32_e32 v71, v71
	v_exp_f32_e32 v80, v67
	v_rcp_f32_e32 v64, v64
	v_rcp_f32_e32 v65, v65
	v_add_f32_e32 v67, 1.0, v71
	v_add_f32_e32 v71, 1.0, v80
	v_rcp_f32_e32 v68, v68
	v_rcp_f32_e32 v69, v69
	v_rcp_f32_e32 v66, v66
	v_rcp_f32_e32 v70, v70
	v_rcp_f32_e32 v67, v67
	v_rcp_f32_e32 v71, v71
	v_lshlrev_b32_e32 v84, 16, v216
	v_and_b32_e32 v85, 0xffff0000, v216
	v_lshlrev_b32_e32 v80, 16, v212
	v_and_b32_e32 v81, 0xffff0000, v212
	v_lshlrev_b32_e32 v86, 16, v217
	v_and_b32_e32 v87, 0xffff0000, v217
	v_lshlrev_b32_e32 v88, 16, v218
	v_and_b32_e32 v89, 0xffff0000, v218
	v_lshlrev_b32_e32 v90, 16, v219
	v_and_b32_e32 v91, 0xffff0000, v219
	v_lshlrev_b32_e32 v92, 16, v213
	v_and_b32_e32 v93, 0xffff0000, v213
	v_pk_fma_f32 v[64:65], v[64:65], v[84:85], v[80:81]
	v_lshlrev_b32_e32 v80, 16, v214
	v_and_b32_e32 v81, 0xffff0000, v214
	v_lshlrev_b32_e32 v84, 16, v215
	v_and_b32_e32 v85, 0xffff0000, v215
	v_pk_fma_f32 v[66:67], v[66:67], v[86:87], v[92:93]
	v_pk_fma_f32 v[68:69], v[68:69], v[88:89], v[80:81]
	s_and_b64 vcc, exec, s[8:9]
	v_pk_fma_f32 v[70:71], v[70:71], v[90:91], v[84:85]
	s_cbranch_vccnz .LBB0_690

; __device__ __forceinline__ u32x4 pack8(f32x4 a, f32x4 b) { u32x4 w; w.x = pk2(a[0], a[1]); w.y = pk2(a[2], a[3]); w.z = pk2(b[0], b[1]); w.w = pk2(b[2], b[3]); return w; }
;     __device__ __forceinline__ void operator()(const Acc& acc, const pg8::Unit& u, int wid) const {
;     ...
;                     for (int bj = 0; bj < 2; ++bj) {
;                         const size_t off = (size_t)row * 1024 + col0 + bj * 128;
;                         const u32x4 pwv = pw[mm][bj], hw = hv[mm][bj];
;                         const f32x4 p0 = (f32x4){bflo(pwv.x), bfhi(pwv.x), bflo(pwv.y), bfhi(pwv.y)}, p1 = (f32x4){bflo(pwv.z), bfhi(pwv.z), bflo(pwv.w), bfhi(pwv.w)};
;                         f32x4 g0 = acc[ai][bj][m][0] * sc, g1 = acc[ai][bj][m][1] * sc;
; #pragma unroll
;                         for (int e = 0; e < 4; ++e) { g0[e] = __builtin_amdgcn_rcpf(1.f + __builtin_amdgcn_exp2f(-1.4426950408889634f * g0[e])); g1[e] = __builtin_amdgcn_rcpf(1.f + __builtin_amdgcn_exp2f(-1.4426950408889634f * g1[e])); }
;                         const f32x4 o0 = (f32x4){bflo(hw.x), bfhi(hw.x), bflo(hw.y), bfhi(hw.y)} + g0 * p0;
;                         const f32x4 o1 = (f32x4){bflo(hw.z), bfhi(hw.z), bflo(hw.w), bfhi(hw.w)} + g1 * p1;
;                         if (fout) { *(f32x4*)(fout + off) = o0; *(f32x4*)(fout + off + 4) = o1; }
;                         if (hb_out) *(u32x4*)(hb_out + off) = pack8(o0, o1);
;                         sq += (o0[0] * o0[0] + o0[1] * o0[1]) + (o0[2] * o0[2] + o0[3] * o0[3]) + (o1[0] * o1[0] + o1[1] * o1[1]) + (o1[2] * o1[2] + o1[3] * o1[3]);
;                     }
;                     if (ssq_out) { sq += __shfl_xor(sq, 16); sq += __shfl_xor(sq, 32); if (fq == 0) atomicAdd(ssq_out + row, sq); }
	v_cvt_pk_bf16_f32 v84, v64, v65
	v_cvt_pk_bf16_f32 v85, v66, v67
	v_cvt_pk_bf16_f32 v86, v68, v69
	v_cvt_pk_bf16_f32 v87, v70, v71
	global_store_dwordx4 v[82:83], v[84:87], off offset:256
.LBB0_690:
	v_mul_f32_e32 v75, v75, v75
	v_mul_f32_e32 v73, v73, v73
	v_mul_f32_e32 v65, v65, v65
	v_fmac_f32_e32 v75, v74, v74
	v_fmac_f32_e32 v73, v72, v72
	v_fmac_f32_e32 v65, v64, v64
	v_mul_f32_e32 v64, v67, v67
	v_add_f32_e32 v72, v75, v73
	v_mul_f32_e32 v73, v79, v79
	v_fmac_f32_e32 v64, v66, v66
	v_fmac_f32_e32 v73, v78, v78
	v_add_f32_e32 v64, v65, v64
	v_mul_f32_e32 v65, v69, v69
	v_add_f32_e32 v72, v73, v72
	v_mul_f32_e32 v73, v77, v77
	v_mul_f32_e32 v71, v71, v71
	v_fmac_f32_e32 v65, v68, v68
	v_fmac_f32_e32 v73, v76, v76
	v_fmac_f32_e32 v71, v70, v70
	v_add_f32_e32 v64, v65, v64
	v_add_f32_e32 v72, v73, v72
	v_add_f32_e32 v64, v71, v64
	v_add_f32_e32 v64, v72, v64
	ds_bpermute_b32 v65, v144, v64
	s_waitcnt lgkmcnt(0)
	v_add_f32_e32 v64, v64, v65
	ds_bpermute_b32 v65, v145, v64
	s_and_saveexec_b64 s[28:29], s[10:11]
	s_cbranch_execz .LBB0_692

; __device__ __forceinline__ u32x4 pack8(f32x4 a, f32x4 b) { u32x4 w; w.x = pk2(a[0], a[1]); w.y = pk2(a[2], a[3]); w.z = pk2(b[0], b[1]); w.w = pk2(b[2], b[3]); return w; }
;     __device__ __forceinline__ void operator()(const Acc& acc, const pg8::Unit& u, int wid) const {
;     ...
;             for (int mp = 0; mp < 2; ++mp) {
;                 u32x4 hv[2][2], pw[2][2]; float scv[2];
; #pragma unroll
;                 for (int mm = 0; mm < 2; ++mm) {
;                     const int row = row0 + ai * 128 + (2 * mp + mm) * 16;
;                     scv[mm] = ssq[row];
; #pragma unroll
;                     for (int bj = 0; bj < 2; ++bj) { const size_t off = (size_t)row * 1024 + col0 + bj * 128; hv[mm][bj] = *(const u32x4*)(hbase + off); pw[mm][bj] = *(const u32x4*)(pp + off); }
;                 }
; #pragma unroll
;                 for (int mm = 0; mm < 2; ++mm) {
;                     const int m = 2 * mp + mm, row = row0 + ai * 128 + m * 16; float sq = 0.f;
;                     const float sc = __builtin_amdgcn_rsqf(scv[mm] * (1.f / 1024.f) + EPS);
; #pragma unroll
;                     for (int bj = 0; bj < 2; ++bj) {
;                         const size_t off = (size_t)row * 1024 + col0 + bj * 128;
;                         const u32x4 pwv = pw[mm][bj], hw = hv[mm][bj];
;                         const f32x4 p0 = (f32x4){bflo(pwv.x), bfhi(pwv.x), bflo(pwv.y), bfhi(pwv.y)}, p1 = (f32x4){bflo(pwv.z), bfhi(pwv.z), bflo(pwv.w), bfhi(pwv.w)};
;                         f32x4 g0 = acc[ai][bj][m][0] * sc, g1 = acc[ai][bj][m][1] * sc;
; #pragma unroll
;                         for (int e = 0; e < 4; ++e) { g0[e] = __builtin_amdgcn_rcpf(1.f + __builtin_amdgcn_exp2f(-1.4426950408889634f * g0[e])); g1[e] = __builtin_amdgcn_rcpf(1.f + __builtin_amdgcn_exp2f(-1.4426950408889634f * g1[e])); }
;                         const f32x4 o0 = (f32x4){bflo(hw.x), bfhi(hw.x), bflo(hw.y), bfhi(hw.y)} + g0 * p0;
;                         const f32x4 o1 = (f32x4){bflo(hw.z), bfhi(hw.z), bflo(hw.w), bfhi(hw.w)} + g1 * p1;
;                         if (fout) { *(f32x4*)(fout + off) = o0; *(f32x4*)(fout + off + 4) = o1; }
;                         if (hb_out) *(u32x4*)(hb_out + off) = pack8(o0, o1);
	v_lshl_add_u64 v[66:67], v[210:211], 2, s[58:59]
	s_waitcnt lgkmcnt(0)
	v_add_f32_e32 v64, v64, v65
	flat_atomic_add_f32 v[66:67], v64
.LBB0_692:
	s_or_b64 exec, exec, s[28:29]
	s_and_b64 vcc, exec, s[8:9]
	v_lshl_add_u64 v[200:201], v[200:201], 1, s[52:53]
	s_waitcnt vmcnt(4)
	global_load_dword v146, v[170:171], off offset:640
	v_add_u32_e32 v130, 0xa0, v172
	v_add_u32_e32 v86, 0xb0, v172
	v_ashrrev_i32_e32 v131, 31, v130
	v_ashrrev_i32_e32 v87, 31, v86
	s_waitcnt lgkmcnt(0)
	v_lshlrev_b64 v[88:89], 10, v[130:131]
	v_lshlrev_b64 v[92:93], 10, v[86:87]
	v_lshl_add_u64 v[202:203], v[88:89], 0, v[168:169]
	v_lshl_add_u64 v[96:97], v[92:93], 0, v[168:169]
	v_lshlrev_b64 v[88:89], 1, v[202:203]
	v_lshlrev_b64 v[92:93], 1, v[96:97]
	v_lshl_add_u64 v[90:91], s[48:49], 0, v[88:89]
	v_lshl_add_u64 v[88:89], s[42:43], 0, v[88:89]
	v_lshl_add_u64 v[94:95], s[42:43], 0, v[92:93]
	v_lshl_add_u64 v[92:93], s[48:49], 0, v[92:93]
	global_load_dwordx4 v[204:207], v[90:91], off
	global_load_dwordx4 v[208:211], v[88:89], off
	global_load_dwordx4 v[140:143], v[88:89], off offset:256
	global_load_dword v85, v[170:171], off offset:704
	global_load_dwordx4 v[148:151], v[90:91], off offset:256
	global_load_dwordx4 v[100:103], v[94:95], off
	global_load_dwordx4 v[104:107], v[92:93], off
	s_nop 0
	global_load_dwordx4 v[88:91], v[94:95], off offset:256
	s_nop 0
	global_load_dwordx4 v[92:95], v[92:93], off offset:256
	v_fmamk_f32 v180, v180, 0x3a800000, v186
	v_rsq_f32_e32 v180, v180
	s_waitcnt lgkmcnt(0)
	v_lshlrev_b32_e32 v108, 16, v192
	v_pk_mul_f32 v[62:63], v[62:63], v[180:181] op_sel_hi:[1,0]
	v_pk_mul_f32 v[60:61], v[60:61], v[180:181] op_sel_hi:[1,0]
	v_pk_mul_f32 v[58:59], v[58:59], v[180:181] op_sel_hi:[1,0]
	v_pk_mul_f32 v[56:57], v[56:57], v[180:181] op_sel_hi:[1,0]
	v_mul_f32_e32 v60, 0xbfb8aa3b, v60
	v_mul_f32_e32 v181, 0xbfb8aa3b, v56
	v_mul_f32_e32 v61, 0xbfb8aa3b, v61
	v_mul_f32_e32 v99, 0xbfb8aa3b, v57
	v_mul_f32_e32 v62, 0xbfb8aa3b, v62
	v_mul_f32_e32 v112, 0xbfb8aa3b, v58
	v_mul_f32_e32 v63, 0xbfb8aa3b, v63
	v_mul_f32_e32 v113, 0xbfb8aa3b, v59
	v_exp_f32_e32 v60, v60
	v_exp_f32_e32 v181, v181
	v_exp_f32_e32 v61, v61
	v_exp_f32_e32 v99, v99
	v_exp_f32_e32 v62, v62
	v_exp_f32_e32 v112, v112
	v_exp_f32_e32 v63, v63
	v_exp_f32_e32 v113, v113
	v_add_f32_e32 v60, 1.0, v60
	v_add_f32_e32 v181, 1.0, v181
	v_add_f32_e32 v61, 1.0, v61
	v_add_f32_e32 v99, 1.0, v99
	v_add_f32_e32 v114, 1.0, v62
	v_add_f32_e32 v115, 1.0, v112
	v_add_f32_e32 v116, 1.0, v63
	v_add_f32_e32 v113, 1.0, v113
	v_rcp_f32_e32 v62, v60
	v_rcp_f32_e32 v112, v181
	v_rcp_f32_e32 v63, v61
	v_rcp_f32_e32 v60, v114
	v_rcp_f32_e32 v61, v116
	v_rcp_f32_e32 v114, v115
	v_rcp_f32_e32 v115, v113
	v_rcp_f32_e32 v113, v99
	v_and_b32_e32 v109, 0xffff0000, v192
	v_lshlrev_b32_e32 v192, 16, v193
	v_and_b32_e32 v193, 0xffff0000, v193
	v_lshlrev_b32_e32 v110, 16, v194
	v_and_b32_e32 v111, 0xffff0000, v194
	v_lshlrev_b32_e32 v194, 16, v195
	v_and_b32_e32 v195, 0xffff0000, v195
	v_lshlrev_b32_e32 v56, 16, v196
	v_and_b32_e32 v57, 0xffff0000, v196
	v_lshlrev_b32_e32 v58, 16, v197
	v_and_b32_e32 v59, 0xffff0000, v197
	v_lshlrev_b32_e32 v196, 16, v198
	v_and_b32_e32 v197, 0xffff0000, v198
	v_lshlrev_b32_e32 v198, 16, v199
	v_and_b32_e32 v199, 0xffff0000, v199
	v_pk_fma_f32 v[60:61], v[60:61], v[192:193], v[58:59]
	v_pk_fma_f32 v[62:63], v[62:63], v[108:109], v[56:57]
	v_pk_fma_f32 v[56:57], v[114:115], v[194:195], v[198:199]
	v_pk_fma_f32 v[58:59], v[112:113], v[110:111], v[196:197]
	s_cbranch_vccnz .LBB0_694

; __device__ __forceinline__ u32x4 pack8(f32x4 a, f32x4 b) { u32x4 w; w.x = pk2(a[0], a[1]); w.y = pk2(a[2], a[3]); w.z = pk2(b[0], b[1]); w.w = pk2(b[2], b[3]); return w; }
;     __device__ __forceinline__ void operator()(const Acc& acc, const pg8::Unit& u, int wid) const {
;     ...
;                     for (int bj = 0; bj < 2; ++bj) {
;                         const size_t off = (size_t)row * 1024 + col0 + bj * 128;
;                         const u32x4 pwv = pw[mm][bj], hw = hv[mm][bj];
;                         const f32x4 p0 = (f32x4){bflo(pwv.x), bfhi(pwv.x), bflo(pwv.y), bfhi(pwv.y)}, p1 = (f32x4){bflo(pwv.z), bfhi(pwv.z), bflo(pwv.w), bfhi(pwv.w)};
;                         f32x4 g0 = acc[ai][bj][m][0] * sc, g1 = acc[ai][bj][m][1] * sc;
; #pragma unroll
;                         for (int e = 0; e < 4; ++e) { g0[e] = __builtin_amdgcn_rcpf(1.f + __builtin_amdgcn_exp2f(-1.4426950408889634f * g0[e])); g1[e] = __builtin_amdgcn_rcpf(1.f + __builtin_amdgcn_exp2f(-1.4426950408889634f * g1[e])); }
;                         const f32x4 o0 = (f32x4){bflo(hw.x), bfhi(hw.x), bflo(hw.y), bfhi(hw.y)} + g0 * p0;
;                         const f32x4 o1 = (f32x4){bflo(hw.z), bfhi(hw.z), bflo(hw.w), bfhi(hw.w)} + g1 * p1;
;                         if (fout) { *(f32x4*)(fout + off) = o0; *(f32x4*)(fout + off + 4) = o1; }
;                         if (hb_out) *(u32x4*)(hb_out + off) = pack8(o0, o1);
	v_cvt_pk_bf16_f32 v192, v62, v63
	v_cvt_pk_bf16_f32 v193, v60, v61
	v_cvt_pk_bf16_f32 v194, v58, v59
	v_cvt_pk_bf16_f32 v195, v56, v57
	global_store_dwordx4 v[200:201], v[192:195], off
.LBB0_694:
	v_mov_b32_e32 v181, v180
	v_pk_mul_f32 v[52:53], v[52:53], v[180:181]
	v_pk_mul_f32 v[48:49], v[48:49], v[180:181]
	v_mul_f32_e32 v52, 0xbfb8aa3b, v52
	v_mul_f32_e32 v48, 0xbfb8aa3b, v48
	v_mov_b32_e32 v196, v180
	v_mov_b32_e32 v197, v180
	v_exp_f32_e32 v52, v52
	v_exp_f32_e32 v180, v48
	v_mul_f32_e32 v53, 0xbfb8aa3b, v53
	v_mul_f32_e32 v49, 0xbfb8aa3b, v49
	v_add_f32_e32 v48, 1.0, v52
	v_add_f32_e32 v52, 1.0, v180
	v_exp_f32_e32 v53, v53
	v_exp_f32_e32 v180, v49
	v_pk_mul_f32 v[54:55], v[54:55], v[196:197]
	v_pk_mul_f32 v[50:51], v[50:51], v[196:197]
	v_mul_f32_e32 v54, 0xbfb8aa3b, v54
	v_mul_f32_e32 v50, 0xbfb8aa3b, v50
	v_add_f32_e32 v49, 1.0, v53
	v_add_f32_e32 v53, 1.0, v180
	v_exp_f32_e32 v54, v54
	v_exp_f32_e32 v180, v50
	v_mul_f32_e32 v55, 0xbfb8aa3b, v55
	v_exp_f32_e32 v55, v55
	v_mul_f32_e32 v51, 0xbfb8aa3b, v51
	v_add_f32_e32 v50, 1.0, v54
	v_add_f32_e32 v54, 1.0, v180
	v_exp_f32_e32 v180, v51
	v_add_f32_e32 v51, 1.0, v55
	v_rcp_f32_e32 v50, v50
	v_rcp_f32_e32 v51, v51
	v_add_f32_e32 v55, 1.0, v180
	v_rcp_f32_e32 v48, v48
	v_rcp_f32_e32 v52, v52
	v_rcp_f32_e32 v49, v49
	v_rcp_f32_e32 v53, v53
	v_rcp_f32_e32 v54, v54
	v_rcp_f32_e32 v55, v55
	v_lshlrev_b32_e32 v192, 16, v188
	v_and_b32_e32 v193, 0xffff0000, v188
	v_lshlrev_b32_e32 v188, 16, v189
	v_and_b32_e32 v189, 0xffff0000, v189
	v_lshlrev_b32_e32 v180, 16, v176
	v_and_b32_e32 v181, 0xffff0000, v176
	v_lshlrev_b32_e32 v176, 16, v177
	v_and_b32_e32 v177, 0xffff0000, v177
	v_lshlrev_b32_e32 v194, 16, v190
	v_and_b32_e32 v195, 0xffff0000, v190
	v_lshlrev_b32_e32 v190, 16, v191
	v_and_b32_e32 v191, 0xffff0000, v191
	v_pk_fma_f32 v[50:51], v[50:51], v[188:189], v[176:177]
	v_lshlrev_b32_e32 v176, 16, v178
	v_and_b32_e32 v177, 0xffff0000, v178
	v_lshlrev_b32_e32 v178, 16, v179
	v_and_b32_e32 v179, 0xffff0000, v179
	v_pk_fma_f32 v[48:49], v[48:49], v[192:193], v[180:181]
	v_pk_fma_f32 v[52:53], v[52:53], v[194:195], v[176:177]
	s_and_b64 vcc, exec, s[8:9]
	v_pk_fma_f32 v[54:55], v[54:55], v[190:191], v[178:179]
	s_cbranch_vccnz .LBB0_696

; __device__ __forceinline__ u32x4 pack8(f32x4 a, f32x4 b) { u32x4 w; w.x = pk2(a[0], a[1]); w.y = pk2(a[2], a[3]); w.z = pk2(b[0], b[1]); w.w = pk2(b[2], b[3]); return w; }
;     __device__ __forceinline__ void operator()(const Acc& acc, const pg8::Unit& u, int wid) const {
;     ...
;                     for (int bj = 0; bj < 2; ++bj) {
;                         const size_t off = (size_t)row * 1024 + col0 + bj * 128;
;                         const u32x4 pwv = pw[mm][bj], hw = hv[mm][bj];
;                         const f32x4 p0 = (f32x4){bflo(pwv.x), bfhi(pwv.x), bflo(pwv.y), bfhi(pwv.y)}, p1 = (f32x4){bflo(pwv.z), bfhi(pwv.z), bflo(pwv.w), bfhi(pwv.w)};
;                         f32x4 g0 = acc[ai][bj][m][0] * sc, g1 = acc[ai][bj][m][1] * sc;
; #pragma unroll
;                         for (int e = 0; e < 4; ++e) { g0[e] = __builtin_amdgcn_rcpf(1.f + __builtin_amdgcn_exp2f(-1.4426950408889634f * g0[e])); g1[e] = __builtin_amdgcn_rcpf(1.f + __builtin_amdgcn_exp2f(-1.4426950408889634f * g1[e])); }
;                         const f32x4 o0 = (f32x4){bflo(hw.x), bfhi(hw.x), bflo(hw.y), bfhi(hw.y)} + g0 * p0;
;                         const f32x4 o1 = (f32x4){bflo(hw.z), bfhi(hw.z), bflo(hw.w), bfhi(hw.w)} + g1 * p1;
;                         if (fout) { *(f32x4*)(fout + off) = o0; *(f32x4*)(fout + off + 4) = o1; }
;                         if (hb_out) *(u32x4*)(hb_out + off) = pack8(o0, o1);
;                         sq += (o0[0] * o0[0] + o0[1] * o0[1]) + (o0[2] * o0[2] + o0[3] * o0[3]) + (o1[0] * o1[0] + o1[1] * o1[1]) + (o1[2] * o1[2] + o1[3] * o1[3]);
;                     }
;                     if (ssq_out) { sq += __shfl_xor(sq, 16); sq += __shfl_xor(sq, 32); if (fq == 0) atomicAdd(ssq_out + row, sq); }
	v_cvt_pk_bf16_f32 v176, v48, v49
	v_cvt_pk_bf16_f32 v177, v50, v51
	v_cvt_pk_bf16_f32 v178, v52, v53
	v_cvt_pk_bf16_f32 v179, v54, v55
	global_store_dwordx4 v[200:201], v[176:179], off offset:256
.LBB0_696:
	v_mul_f32_e32 v49, v49, v49
	v_fmac_f32_e32 v49, v48, v48
	v_mul_f32_e32 v48, v51, v51
	v_mul_f32_e32 v63, v63, v63
	v_mul_f32_e32 v61, v61, v61
	v_fmac_f32_e32 v48, v50, v50
	v_fmac_f32_e32 v63, v62, v62
	v_fmac_f32_e32 v61, v60, v60
	v_mul_f32_e32 v59, v59, v59
	v_add_f32_e32 v48, v49, v48
	v_mul_f32_e32 v49, v53, v53
	v_add_f32_e32 v60, v63, v61
	v_fmac_f32_e32 v59, v58, v58
	v_mul_f32_e32 v57, v57, v57
	v_mul_f32_e32 v55, v55, v55
	v_fmac_f32_e32 v49, v52, v52
	v_add_f32_e32 v58, v59, v60
	v_fmac_f32_e32 v57, v56, v56
	v_fmac_f32_e32 v55, v54, v54
	v_add_f32_e32 v48, v49, v48
	v_add_f32_e32 v56, v57, v58
	v_add_f32_e32 v48, v55, v48
	v_add_f32_e32 v48, v56, v48
	ds_bpermute_b32 v49, v144, v48
	s_waitcnt lgkmcnt(0)
	v_add_f32_e32 v48, v48, v49
	ds_bpermute_b32 v49, v145, v48
	s_and_saveexec_b64 s[28:29], s[10:11]
	s_cbranch_execz .LBB0_698

; __device__ __forceinline__ u32x4 pack8(f32x4 a, f32x4 b) { u32x4 w; w.x = pk2(a[0], a[1]); w.y = pk2(a[2], a[3]); w.z = pk2(b[0], b[1]); w.w = pk2(b[2], b[3]); return w; }
;     __device__ __forceinline__ void operator()(const Acc& acc, const pg8::Unit& u, int wid) const {
;     ...
;                 for (int mm = 0; mm < 2; ++mm) {
;                     const int m = 2 * mp + mm, row = row0 + ai * 128 + m * 16; float sq = 0.f;
;                     const float sc = __builtin_amdgcn_rsqf(scv[mm] * (1.f / 1024.f) + EPS);
; #pragma unroll
;                     for (int bj = 0; bj < 2; ++bj) {
;                         const size_t off = (size_t)row * 1024 + col0 + bj * 128;
;                         const u32x4 pwv = pw[mm][bj], hw = hv[mm][bj];
;                         const f32x4 p0 = (f32x4){bflo(pwv.x), bfhi(pwv.x), bflo(pwv.y), bfhi(pwv.y)}, p1 = (f32x4){bflo(pwv.z), bfhi(pwv.z), bflo(pwv.w), bfhi(pwv.w)};
;                         f32x4 g0 = acc[ai][bj][m][0] * sc, g1 = acc[ai][bj][m][1] * sc;
; #pragma unroll
;                         for (int e = 0; e < 4; ++e) { g0[e] = __builtin_amdgcn_rcpf(1.f + __builtin_amdgcn_exp2f(-1.4426950408889634f * g0[e])); g1[e] = __builtin_amdgcn_rcpf(1.f + __builtin_amdgcn_exp2f(-1.4426950408889634f * g1[e])); }
;                         const f32x4 o0 = (f32x4){bflo(hw.x), bfhi(hw.x), bflo(hw.y), bfhi(hw.y)} + g0 * p0;
;                         const f32x4 o1 = (f32x4){bflo(hw.z), bfhi(hw.z), bflo(hw.w), bfhi(hw.w)} + g1 * p1;
;                         if (fout) { *(f32x4*)(fout + off) = o0; *(f32x4*)(fout + off + 4) = o1; }
;                         if (hb_out) *(u32x4*)(hb_out + off) = pack8(o0, o1);
;                         sq += (o0[0] * o0[0] + o0[1] * o0[1]) + (o0[2] * o0[2] + o0[3] * o0[3]) + (o1[0] * o1[0] + o1[1] * o1[1]) + (o1[2] * o1[2] + o1[3] * o1[3]);
;                     }
;                     if (ssq_out) { sq += __shfl_xor(sq, 16); sq += __shfl_xor(sq, 32); if (fq == 0) atomicAdd(ssq_out + row, sq); }
	v_lshl_add_u64 v[50:51], v[174:175], 2, s[58:59]
	s_waitcnt lgkmcnt(0)
	v_add_f32_e32 v48, v48, v49
	flat_atomic_add_f32 v[50:51], v48
.LBB0_698:
	s_or_b64 exec, exec, s[28:29]
	v_fmamk_f32 v48, v117, 0x3a800000, v186
	v_rsq_f32_e32 v48, v48
	v_lshlrev_b32_e32 v50, 16, v136
	v_and_b32_e32 v51, 0xffff0000, v136
	v_lshlrev_b32_e32 v52, 16, v137
	s_waitcnt lgkmcnt(0)
	v_pk_mul_f32 v[40:41], v[40:41], v[48:49] op_sel_hi:[1,0]
	v_pk_mul_f32 v[44:45], v[44:45], v[48:49] op_sel_hi:[1,0]
	v_mul_f32_e32 v40, 0xbfb8aa3b, v40
	v_exp_f32_e32 v40, v40
	v_mul_f32_e32 v45, 0xbfb8aa3b, v45
	v_exp_f32_e32 v45, v45
	v_mul_f32_e32 v41, 0xbfb8aa3b, v41
	v_exp_f32_e32 v41, v41
	v_add_f32_e32 v40, 1.0, v40
	v_pk_mul_f32 v[46:47], v[46:47], v[48:49] op_sel_hi:[1,0]
	v_pk_mul_f32 v[42:43], v[42:43], v[48:49] op_sel_hi:[1,0]
	v_rcp_f32_e32 v58, v40
	v_add_f32_e32 v40, 1.0, v45
	v_rcp_f32_e32 v45, v40
	v_add_f32_e32 v40, 1.0, v41
	v_mul_f32_e32 v41, 0xbfb8aa3b, v46
	v_mul_f32_e32 v42, 0xbfb8aa3b, v42
	v_exp_f32_e32 v41, v41
	v_exp_f32_e32 v42, v42
	v_mul_f32_e32 v44, 0xbfb8aa3b, v44
	v_exp_f32_e32 v44, v44
	v_rcp_f32_e32 v59, v40
	v_add_f32_e32 v40, 1.0, v41
	v_add_f32_e32 v41, 1.0, v42
	v_mul_f32_e32 v42, 0xbfb8aa3b, v47
	v_mul_f32_e32 v43, 0xbfb8aa3b, v43
	v_exp_f32_e32 v42, v42
	v_exp_f32_e32 v43, v43
	v_add_f32_e32 v44, 1.0, v44
	v_rcp_f32_e32 v44, v44
	v_rcp_f32_e32 v46, v41
	v_add_f32_e32 v41, 1.0, v42
	v_add_f32_e32 v42, 1.0, v43
	v_rcp_f32_e32 v40, v40
	v_rcp_f32_e32 v41, v41
	v_rcp_f32_e32 v47, v42
	v_lshlrev_b32_e32 v42, 16, v132
	v_and_b32_e32 v43, 0xffff0000, v132
	v_and_b32_e32 v53, 0xffff0000, v137
	v_lshlrev_b32_e32 v54, 16, v138
	v_and_b32_e32 v55, 0xffff0000, v138
	v_lshlrev_b32_e32 v56, 16, v139
	v_and_b32_e32 v57, 0xffff0000, v139
	v_lshlrev_b32_e32 v60, 16, v133
	v_and_b32_e32 v61, 0xffff0000, v133
	v_pk_fma_f32 v[42:43], v[44:45], v[50:51], v[42:43]
	v_lshlrev_b32_e32 v50, 16, v134
	v_and_b32_e32 v51, 0xffff0000, v134
	v_lshlrev_b32_e32 v44, 16, v135
	v_and_b32_e32 v45, 0xffff0000, v135
	v_pk_fma_f32 v[40:41], v[40:41], v[52:53], v[60:61]
	v_pk_fma_f32 v[44:45], v[46:47], v[56:57], v[44:45]
	v_pk_fma_f32 v[46:47], v[58:59], v[54:55], v[50:51]
	s_and_b64 vcc, exec, s[8:9]
	v_lshl_add_u64 v[50:51], v[128:129], 1, s[52:53]
	s_cbranch_vccnz .LBB0_700

; __device__ __forceinline__ u32x4 pack8(f32x4 a, f32x4 b) { u32x4 w; w.x = pk2(a[0], a[1]); w.y = pk2(a[2], a[3]); w.z = pk2(b[0], b[1]); w.w = pk2(b[2], b[3]); return w; }
;     __device__ __forceinline__ void operator()(const Acc& acc, const pg8::Unit& u, int wid) const {
;     ...
;                     for (int bj = 0; bj < 2; ++bj) {
;                         const size_t off = (size_t)row * 1024 + col0 + bj * 128;
;                         const u32x4 pwv = pw[mm][bj], hw = hv[mm][bj];
;                         const f32x4 p0 = (f32x4){bflo(pwv.x), bfhi(pwv.x), bflo(pwv.y), bfhi(pwv.y)}, p1 = (f32x4){bflo(pwv.z), bfhi(pwv.z), bflo(pwv.w), bfhi(pwv.w)};
;                         f32x4 g0 = acc[ai][bj][m][0] * sc, g1 = acc[ai][bj][m][1] * sc;
; #pragma unroll
;                         for (int e = 0; e < 4; ++e) { g0[e] = __builtin_amdgcn_rcpf(1.f + __builtin_amdgcn_exp2f(-1.4426950408889634f * g0[e])); g1[e] = __builtin_amdgcn_rcpf(1.f + __builtin_amdgcn_exp2f(-1.4426950408889634f * g1[e])); }
;                         const f32x4 o0 = (f32x4){bflo(hw.x), bfhi(hw.x), bflo(hw.y), bfhi(hw.y)} + g0 * p0;
;                         const f32x4 o1 = (f32x4){bflo(hw.z), bfhi(hw.z), bflo(hw.w), bfhi(hw.w)} + g1 * p1;
;                         if (fout) { *(f32x4*)(fout + off) = o0; *(f32x4*)(fout + off + 4) = o1; }
;                         if (hb_out) *(u32x4*)(hb_out + off) = pack8(o0, o1);
	v_cvt_pk_bf16_f32 v52, v42, v43
	v_cvt_pk_bf16_f32 v53, v40, v41
	v_cvt_pk_bf16_f32 v54, v46, v47
	v_cvt_pk_bf16_f32 v55, v44, v45
	global_store_dwordx4 v[50:51], v[52:55], off
.LBB0_700:
	v_mov_b32_e32 v49, v48
	v_pk_mul_f32 v[36:37], v[36:37], v[48:49]
	v_pk_mul_f32 v[32:33], v[32:33], v[48:49]
	v_mul_f32_e32 v36, 0xbfb8aa3b, v36
	v_mul_f32_e32 v32, 0xbfb8aa3b, v32
	v_mov_b32_e32 v60, v48
	v_mov_b32_e32 v61, v48
	v_exp_f32_e32 v36, v36
	v_exp_f32_e32 v48, v32
	v_mul_f32_e32 v37, 0xbfb8aa3b, v37
	v_mul_f32_e32 v33, 0xbfb8aa3b, v33
	v_add_f32_e32 v32, 1.0, v36
	v_add_f32_e32 v36, 1.0, v48
	v_exp_f32_e32 v37, v37
	v_exp_f32_e32 v48, v33
	v_pk_mul_f32 v[38:39], v[38:39], v[60:61]
	v_pk_mul_f32 v[34:35], v[34:35], v[60:61]
	v_mul_f32_e32 v38, 0xbfb8aa3b, v38
	v_mul_f32_e32 v34, 0xbfb8aa3b, v34
	v_add_f32_e32 v33, 1.0, v37
	v_add_f32_e32 v37, 1.0, v48
	v_exp_f32_e32 v38, v38
	v_exp_f32_e32 v48, v34
	v_mul_f32_e32 v39, 0xbfb8aa3b, v39
	v_mul_f32_e32 v35, 0xbfb8aa3b, v35
	v_add_f32_e32 v34, 1.0, v38
	v_add_f32_e32 v38, 1.0, v48
	v_exp_f32_e32 v39, v39
	v_exp_f32_e32 v48, v35
	v_rcp_f32_e32 v32, v32
	v_rcp_f32_e32 v33, v33
	v_add_f32_e32 v35, 1.0, v39
	v_add_f32_e32 v39, 1.0, v48
	v_rcp_f32_e32 v36, v36
	v_rcp_f32_e32 v37, v37
	v_rcp_f32_e32 v34, v34
	v_rcp_f32_e32 v38, v38
	v_rcp_f32_e32 v35, v35
	v_rcp_f32_e32 v39, v39
	v_lshlrev_b32_e32 v52, 16, v124
	v_and_b32_e32 v53, 0xffff0000, v124
	v_lshlrev_b32_e32 v48, 16, v120
	v_and_b32_e32 v49, 0xffff0000, v120
	v_lshlrev_b32_e32 v54, 16, v125
	v_and_b32_e32 v55, 0xffff0000, v125
	v_lshlrev_b32_e32 v56, 16, v126
	v_and_b32_e32 v57, 0xffff0000, v126
	v_lshlrev_b32_e32 v58, 16, v127
	v_and_b32_e32 v59, 0xffff0000, v127
	v_lshlrev_b32_e32 v60, 16, v121
	v_and_b32_e32 v61, 0xffff0000, v121
	v_pk_fma_f32 v[32:33], v[32:33], v[52:53], v[48:49]
	v_lshlrev_b32_e32 v48, 16, v122
	v_and_b32_e32 v49, 0xffff0000, v122
	v_lshlrev_b32_e32 v52, 16, v123
	v_and_b32_e32 v53, 0xffff0000, v123
	v_pk_fma_f32 v[34:35], v[34:35], v[54:55], v[60:61]
	v_pk_fma_f32 v[36:37], v[36:37], v[56:57], v[48:49]
	s_and_b64 vcc, exec, s[8:9]
	v_pk_fma_f32 v[38:39], v[38:39], v[58:59], v[52:53]
	s_cbranch_vccnz .LBB0_702

; __device__ __forceinline__ u32x4 pack8(f32x4 a, f32x4 b) { u32x4 w; w.x = pk2(a[0], a[1]); w.y = pk2(a[2], a[3]); w.z = pk2(b[0], b[1]); w.w = pk2(b[2], b[3]); return w; }
;     __device__ __forceinline__ void operator()(const Acc& acc, const pg8::Unit& u, int wid) const {
;     ...
;                     for (int bj = 0; bj < 2; ++bj) {
;                         const size_t off = (size_t)row * 1024 + col0 + bj * 128;
;                         const u32x4 pwv = pw[mm][bj], hw = hv[mm][bj];
;                         const f32x4 p0 = (f32x4){bflo(pwv.x), bfhi(pwv.x), bflo(pwv.y), bfhi(pwv.y)}, p1 = (f32x4){bflo(pwv.z), bfhi(pwv.z), bflo(pwv.w), bfhi(pwv.w)};
;                         f32x4 g0 = acc[ai][bj][m][0] * sc, g1 = acc[ai][bj][m][1] * sc;
; #pragma unroll
;                         for (int e = 0; e < 4; ++e) { g0[e] = __builtin_amdgcn_rcpf(1.f + __builtin_amdgcn_exp2f(-1.4426950408889634f * g0[e])); g1[e] = __builtin_amdgcn_rcpf(1.f + __builtin_amdgcn_exp2f(-1.4426950408889634f * g1[e])); }
;                         const f32x4 o0 = (f32x4){bflo(hw.x), bfhi(hw.x), bflo(hw.y), bfhi(hw.y)} + g0 * p0;
;                         const f32x4 o1 = (f32x4){bflo(hw.z), bfhi(hw.z), bflo(hw.w), bfhi(hw.w)} + g1 * p1;
;                         if (fout) { *(f32x4*)(fout + off) = o0; *(f32x4*)(fout + off + 4) = o1; }
;                         if (hb_out) *(u32x4*)(hb_out + off) = pack8(o0, o1);
;                         sq += (o0[0] * o0[0] + o0[1] * o0[1]) + (o0[2] * o0[2] + o0[3] * o0[3]) + (o1[0] * o1[0] + o1[1] * o1[1]) + (o1[2] * o1[2] + o1[3] * o1[3]);
;                     }
;                     if (ssq_out) { sq += __shfl_xor(sq, 16); sq += __shfl_xor(sq, 32); if (fq == 0) atomicAdd(ssq_out + row, sq); }
	v_cvt_pk_bf16_f32 v52, v32, v33
	v_cvt_pk_bf16_f32 v53, v34, v35
	v_cvt_pk_bf16_f32 v54, v36, v37
	v_cvt_pk_bf16_f32 v55, v38, v39
	global_store_dwordx4 v[50:51], v[52:55], off offset:256
.LBB0_702:
	v_mul_f32_e32 v43, v43, v43
	v_mul_f32_e32 v41, v41, v41
	v_mul_f32_e32 v33, v33, v33
	v_fmac_f32_e32 v43, v42, v42
	v_fmac_f32_e32 v41, v40, v40
	v_fmac_f32_e32 v33, v32, v32
	v_mul_f32_e32 v32, v35, v35
	v_add_f32_e32 v40, v43, v41
	v_mul_f32_e32 v41, v47, v47
	v_fmac_f32_e32 v32, v34, v34
	v_fmac_f32_e32 v41, v46, v46
	v_add_f32_e32 v32, v33, v32
	v_mul_f32_e32 v33, v37, v37
	v_add_f32_e32 v40, v41, v40
	v_mul_f32_e32 v41, v45, v45
	v_mul_f32_e32 v39, v39, v39
	v_fmac_f32_e32 v33, v36, v36
	v_fmac_f32_e32 v41, v44, v44
	v_fmac_f32_e32 v39, v38, v38
	v_add_f32_e32 v32, v33, v32
	v_add_f32_e32 v40, v41, v40
	v_add_f32_e32 v32, v39, v32
	v_add_f32_e32 v32, v40, v32
	ds_bpermute_b32 v33, v144, v32
	s_waitcnt lgkmcnt(0)
	v_add_f32_e32 v32, v32, v33
	ds_bpermute_b32 v33, v145, v32
	s_and_saveexec_b64 s[28:29], s[10:11]
	s_cbranch_execz .LBB0_704

; __device__ __forceinline__ u32x4 pack8(f32x4 a, f32x4 b) { u32x4 w; w.x = pk2(a[0], a[1]); w.y = pk2(a[2], a[3]); w.z = pk2(b[0], b[1]); w.w = pk2(b[2], b[3]); return w; }
;     __device__ __forceinline__ void operator()(const Acc& acc, const pg8::Unit& u, int wid) const {
;     ...
;             for (int mp = 0; mp < 2; ++mp) {
;                 u32x4 hv[2][2], pw[2][2]; float scv[2];
; #pragma unroll
;                 for (int mm = 0; mm < 2; ++mm) {
;                     const int row = row0 + ai * 128 + (2 * mp + mm) * 16;
;                     scv[mm] = ssq[row];
; #pragma unroll
;                     for (int bj = 0; bj < 2; ++bj) { const size_t off = (size_t)row * 1024 + col0 + bj * 128; hv[mm][bj] = *(const u32x4*)(hbase + off); pw[mm][bj] = *(const u32x4*)(pp + off); }
;                 }
; #pragma unroll
;                 for (int mm = 0; mm < 2; ++mm) {
;                     const int m = 2 * mp + mm, row = row0 + ai * 128 + m * 16; float sq = 0.f;
;                     const float sc = __builtin_amdgcn_rsqf(scv[mm] * (1.f / 1024.f) + EPS);
; #pragma unroll
;                     for (int bj = 0; bj < 2; ++bj) {
;                         const size_t off = (size_t)row * 1024 + col0 + bj * 128;
;                         const u32x4 pwv = pw[mm][bj], hw = hv[mm][bj];
;                         const f32x4 p0 = (f32x4){bflo(pwv.x), bfhi(pwv.x), bflo(pwv.y), bfhi(pwv.y)}, p1 = (f32x4){bflo(pwv.z), bfhi(pwv.z), bflo(pwv.w), bfhi(pwv.w)};
;                         f32x4 g0 = acc[ai][bj][m][0] * sc, g1 = acc[ai][bj][m][1] * sc;
; #pragma unroll
;                         for (int e = 0; e < 4; ++e) { g0[e] = __builtin_amdgcn_rcpf(1.f + __builtin_amdgcn_exp2f(-1.4426950408889634f * g0[e])); g1[e] = __builtin_amdgcn_rcpf(1.f + __builtin_amdgcn_exp2f(-1.4426950408889634f * g1[e])); }
;                         const f32x4 o0 = (f32x4){bflo(hw.x), bfhi(hw.x), bflo(hw.y), bfhi(hw.y)} + g0 * p0;
;                         const f32x4 o1 = (f32x4){bflo(hw.z), bfhi(hw.z), bflo(hw.w), bfhi(hw.w)} + g1 * p1;
;                         if (fout) { *(f32x4*)(fout + off) = o0; *(f32x4*)(fout + off + 4) = o1; }
;                         if (hb_out) *(u32x4*)(hb_out + off) = pack8(o0, o1);
	v_lshl_add_u64 v[34:35], v[118:119], 2, s[58:59]
	s_waitcnt lgkmcnt(0)
	v_add_f32_e32 v32, v32, v33
	flat_atomic_add_f32 v[34:35], v32
.LBB0_704:
	s_or_b64 exec, exec, s[28:29]
	s_and_b64 vcc, exec, s[8:9]
	v_lshl_add_u64 v[202:203], v[202:203], 1, s[52:53]
	s_waitcnt vmcnt(4)
	v_fmamk_f32 v146, v146, 0x3a800000, v186
	v_rsq_f32_e32 v146, v146
	s_waitcnt lgkmcnt(0)
	v_lshlrev_b32_e32 v76, 16, v204
	v_pk_mul_f32 v[30:31], v[30:31], v[146:147] op_sel_hi:[1,0]
	v_pk_mul_f32 v[28:29], v[28:29], v[146:147] op_sel_hi:[1,0]
	v_pk_mul_f32 v[26:27], v[26:27], v[146:147] op_sel_hi:[1,0]
	v_pk_mul_f32 v[24:25], v[24:25], v[146:147] op_sel_hi:[1,0]
	v_mul_f32_e32 v28, 0xbfb8aa3b, v28
	v_mul_f32_e32 v147, 0xbfb8aa3b, v24
	v_mul_f32_e32 v29, 0xbfb8aa3b, v29
	v_mul_f32_e32 v67, 0xbfb8aa3b, v25
	v_mul_f32_e32 v30, 0xbfb8aa3b, v30
	v_mul_f32_e32 v80, 0xbfb8aa3b, v26
	v_mul_f32_e32 v31, 0xbfb8aa3b, v31
	v_mul_f32_e32 v81, 0xbfb8aa3b, v27
	v_exp_f32_e32 v28, v28
	v_exp_f32_e32 v147, v147
	v_exp_f32_e32 v29, v29
	v_exp_f32_e32 v67, v67
	v_exp_f32_e32 v30, v30
	v_exp_f32_e32 v80, v80
	v_exp_f32_e32 v31, v31
	v_exp_f32_e32 v81, v81
	v_add_f32_e32 v28, 1.0, v28
	v_add_f32_e32 v147, 1.0, v147
	v_add_f32_e32 v29, 1.0, v29
	v_add_f32_e32 v67, 1.0, v67
	v_add_f32_e32 v82, 1.0, v30
	v_add_f32_e32 v83, 1.0, v80
	v_add_f32_e32 v84, 1.0, v31
	v_add_f32_e32 v81, 1.0, v81
	v_rcp_f32_e32 v30, v28
	v_rcp_f32_e32 v80, v147
	v_rcp_f32_e32 v31, v29
	v_rcp_f32_e32 v28, v82
	v_rcp_f32_e32 v29, v84
	v_rcp_f32_e32 v82, v83
	v_rcp_f32_e32 v83, v81
	v_rcp_f32_e32 v81, v67
	v_and_b32_e32 v77, 0xffff0000, v204
	v_lshlrev_b32_e32 v204, 16, v205
	v_and_b32_e32 v205, 0xffff0000, v205
	v_lshlrev_b32_e32 v78, 16, v206
	v_and_b32_e32 v79, 0xffff0000, v206
	v_lshlrev_b32_e32 v206, 16, v207
	v_and_b32_e32 v207, 0xffff0000, v207
	v_lshlrev_b32_e32 v24, 16, v208
	v_and_b32_e32 v25, 0xffff0000, v208
	v_lshlrev_b32_e32 v26, 16, v209
	v_and_b32_e32 v27, 0xffff0000, v209
	v_lshlrev_b32_e32 v208, 16, v210
	v_and_b32_e32 v209, 0xffff0000, v210
	v_lshlrev_b32_e32 v210, 16, v211
	v_and_b32_e32 v211, 0xffff0000, v211
	v_pk_fma_f32 v[28:29], v[28:29], v[204:205], v[26:27]
	v_pk_fma_f32 v[30:31], v[30:31], v[76:77], v[24:25]
	v_pk_fma_f32 v[24:25], v[82:83], v[206:207], v[210:211]
	v_pk_fma_f32 v[26:27], v[80:81], v[78:79], v[208:209]
	s_cbranch_vccnz .LBB0_706

; __device__ __forceinline__ u32x4 pack8(f32x4 a, f32x4 b) { u32x4 w; w.x = pk2(a[0], a[1]); w.y = pk2(a[2], a[3]); w.z = pk2(b[0], b[1]); w.w = pk2(b[2], b[3]); return w; }
;     __device__ __forceinline__ void operator()(const Acc& acc, const pg8::Unit& u, int wid) const {
;     ...
;                     for (int bj = 0; bj < 2; ++bj) {
;                         const size_t off = (size_t)row * 1024 + col0 + bj * 128;
;                         const u32x4 pwv = pw[mm][bj], hw = hv[mm][bj];
;                         const f32x4 p0 = (f32x4){bflo(pwv.x), bfhi(pwv.x), bflo(pwv.y), bfhi(pwv.y)}, p1 = (f32x4){bflo(pwv.z), bfhi(pwv.z), bflo(pwv.w), bfhi(pwv.w)};
;                         f32x4 g0 = acc[ai][bj][m][0] * sc, g1 = acc[ai][bj][m][1] * sc;
; #pragma unroll
;                         for (int e = 0; e < 4; ++e) { g0[e] = __builtin_amdgcn_rcpf(1.f + __builtin_amdgcn_exp2f(-1.4426950408889634f * g0[e])); g1[e] = __builtin_amdgcn_rcpf(1.f + __builtin_amdgcn_exp2f(-1.4426950408889634f * g1[e])); }
;                         const f32x4 o0 = (f32x4){bflo(hw.x), bfhi(hw.x), bflo(hw.y), bfhi(hw.y)} + g0 * p0;
;                         const f32x4 o1 = (f32x4){bflo(hw.z), bfhi(hw.z), bflo(hw.w), bfhi(hw.w)} + g1 * p1;
;                         if (fout) { *(f32x4*)(fout + off) = o0; *(f32x4*)(fout + off + 4) = o1; }
;                         if (hb_out) *(u32x4*)(hb_out + off) = pack8(o0, o1);
	v_cvt_pk_bf16_f32 v204, v30, v31
	v_cvt_pk_bf16_f32 v205, v28, v29
	v_cvt_pk_bf16_f32 v206, v26, v27
	v_cvt_pk_bf16_f32 v207, v24, v25
	global_store_dwordx4 v[202:203], v[204:207], off
.LBB0_706:
	v_mov_b32_e32 v147, v146
	v_pk_mul_f32 v[20:21], v[20:21], v[146:147]
	v_pk_mul_f32 v[16:17], v[16:17], v[146:147]
	v_mul_f32_e32 v20, 0xbfb8aa3b, v20
	v_mul_f32_e32 v16, 0xbfb8aa3b, v16
	v_mov_b32_e32 v208, v146
	v_mov_b32_e32 v209, v146
	v_exp_f32_e32 v20, v20
	v_exp_f32_e32 v146, v16
	v_mul_f32_e32 v21, 0xbfb8aa3b, v21
	v_mul_f32_e32 v17, 0xbfb8aa3b, v17
	v_add_f32_e32 v16, 1.0, v20
	v_add_f32_e32 v20, 1.0, v146
	v_exp_f32_e32 v21, v21
	v_exp_f32_e32 v146, v17
	v_pk_mul_f32 v[22:23], v[22:23], v[208:209]
	v_pk_mul_f32 v[18:19], v[18:19], v[208:209]
	v_mul_f32_e32 v22, 0xbfb8aa3b, v22
	v_mul_f32_e32 v18, 0xbfb8aa3b, v18
	v_add_f32_e32 v17, 1.0, v21
	v_add_f32_e32 v21, 1.0, v146
	v_exp_f32_e32 v22, v22
	v_exp_f32_e32 v146, v18
	v_mul_f32_e32 v23, 0xbfb8aa3b, v23
	v_exp_f32_e32 v23, v23
	v_mul_f32_e32 v19, 0xbfb8aa3b, v19
	v_add_f32_e32 v18, 1.0, v22
	v_add_f32_e32 v22, 1.0, v146
	v_exp_f32_e32 v146, v19
	v_add_f32_e32 v19, 1.0, v23
	v_rcp_f32_e32 v18, v18
	v_rcp_f32_e32 v19, v19
	v_add_f32_e32 v23, 1.0, v146
	v_rcp_f32_e32 v16, v16
	v_rcp_f32_e32 v20, v20
	v_rcp_f32_e32 v17, v17
	v_rcp_f32_e32 v21, v21
	v_rcp_f32_e32 v22, v22
	v_rcp_f32_e32 v23, v23
	v_lshlrev_b32_e32 v204, 16, v148
	v_and_b32_e32 v205, 0xffff0000, v148
	v_lshlrev_b32_e32 v148, 16, v149
	v_and_b32_e32 v149, 0xffff0000, v149
	v_lshlrev_b32_e32 v146, 16, v140
	v_and_b32_e32 v147, 0xffff0000, v140
	v_lshlrev_b32_e32 v140, 16, v141
	v_and_b32_e32 v141, 0xffff0000, v141
	v_lshlrev_b32_e32 v206, 16, v150
	v_and_b32_e32 v207, 0xffff0000, v150
	v_lshlrev_b32_e32 v150, 16, v151
	v_and_b32_e32 v151, 0xffff0000, v151
	v_pk_fma_f32 v[18:19], v[18:19], v[148:149], v[140:141]
	v_lshlrev_b32_e32 v140, 16, v142
	v_and_b32_e32 v141, 0xffff0000, v142
	v_lshlrev_b32_e32 v142, 16, v143
	v_and_b32_e32 v143, 0xffff0000, v143
	v_pk_fma_f32 v[16:17], v[16:17], v[204:205], v[146:147]
	v_pk_fma_f32 v[20:21], v[20:21], v[206:207], v[140:141]
	s_and_b64 vcc, exec, s[8:9]
	v_pk_fma_f32 v[22:23], v[22:23], v[150:151], v[142:143]
	s_cbranch_vccnz .LBB0_708

; __device__ __forceinline__ u32x4 pack8(f32x4 a, f32x4 b) { u32x4 w; w.x = pk2(a[0], a[1]); w.y = pk2(a[2], a[3]); w.z = pk2(b[0], b[1]); w.w = pk2(b[2], b[3]); return w; }
;     __device__ __forceinline__ void operator()(const Acc& acc, const pg8::Unit& u, int wid) const {
;     ...
;                     for (int bj = 0; bj < 2; ++bj) {
;                         const size_t off = (size_t)row * 1024 + col0 + bj * 128;
;                         const u32x4 pwv = pw[mm][bj], hw = hv[mm][bj];
;                         const f32x4 p0 = (f32x4){bflo(pwv.x), bfhi(pwv.x), bflo(pwv.y), bfhi(pwv.y)}, p1 = (f32x4){bflo(pwv.z), bfhi(pwv.z), bflo(pwv.w), bfhi(pwv.w)};
;                         f32x4 g0 = acc[ai][bj][m][0] * sc, g1 = acc[ai][bj][m][1] * sc;
; #pragma unroll
;                         for (int e = 0; e < 4; ++e) { g0[e] = __builtin_amdgcn_rcpf(1.f + __builtin_amdgcn_exp2f(-1.4426950408889634f * g0[e])); g1[e] = __builtin_amdgcn_rcpf(1.f + __builtin_amdgcn_exp2f(-1.4426950408889634f * g1[e])); }
;                         const f32x4 o0 = (f32x4){bflo(hw.x), bfhi(hw.x), bflo(hw.y), bfhi(hw.y)} + g0 * p0;
;                         const f32x4 o1 = (f32x4){bflo(hw.z), bfhi(hw.z), bflo(hw.w), bfhi(hw.w)} + g1 * p1;
;                         if (fout) { *(f32x4*)(fout + off) = o0; *(f32x4*)(fout + off + 4) = o1; }
;                         if (hb_out) *(u32x4*)(hb_out + off) = pack8(o0, o1);
;                         sq += (o0[0] * o0[0] + o0[1] * o0[1]) + (o0[2] * o0[2] + o0[3] * o0[3]) + (o1[0] * o1[0] + o1[1] * o1[1]) + (o1[2] * o1[2] + o1[3] * o1[3]);
;                     }
;                     if (ssq_out) { sq += __shfl_xor(sq, 16); sq += __shfl_xor(sq, 32); if (fq == 0) atomicAdd(ssq_out + row, sq); }
	v_cvt_pk_bf16_f32 v140, v16, v17
	v_cvt_pk_bf16_f32 v141, v18, v19
	v_cvt_pk_bf16_f32 v142, v20, v21
	v_cvt_pk_bf16_f32 v143, v22, v23
	global_store_dwordx4 v[202:203], v[140:143], off offset:256
.LBB0_708:
	v_mul_f32_e32 v17, v17, v17
	v_fmac_f32_e32 v17, v16, v16
	v_mul_f32_e32 v16, v19, v19
	v_mul_f32_e32 v31, v31, v31
	v_mul_f32_e32 v29, v29, v29
	v_fmac_f32_e32 v16, v18, v18
	v_fmac_f32_e32 v31, v30, v30
	v_fmac_f32_e32 v29, v28, v28
	v_mul_f32_e32 v27, v27, v27
	v_add_f32_e32 v16, v17, v16
	v_mul_f32_e32 v17, v21, v21
	v_add_f32_e32 v28, v31, v29
	v_fmac_f32_e32 v27, v26, v26
	v_mul_f32_e32 v25, v25, v25
	v_mul_f32_e32 v23, v23, v23
	v_fmac_f32_e32 v17, v20, v20
	v_add_f32_e32 v26, v27, v28
	v_fmac_f32_e32 v25, v24, v24
	v_fmac_f32_e32 v23, v22, v22
	v_add_f32_e32 v16, v17, v16
	v_add_f32_e32 v24, v25, v26
	v_add_f32_e32 v16, v23, v16
	v_add_f32_e32 v16, v24, v16
	ds_bpermute_b32 v17, v144, v16
	s_waitcnt lgkmcnt(0)
	v_add_f32_e32 v16, v16, v17
	ds_bpermute_b32 v17, v145, v16
	s_and_saveexec_b64 s[28:29], s[10:11]
	s_cbranch_execz .LBB0_710

; __device__ __forceinline__ u32x4 pack8(f32x4 a, f32x4 b) { u32x4 w; w.x = pk2(a[0], a[1]); w.y = pk2(a[2], a[3]); w.z = pk2(b[0], b[1]); w.w = pk2(b[2], b[3]); return w; }
;     __device__ __forceinline__ void operator()(const Acc& acc, const pg8::Unit& u, int wid) const {
;     ...
;                 for (int mm = 0; mm < 2; ++mm) {
;                     const int m = 2 * mp + mm, row = row0 + ai * 128 + m * 16; float sq = 0.f;
;                     const float sc = __builtin_amdgcn_rsqf(scv[mm] * (1.f / 1024.f) + EPS);
; #pragma unroll
;                     for (int bj = 0; bj < 2; ++bj) {
;                         const size_t off = (size_t)row * 1024 + col0 + bj * 128;
;                         const u32x4 pwv = pw[mm][bj], hw = hv[mm][bj];
;                         const f32x4 p0 = (f32x4){bflo(pwv.x), bfhi(pwv.x), bflo(pwv.y), bfhi(pwv.y)}, p1 = (f32x4){bflo(pwv.z), bfhi(pwv.z), bflo(pwv.w), bfhi(pwv.w)};
;                         f32x4 g0 = acc[ai][bj][m][0] * sc, g1 = acc[ai][bj][m][1] * sc;
; #pragma unroll
;                         for (int e = 0; e < 4; ++e) { g0[e] = __builtin_amdgcn_rcpf(1.f + __builtin_amdgcn_exp2f(-1.4426950408889634f * g0[e])); g1[e] = __builtin_amdgcn_rcpf(1.f + __builtin_amdgcn_exp2f(-1.4426950408889634f * g1[e])); }
;                         const f32x4 o0 = (f32x4){bflo(hw.x), bfhi(hw.x), bflo(hw.y), bfhi(hw.y)} + g0 * p0;
;                         const f32x4 o1 = (f32x4){bflo(hw.z), bfhi(hw.z), bflo(hw.w), bfhi(hw.w)} + g1 * p1;
;                         if (fout) { *(f32x4*)(fout + off) = o0; *(f32x4*)(fout + off + 4) = o1; }
;                         if (hb_out) *(u32x4*)(hb_out + off) = pack8(o0, o1);
;                         sq += (o0[0] * o0[0] + o0[1] * o0[1]) + (o0[2] * o0[2] + o0[3] * o0[3]) + (o1[0] * o1[0] + o1[1] * o1[1]) + (o1[2] * o1[2] + o1[3] * o1[3]);
;                     }
;                     if (ssq_out) { sq += __shfl_xor(sq, 16); sq += __shfl_xor(sq, 32); if (fq == 0) atomicAdd(ssq_out + row, sq); }
	v_lshl_add_u64 v[18:19], v[130:131], 2, s[58:59]
	s_waitcnt lgkmcnt(0)
	v_add_f32_e32 v16, v16, v17
	flat_atomic_add_f32 v[18:19], v16
.LBB0_710:
	s_or_b64 exec, exec, s[28:29]
	v_fmamk_f32 v16, v85, 0x3a800000, v186
	v_rsq_f32_e32 v16, v16
	v_lshlrev_b32_e32 v18, 16, v104
	v_and_b32_e32 v19, 0xffff0000, v104
	v_lshlrev_b32_e32 v20, 16, v105
	s_waitcnt lgkmcnt(0)
	v_pk_mul_f32 v[8:9], v[8:9], v[16:17] op_sel_hi:[1,0]
	v_pk_mul_f32 v[12:13], v[12:13], v[16:17] op_sel_hi:[1,0]
	v_mul_f32_e32 v8, 0xbfb8aa3b, v8
	v_exp_f32_e32 v8, v8
	v_mul_f32_e32 v13, 0xbfb8aa3b, v13
	v_exp_f32_e32 v13, v13
	v_mul_f32_e32 v9, 0xbfb8aa3b, v9
	v_exp_f32_e32 v9, v9
	v_add_f32_e32 v8, 1.0, v8
	v_pk_mul_f32 v[14:15], v[14:15], v[16:17] op_sel_hi:[1,0]
	v_pk_mul_f32 v[10:11], v[10:11], v[16:17] op_sel_hi:[1,0]
	v_rcp_f32_e32 v26, v8
	v_add_f32_e32 v8, 1.0, v13
	v_rcp_f32_e32 v13, v8
	v_add_f32_e32 v8, 1.0, v9
	v_mul_f32_e32 v9, 0xbfb8aa3b, v14
	v_mul_f32_e32 v10, 0xbfb8aa3b, v10
	v_exp_f32_e32 v9, v9
	v_exp_f32_e32 v10, v10
	v_mul_f32_e32 v12, 0xbfb8aa3b, v12
	v_exp_f32_e32 v12, v12
	v_rcp_f32_e32 v27, v8
	v_add_f32_e32 v8, 1.0, v9
	v_add_f32_e32 v9, 1.0, v10
	v_mul_f32_e32 v10, 0xbfb8aa3b, v15
	v_mul_f32_e32 v11, 0xbfb8aa3b, v11
	v_exp_f32_e32 v10, v10
	v_exp_f32_e32 v11, v11
	v_add_f32_e32 v12, 1.0, v12
	v_rcp_f32_e32 v12, v12
	v_rcp_f32_e32 v14, v9
	v_add_f32_e32 v9, 1.0, v10
	v_add_f32_e32 v10, 1.0, v11
	v_rcp_f32_e32 v8, v8
	v_rcp_f32_e32 v9, v9
	v_rcp_f32_e32 v15, v10
	v_lshlrev_b32_e32 v10, 16, v100
	v_and_b32_e32 v11, 0xffff0000, v100
	v_and_b32_e32 v21, 0xffff0000, v105
	v_lshlrev_b32_e32 v22, 16, v106
	v_and_b32_e32 v23, 0xffff0000, v106
	v_lshlrev_b32_e32 v24, 16, v107
	v_and_b32_e32 v25, 0xffff0000, v107
	v_lshlrev_b32_e32 v28, 16, v101
	v_and_b32_e32 v29, 0xffff0000, v101
	v_pk_fma_f32 v[10:11], v[12:13], v[18:19], v[10:11]
	v_lshlrev_b32_e32 v18, 16, v102
	v_and_b32_e32 v19, 0xffff0000, v102
	v_lshlrev_b32_e32 v12, 16, v103
	v_and_b32_e32 v13, 0xffff0000, v103
	v_pk_fma_f32 v[8:9], v[8:9], v[20:21], v[28:29]
	v_pk_fma_f32 v[12:13], v[14:15], v[24:25], v[12:13]
	v_pk_fma_f32 v[14:15], v[26:27], v[22:23], v[18:19]
	s_and_b64 vcc, exec, s[8:9]
	v_lshl_add_u64 v[18:19], v[96:97], 1, s[52:53]
	s_cbranch_vccnz .LBB0_712

; __device__ __forceinline__ u32x4 pack8(f32x4 a, f32x4 b) { u32x4 w; w.x = pk2(a[0], a[1]); w.y = pk2(a[2], a[3]); w.z = pk2(b[0], b[1]); w.w = pk2(b[2], b[3]); return w; }
;     __device__ __forceinline__ void operator()(const Acc& acc, const pg8::Unit& u, int wid) const {
;     ...
;                     for (int bj = 0; bj < 2; ++bj) {
;                         const size_t off = (size_t)row * 1024 + col0 + bj * 128;
;                         const u32x4 pwv = pw[mm][bj], hw = hv[mm][bj];
;                         const f32x4 p0 = (f32x4){bflo(pwv.x), bfhi(pwv.x), bflo(pwv.y), bfhi(pwv.y)}, p1 = (f32x4){bflo(pwv.z), bfhi(pwv.z), bflo(pwv.w), bfhi(pwv.w)};
;                         f32x4 g0 = acc[ai][bj][m][0] * sc, g1 = acc[ai][bj][m][1] * sc;
; #pragma unroll
;                         for (int e = 0; e < 4; ++e) { g0[e] = __builtin_amdgcn_rcpf(1.f + __builtin_amdgcn_exp2f(-1.4426950408889634f * g0[e])); g1[e] = __builtin_amdgcn_rcpf(1.f + __builtin_amdgcn_exp2f(-1.4426950408889634f * g1[e])); }
;                         const f32x4 o0 = (f32x4){bflo(hw.x), bfhi(hw.x), bflo(hw.y), bfhi(hw.y)} + g0 * p0;
;                         const f32x4 o1 = (f32x4){bflo(hw.z), bfhi(hw.z), bflo(hw.w), bfhi(hw.w)} + g1 * p1;
;                         if (fout) { *(f32x4*)(fout + off) = o0; *(f32x4*)(fout + off + 4) = o1; }
;                         if (hb_out) *(u32x4*)(hb_out + off) = pack8(o0, o1);
	v_cvt_pk_bf16_f32 v20, v10, v11
	v_cvt_pk_bf16_f32 v21, v8, v9
	v_cvt_pk_bf16_f32 v22, v14, v15
	v_cvt_pk_bf16_f32 v23, v12, v13
	global_store_dwordx4 v[18:19], v[20:23], off
.LBB0_712:
	v_mov_b32_e32 v17, v16
	v_pk_mul_f32 v[4:5], v[4:5], v[16:17]
	v_pk_mul_f32 v[0:1], v[0:1], v[16:17]
	v_mul_f32_e32 v4, 0xbfb8aa3b, v4
	v_mul_f32_e32 v0, 0xbfb8aa3b, v0
	v_mov_b32_e32 v28, v16
	v_mov_b32_e32 v29, v16
	v_exp_f32_e32 v4, v4
	v_exp_f32_e32 v16, v0
	v_mul_f32_e32 v5, 0xbfb8aa3b, v5
	v_mul_f32_e32 v1, 0xbfb8aa3b, v1
	v_add_f32_e32 v0, 1.0, v4
	v_add_f32_e32 v4, 1.0, v16
	v_exp_f32_e32 v5, v5
	v_exp_f32_e32 v16, v1
	v_pk_mul_f32 v[6:7], v[6:7], v[28:29]
	v_pk_mul_f32 v[2:3], v[2:3], v[28:29]
	v_mul_f32_e32 v6, 0xbfb8aa3b, v6
	v_mul_f32_e32 v2, 0xbfb8aa3b, v2
	v_add_f32_e32 v1, 1.0, v5
	v_add_f32_e32 v5, 1.0, v16
	v_exp_f32_e32 v6, v6
	v_exp_f32_e32 v16, v2
	v_mul_f32_e32 v7, 0xbfb8aa3b, v7
	v_mul_f32_e32 v3, 0xbfb8aa3b, v3
	v_add_f32_e32 v2, 1.0, v6
	v_add_f32_e32 v6, 1.0, v16
	v_exp_f32_e32 v7, v7
	v_exp_f32_e32 v16, v3
	v_rcp_f32_e32 v0, v0
	v_rcp_f32_e32 v1, v1
	v_add_f32_e32 v3, 1.0, v7
	v_add_f32_e32 v7, 1.0, v16
	v_rcp_f32_e32 v4, v4
	v_rcp_f32_e32 v5, v5
	v_rcp_f32_e32 v2, v2
	v_rcp_f32_e32 v6, v6
	v_rcp_f32_e32 v3, v3
	v_rcp_f32_e32 v7, v7
	v_lshlrev_b32_e32 v20, 16, v92
	v_and_b32_e32 v21, 0xffff0000, v92
	v_lshlrev_b32_e32 v16, 16, v88
	v_and_b32_e32 v17, 0xffff0000, v88
	v_lshlrev_b32_e32 v22, 16, v93
	v_and_b32_e32 v23, 0xffff0000, v93
	v_lshlrev_b32_e32 v24, 16, v94
	v_and_b32_e32 v25, 0xffff0000, v94
	v_lshlrev_b32_e32 v26, 16, v95
	v_and_b32_e32 v27, 0xffff0000, v95
	v_lshlrev_b32_e32 v28, 16, v89
	v_and_b32_e32 v29, 0xffff0000, v89
	v_pk_fma_f32 v[0:1], v[0:1], v[20:21], v[16:17]
	v_lshlrev_b32_e32 v16, 16, v90
	v_and_b32_e32 v17, 0xffff0000, v90
	v_lshlrev_b32_e32 v20, 16, v91
	v_and_b32_e32 v21, 0xffff0000, v91
	v_pk_fma_f32 v[2:3], v[2:3], v[22:23], v[28:29]
	v_pk_fma_f32 v[4:5], v[4:5], v[24:25], v[16:17]
	s_and_b64 vcc, exec, s[8:9]
	v_pk_fma_f32 v[6:7], v[6:7], v[26:27], v[20:21]
	s_cbranch_vccnz .LBB0_714

; __device__ __forceinline__ u32x4 pack8(f32x4 a, f32x4 b) { u32x4 w; w.x = pk2(a[0], a[1]); w.y = pk2(a[2], a[3]); w.z = pk2(b[0], b[1]); w.w = pk2(b[2], b[3]); return w; }
;     __device__ __forceinline__ void operator()(const Acc& acc, const pg8::Unit& u, int wid) const {
;     ...
;                     for (int bj = 0; bj < 2; ++bj) {
;                         const size_t off = (size_t)row * 1024 + col0 + bj * 128;
;                         const u32x4 pwv = pw[mm][bj], hw = hv[mm][bj];
;                         const f32x4 p0 = (f32x4){bflo(pwv.x), bfhi(pwv.x), bflo(pwv.y), bfhi(pwv.y)}, p1 = (f32x4){bflo(pwv.z), bfhi(pwv.z), bflo(pwv.w), bfhi(pwv.w)};
;                         f32x4 g0 = acc[ai][bj][m][0] * sc, g1 = acc[ai][bj][m][1] * sc;
; #pragma unroll
;                         for (int e = 0; e < 4; ++e) { g0[e] = __builtin_amdgcn_rcpf(1.f + __builtin_amdgcn_exp2f(-1.4426950408889634f * g0[e])); g1[e] = __builtin_amdgcn_rcpf(1.f + __builtin_amdgcn_exp2f(-1.4426950408889634f * g1[e])); }
;                         const f32x4 o0 = (f32x4){bflo(hw.x), bfhi(hw.x), bflo(hw.y), bfhi(hw.y)} + g0 * p0;
;                         const f32x4 o1 = (f32x4){bflo(hw.z), bfhi(hw.z), bflo(hw.w), bfhi(hw.w)} + g1 * p1;
;                         if (fout) { *(f32x4*)(fout + off) = o0; *(f32x4*)(fout + off + 4) = o1; }
;                         if (hb_out) *(u32x4*)(hb_out + off) = pack8(o0, o1);
;                         sq += (o0[0] * o0[0] + o0[1] * o0[1]) + (o0[2] * o0[2] + o0[3] * o0[3]) + (o1[0] * o1[0] + o1[1] * o1[1]) + (o1[2] * o1[2] + o1[3] * o1[3]);
;                     }
;                     if (ssq_out) { sq += __shfl_xor(sq, 16); sq += __shfl_xor(sq, 32); if (fq == 0) atomicAdd(ssq_out + row, sq); }
	v_cvt_pk_bf16_f32 v20, v0, v1
	v_cvt_pk_bf16_f32 v21, v2, v3
	v_cvt_pk_bf16_f32 v22, v4, v5
	v_cvt_pk_bf16_f32 v23, v6, v7
	global_store_dwordx4 v[18:19], v[20:23], off offset:256
.LBB0_714:
	v_mul_f32_e32 v11, v11, v11
	v_mul_f32_e32 v9, v9, v9
	v_mul_f32_e32 v1, v1, v1
	v_fmac_f32_e32 v11, v10, v10
	v_fmac_f32_e32 v9, v8, v8
	v_fmac_f32_e32 v1, v0, v0
	v_mul_f32_e32 v0, v3, v3
	v_add_f32_e32 v8, v11, v9
	v_mul_f32_e32 v9, v15, v15
	v_fmac_f32_e32 v0, v2, v2
	v_fmac_f32_e32 v9, v14, v14
	v_add_f32_e32 v0, v1, v0
	v_mul_f32_e32 v1, v5, v5
	v_add_f32_e32 v8, v9, v8
	v_mul_f32_e32 v9, v13, v13
	v_mul_f32_e32 v7, v7, v7
	v_fmac_f32_e32 v1, v4, v4
	v_fmac_f32_e32 v9, v12, v12
	v_fmac_f32_e32 v7, v6, v6
	v_add_f32_e32 v0, v1, v0
	v_add_f32_e32 v8, v9, v8
	v_add_f32_e32 v0, v7, v0
	v_add_f32_e32 v0, v8, v0
	ds_bpermute_b32 v1, v144, v0
	s_waitcnt lgkmcnt(0)
	v_add_f32_e32 v0, v0, v1
	ds_bpermute_b32 v1, v145, v0
	s_and_saveexec_b64 s[8:9], s[10:11]
	s_cbranch_execz .LBB0_716

; #define PG8_BAR __builtin_amdgcn_s_barrier()
; template <class Epi>
; __device__ __forceinline__ void gemm_phase(LAS unsigned char* lds, const Gemm g, const StaticOrder& S, const Epi& E, const int wid) {
;     ...
;         if (wr == 0) PG8_BAR;
;         E(acc, cur, wid);
;         if (!has_next) break;
; #pragma unroll
;         for (int a = 0; a < 2; ++a)
; #pragma unroll
;             for (int b = 0; b < 2; ++b)
; #pragma unroll
;                 for (int m = 0; m < 4; ++m)
; #pragma unroll
;                     for (int n = 0; n < 2; ++n) acc[a][b][m][n] = (f32x4){0.f, 0.f, 0.f, 0.f};
;         cur = nxt; cA = nA; cB = nB; ++ui;
;         if (wr == 1) PG8_BAR;
;     }
;     __device__ __forceinline__ void operator()(const Acc& acc, const pg8::Unit& u, int wid) const {
;     ...
;                         sq += (o0[0] * o0[0] + o0[1] * o0[1]) + (o0[2] * o0[2] + o0[3] * o0[3]) + (o1[0] * o1[0] + o1[1] * o1[1]) + (o1[2] * o1[2] + o1[3] * o1[3]);
;                     }
;                     if (ssq_out) { sq += __shfl_xor(sq, 16); sq += __shfl_xor(sq, 32); if (fq == 0) atomicAdd(ssq_out + row, sq); }
;                 }
;             }
;     }
	v_lshl_add_u64 v[2:3], v[86:87], 2, s[58:59]
	s_waitcnt lgkmcnt(0)
	v_add_f32_e32 v0, v0, v1
	flat_atomic_add_f32 v[2:3], v0
.LBB0_716:
	s_or_b64 exec, exec, s[8:9]
	s_andn2_b64 vcc, exec, s[6:7]
	s_mov_b64 s[6:7], -1
	s_cbranch_vccnz .LBB0_657

; #define PG8_BAR __builtin_amdgcn_s_barrier()
; template <class Epi>
; __device__ __forceinline__ void gemm_phase(LAS unsigned char* lds, const Gemm g, const StaticOrder& S, const Epi& E, const int wid) {
;     ...
;         if (wr == 0) PG8_BAR;
;         E(acc, cur, wid);
;         if (!has_next) break;
; #pragma unroll
;         for (int a = 0; a < 2; ++a)
; #pragma unroll
;             for (int b = 0; b < 2; ++b)
; #pragma unroll
;                 for (int m = 0; m < 4; ++m)
; #pragma unroll
;                     for (int n = 0; n < 2; ++n) acc[a][b][m][n] = (f32x4){0.f, 0.f, 0.f, 0.f};
;         cur = nxt; cA = nA; cB = nB; ++ui;
;         if (wr == 1) PG8_BAR;
;     }
	s_andn2_b64 vcc, exec, s[0:1]
	s_cbranch_vccnz .LBB0_656

; #define PG8_BAR __builtin_amdgcn_s_barrier()
; template <class Epi>
; __device__ __forceinline__ void gemm_phase(LAS unsigned char* lds, const Gemm g, const StaticOrder& S, const Epi& E, const int wid) {
;     ...
;         if (wr == 1) PG8_BAR;
;     }
	s_barrier
	s_branch .LBB0_656
.LBB0_719:

; #define PG8_WAIT_V(n) asm volatile("s_waitcnt vmcnt(" #n ")" ::: "memory")
; #define PG8_BAR __builtin_amdgcn_s_barrier()
; template <class Epi>
; __device__ __forceinline__ void gemm_phase(LAS unsigned char* lds, const Gemm g, const StaticOrder& S, const Epi& E, const int wid) {
;     ...
;     PG8_WAIT_V(0);
;     PG8_BAR;
	s_waitcnt vmcnt(0)

; #define PG8_WAIT_V(n) asm volatile("s_waitcnt vmcnt(" #n ")" ::: "memory")
; #define PG8_BAR __builtin_amdgcn_s_barrier()
; template <class Epi>
; __device__ __forceinline__ void gemm_phase(LAS unsigned char* lds, const Gemm g, const StaticOrder& S, const Epi& E, const int wid) {
;     ...
;     PG8_WAIT_V(0);
;     PG8_BAR;
	s_barrier
.LBB0_720:

; #define PG8_WAIT_V(n) asm volatile("s_waitcnt vmcnt(" #n ")" ::: "memory")
; #define PG8_BAR __builtin_amdgcn_s_barrier()
; template <class Epi>
; __device__ __forceinline__ void gemm_phase(LAS unsigned char* lds, const Gemm g, const StaticOrder& S, const Epi& E, const int wid) {
;     ...
;     PG8_WAIT_V(0);
;     PG8_BAR;
	s_waitcnt vmcnt(0)

; __device__ __forceinline__ unsigned xb_add(unsigned* p, unsigned v) { return __hip_atomic_fetch_add(p, v, __ATOMIC_RELAXED, __HIP_MEMORY_SCOPE_AGENT); }
; __device__ __forceinline__ void xcd_barrier(const XcdBarrier& b) {
;     asm volatile("s_waitcnt vmcnt(0)" ::: "memory");
;     __syncthreads();
;     if (threadIdx.x == 0) {
;         unsigned* bar = b.bar;
;         __builtin_amdgcn_s_waitcnt(0);
;         unsigned nloc = b.st[0], nx = b.st[1];
;         if (nloc == 0u) { xcd_barrier_complete(bar, b.x, nloc, nx); b.st[0] = nloc; b.st[1] = nx; }
;         const unsigned old = xb_add(&bar[XB_XSUB(b.x)], 1u);
	s_waitcnt vmcnt(0) lgkmcnt(0)
	s_barrier
	s_and_saveexec_b64 s[60:61], s[12:13]
	s_cbranch_execz .LBB0_764

; __device__ __forceinline__ void xcd_barrier(const XcdBarrier& b) {
;     ...
;         unsigned nloc = b.st[0], nx = b.st[1];
;         if (nloc == 0u) { xcd_barrier_complete(bar, b.x, nloc, nx); b.st[0] = nloc; b.st[1] = nx; }
	s_add_i32 s0, 0, 0x27fc0
	v_mov_b32_e32 v0, s0
	s_waitcnt vmcnt(0) expcnt(0) lgkmcnt(0)
	ds_read_b32 v2, v0
	s_add_i32 s0, 0, 0x27fc4
	v_mov_b32_e32 v0, s0
	ds_read_b32 v0, v0
	s_waitcnt lgkmcnt(1)
	v_cmp_ne_u32_e32 vcc, 0, v2
	s_cbranch_vccnz .LBB0_735

; __device__ __forceinline__ unsigned xb_ld(unsigned* p)              { return __hip_atomic_load(p, __ATOMIC_RELAXED, __HIP_MEMORY_SCOPE_AGENT); }
; __device__ __forceinline__ void xcd_barrier_complete(unsigned* bar, unsigned x, unsigned& nloc, unsigned& nx) {
;     const unsigned G = gridDim.x * gridDim.y * gridDim.z;
;     unsigned sum, cnt, mine, sp = 0u;
;     for (;;) {
;         sum = 0u; cnt = 0u; mine = 0u;
; #pragma unroll
;         for (unsigned j = 0; j < 16; ++j) { const unsigned c = xb_ld(&bar[XB_XCNT(j)]); sum += c; cnt += (c > 0u) ? 1u : 0u; mine = (j == x) ? c : mine; }
;         if (sum == G) break;
;         __builtin_amdgcn_s_sleep(1);
;         if ((++sp & 255u) == 0u) { if (xb_ld(&bar[XB_TMO])) break; if (sp > XB_SPIN_CAP) { atomicAdd(&bar[XB_TMO], 1u); break; } }
;     }
;     nloc = mine > 0u ? mine : 1u; nx = cnt > 0u ? cnt : 1u;
	v_readlane_b32 s0, v254, 0
	s_mul_i32 s4, s57, s0
	s_add_u32 s0, s54, 0xc00200
	s_addc_u32 s1, s55, 0
	s_add_u32 s8, s54, 0xc00400
	s_addc_u32 s9, s55, 0
	s_add_u32 s10, s54, 0xc00500
	s_addc_u32 s11, s55, 0
	s_add_u32 s16, s54, 0xc00600
	s_addc_u32 s17, s55, 0
	s_add_u32 s18, s54, 0xc00700
	s_addc_u32 s19, s55, 0
	s_add_u32 s20, s54, 0xc00800
	s_addc_u32 s21, s55, 0
	s_add_u32 s22, s54, 0xc00900
	s_addc_u32 s23, s55, 0
	s_add_u32 s24, s54, 0xc00a00
	s_addc_u32 s25, s55, 0
	s_add_u32 s26, s54, 0xc00b00
	s_addc_u32 s27, s55, 0
	s_add_u32 s28, s54, 0xc00c00
	s_addc_u32 s29, s55, 0
	s_add_u32 s30, s54, 0xc00d00
	s_addc_u32 s31, s55, 0
	s_add_u32 s34, s54, 0xc00e00
	s_addc_u32 s35, s55, 0
	s_add_u32 s36, s54, 0xc00f00
	s_addc_u32 s37, s55, 0
	s_add_u32 s38, s54, 0xc01000
	s_addc_u32 s39, s55, 0
	s_add_u32 s50, s54, 0xc01100
	s_addc_u32 s51, s55, 0
	s_add_u32 s62, s54, 0xc01200
	s_addc_u32 s63, s55, 0
	s_add_u32 s64, s54, 0xc01300
	s_addc_u32 s65, s55, 0
	s_mul_i32 s4, s4, s56
	s_mov_b32 s5, 1
	s_mov_b64 s[6:7], 0
	s_waitcnt lgkmcnt(0)
	v_mov_b64_e32 v[0:1], s[8:9]
	v_mov_b64_e32 v[2:3], s[10:11]
	v_mov_b64_e32 v[4:5], s[16:17]
	v_mov_b64_e32 v[6:7], s[18:19]
	v_mov_b64_e32 v[8:9], s[20:21]
	v_mov_b64_e32 v[10:11], s[22:23]
	v_mov_b64_e32 v[12:13], s[24:25]
	v_mov_b64_e32 v[14:15], s[26:27]
	v_mov_b64_e32 v[16:17], s[28:29]
	v_mov_b64_e32 v[18:19], s[30:31]
	v_mov_b64_e32 v[20:21], s[34:35]
	v_mov_b64_e32 v[22:23], s[36:37]
	v_mov_b64_e32 v[24:25], s[38:39]
	v_mov_b64_e32 v[26:27], s[50:51]
	v_mov_b64_e32 v[28:29], s[62:63]
	v_mov_b64_e32 v[30:31], s[64:65]


; __device__ __forceinline__ unsigned xb_ld(unsigned* p)              { return __hip_atomic_load(p, __ATOMIC_RELAXED, __HIP_MEMORY_SCOPE_AGENT); }
; __device__ __forceinline__ void xcd_barrier_complete(unsigned* bar, unsigned x, unsigned& nloc, unsigned& nx) {
;     const unsigned G = gridDim.x * gridDim.y * gridDim.z;
;     unsigned sum, cnt, mine, sp = 0u;
;     for (;;) {
;         sum = 0u; cnt = 0u; mine = 0u;
; #pragma unroll
;         for (unsigned j = 0; j < 16; ++j) { const unsigned c = xb_ld(&bar[XB_XCNT(j)]); sum += c; cnt += (c > 0u) ? 1u : 0u; mine = (j == x) ? c : mine; }
;         if (sum == G) break;
;         __builtin_amdgcn_s_sleep(1);
;         if ((++sp & 255u) == 0u) { if (xb_ld(&bar[XB_TMO])) break; if (sp > XB_SPIN_CAP) { atomicAdd(&bar[XB_TMO], 1u); break; } }
;     }
;     nloc = mine > 0u ? mine : 1u; nx = cnt > 0u ? cnt : 1u;
	s_branch .LBB0_725
